# speedup vs baseline: 1.0106x; 1.0106x over previous
; #define MFMA32(a, b, c) __builtin_amdgcn_mfma_f32_32x32x16_bf16((a), (b), (c), 0, 0, 0)
; DI unsigned fkey(float f) { const unsigned u = __float_as_uint(f); return (u & 0x80000000u) ? ~u : (u | 0x80000000u); }
; #define TK_PREFETCH(t_, p_) do { const int tk0_ = ((t_) >> 3) * 64, hp_ = ((t_) & 7) * 2 + (p_); \
;         _Pragma("unroll") for (int i_ = 0; i_ < 4; ++i_) { const int c_ = tid + 256 * i_; pre[i_] = *(const u32x4*)(qp + (size_t)(tk0_ + (c_ >> 4)) * 2048 + hp_ * 128 + (c_ & 15) * 8); } } while (0)
; DI void topk_phase(unsigned char* smem_, const bf16_t* __restrict__ qp, const bf16_t* __restrict__ keys, int* __restrict__ eidx, float* __restrict__ gate) {
;     ...
;     for (int p = 0; p < 2; ++p) {
; #pragma unroll
;         for (int i = 0; i < 4; ++i) { const int c = tid + 256 * i; *(u32x4*)(As + (c >> 4) * LDA + (c & 15) * 8) = pre[i]; }
;         __syncthreads();
;         f32x16 acc[2];
; #pragma unroll
;         for (int i = 0; i < 16; ++i) { acc[0][i] = 0.f; acc[1][i] = 0.f; }
; #pragma unroll
;         for (int ks = 0; ks < 8; ++ks) {
; #pragma unroll
;             for (int th = 0; th < 2; ++th) { const bf16x8 qf = *(const bf16x8*)(As + (32 * th + l31) * LDA + ks * 16 + hi * 8); acc[th] = MFMA32(kf[p][ks], qf, acc[th]); }
;         }
; #pragma unroll
;         for (int th = 0; th < 2; ++th)
; #pragma unroll
;             for (int g = 0; g < 4; ++g) { f32x4 o; o.x = acc[th][4 * g]; o.y = acc[th][4 * g + 1]; o.z = acc[th][4 * g + 2]; o.w = acc[th][4 * g + 3]; *(f32x4*)(S + (32 * th + l31) * LDS_ + 32 * wid + 8 * g + 4 * hi) = o; }
;         __syncthreads();
;         if (p == 0) TK_PREFETCH(t, 1); else if (t + G < NT) TK_PREFETCH(t + G, 0);
;         unsigned v[32];
; #pragma unroll
;         for (int i = 0; i < 8; ++i) {
;             const f32x4 sv4 = *(const f32x4*)(S + row * LDS_ + 32 * q + 4 * i);
;             const int ib = 127 - (32 * q + 4 * i);
;             v[4 * i] = (fkey(sv4.x) & ~127u) | (unsigned)ib; v[4 * i + 1] = (fkey(sv4.y) & ~127u) | (unsigned)(ib - 1);
;             v[4 * i + 2] = (fkey(sv4.z) & ~127u) | (unsigned)(ib - 2); v[4 * i + 3] = (fkey(sv4.w) & ~127u) | (unsigned)(ib - 3);
.LBB0_57:
	s_waitcnt vmcnt(0)
	ds_write_b128 v234, v[96:99]
	ds_write_b128 v234, v[100:103] offset:4352
	ds_write_b128 v234, v[104:107] offset:8704
	ds_write_b128 v234, v[108:111] offset:13056
	s_waitcnt lgkmcnt(0)
	s_barrier
	ds_read_b128 v[0:3], v235
	ds_read_b128 v[96:99], v235 offset:32
	s_waitcnt lgkmcnt(1)
	v_mfma_f32_32x32x16_bf16 v[16:31], v[32:35], v[0:3], 0
	ds_read_b128 v[0:3], v235 offset:8704
	s_and_b32 s24, s22, 0xffffffc0
	s_lshl_b32 s0, s0, 1
	s_add_u32 s0, s86, s0
	s_addc_u32 s1, s87, 0
	s_waitcnt lgkmcnt(1)
	v_mfma_f32_32x32x16_bf16 v[16:31], v[36:39], v[96:99], v[16:31]
	ds_read_b128 v[96:99], v235 offset:8736
	s_waitcnt lgkmcnt(1)
	v_mfma_f32_32x32x16_bf16 v[0:15], v[32:35], v[0:3], 0
	s_waitcnt lgkmcnt(0)
	v_mfma_f32_32x32x16_bf16 v[0:15], v[36:39], v[96:99], v[0:15]
	ds_read_b128 v[96:99], v235 offset:64
	s_waitcnt lgkmcnt(0)
	v_mfma_f32_32x32x16_bf16 v[16:31], v[40:43], v[96:99], v[16:31]
	ds_read_b128 v[96:99], v235 offset:8768
	s_waitcnt lgkmcnt(0)
	v_mfma_f32_32x32x16_bf16 v[0:15], v[40:43], v[96:99], v[0:15]
	ds_read_b128 v[96:99], v235 offset:96
	s_waitcnt lgkmcnt(0)
	v_mfma_f32_32x32x16_bf16 v[16:31], v[44:47], v[96:99], v[16:31]
	ds_read_b128 v[96:99], v235 offset:8800
	s_waitcnt lgkmcnt(0)
	v_mfma_f32_32x32x16_bf16 v[0:15], v[44:47], v[96:99], v[0:15]
	ds_read_b128 v[96:99], v235 offset:128
	s_waitcnt lgkmcnt(0)
	v_mfma_f32_32x32x16_bf16 v[16:31], v[48:51], v[96:99], v[16:31]
	ds_read_b128 v[96:99], v235 offset:8832
	s_waitcnt lgkmcnt(0)
	v_mfma_f32_32x32x16_bf16 v[0:15], v[48:51], v[96:99], v[0:15]
	ds_read_b128 v[96:99], v235 offset:160
	s_waitcnt lgkmcnt(0)
	v_mfma_f32_32x32x16_bf16 v[16:31], v[52:55], v[96:99], v[16:31]
	ds_read_b128 v[96:99], v235 offset:8864
	s_waitcnt lgkmcnt(0)
	v_mfma_f32_32x32x16_bf16 v[0:15], v[52:55], v[96:99], v[0:15]
	ds_read_b128 v[96:99], v235 offset:192
	s_waitcnt lgkmcnt(0)
	v_mfma_f32_32x32x16_bf16 v[16:31], v[56:59], v[96:99], v[16:31]
	ds_read_b128 v[96:99], v235 offset:8896
	s_waitcnt lgkmcnt(0)
	v_mfma_f32_32x32x16_bf16 v[0:15], v[56:59], v[96:99], v[0:15]
	ds_read_b128 v[96:99], v235 offset:224
	s_waitcnt lgkmcnt(0)
	v_mfma_f32_32x32x16_bf16 v[16:31], v[60:63], v[96:99], v[16:31]
	ds_read_b128 v[96:99], v235 offset:8928
	s_nop 10
	ds_write_b128 v236, v[16:19] offset:17408
	ds_write_b128 v236, v[20:23] offset:17440
	ds_write_b128 v236, v[24:27] offset:17472
	ds_write_b128 v236, v[28:31] offset:17504
	s_waitcnt lgkmcnt(4)
	v_mfma_f32_32x32x16_bf16 v[0:15], v[60:63], v[96:99], v[0:15]
	s_nop 11
	ds_write_b128 v236, v[0:3] offset:34304
	ds_write_b128 v236, v[4:7] offset:34336
	ds_write_b128 v236, v[8:11] offset:34368
	ds_write_b128 v236, v[12:15] offset:34400
	v_or_b32_e32 v0, s24, v165
	v_ashrrev_i32_e32 v1, 31, v0
	v_lshlrev_b64 v[0:1], 12, v[0:1]
	v_lshl_add_u64 v[0:1], s[0:1], 0, v[0:1]
	v_lshl_add_u64 v[0:1], v[0:1], 0, v[128:129]
	s_waitcnt lgkmcnt(0)
	s_barrier
	global_load_dwordx4 v[96:99], v[0:1], off offset:256
	v_or_b32_e32 v0, s24, v166
	v_ashrrev_i32_e32 v1, 31, v0
	v_lshlrev_b64 v[0:1], 12, v[0:1]
	v_lshl_add_u64 v[0:1], s[0:1], 0, v[0:1]
	v_lshl_add_u64 v[0:1], v[0:1], 0, v[128:129]
	global_load_dwordx4 v[100:103], v[0:1], off offset:256
	v_or_b32_e32 v0, s24, v167
	v_ashrrev_i32_e32 v1, 31, v0
	v_lshlrev_b64 v[0:1], 12, v[0:1]
	v_lshl_add_u64 v[0:1], s[0:1], 0, v[0:1]
	v_lshl_add_u64 v[0:1], v[0:1], 0, v[128:129]
	global_load_dwordx4 v[104:107], v[0:1], off offset:256
	v_or_b32_e32 v0, s24, v168
	v_ashrrev_i32_e32 v1, 31, v0
	v_lshlrev_b64 v[0:1], 12, v[0:1]
	v_lshl_add_u64 v[0:1], s[0:1], 0, v[0:1]
	v_lshl_add_u64 v[4:5], v[0:1], 0, v[128:129]
	ds_read_b128 v[0:3], v171 offset:17408
	global_load_dwordx4 v[108:111], v[4:5], off offset:256
	ds_read_b128 v[4:7], v171 offset:17424
	ds_read_b128 v[8:11], v171 offset:17440
	ds_read_b128 v[12:15], v171 offset:17456
	s_waitcnt lgkmcnt(3)
	v_ashrrev_i32_e32 v16, 31, v0
	v_or_b32_e32 v17, 0x80000000, v16

; DI unsigned fkey(float f) { const unsigned u = __float_as_uint(f); return (u & 0x80000000u) ? ~u : (u | 0x80000000u); }
; DI void topk_phase(unsigned char* smem_, const bf16_t* __restrict__ qp, const bf16_t* __restrict__ keys, int* __restrict__ eidx, float* __restrict__ gate) {
;     ...
;             const f32x4 sv4 = *(const f32x4*)(S + row * LDS_ + 32 * q + 4 * i);
;             const int ib = 127 - (32 * q + 4 * i);
;             v[4 * i] = (fkey(sv4.x) & ~127u) | (unsigned)ib; v[4 * i + 1] = (fkey(sv4.y) & ~127u) | (unsigned)(ib - 1);
;             v[4 * i + 2] = (fkey(sv4.z) & ~127u) | (unsigned)(ib - 2); v[4 * i + 3] = (fkey(sv4.w) & ~127u) | (unsigned)(ib - 3);
	s_waitcnt lgkmcnt(0)
	v_not_b32_e32 v20, v15
	v_or_b32_e32 v21, 0x80000000, v15
	v_xor_b32_e32 v0, v17, v0
	v_ashrrev_i32_e32 v16, 31, v1
	v_or_b32_e32 v17, 0x80000000, v16

; DI unsigned fkey(float f) { const unsigned u = __float_as_uint(f); return (u & 0x80000000u) ? ~u : (u | 0x80000000u); }
; DI void topk_phase(unsigned char* smem_, const bf16_t* __restrict__ qp, const bf16_t* __restrict__ keys, int* __restrict__ eidx, float* __restrict__ gate) {
;     ...
;             const f32x4 sv4 = *(const f32x4*)(S + row * LDS_ + 32 * q + 4 * i);
;             const int ib = 127 - (32 * q + 4 * i);
;             v[4 * i] = (fkey(sv4.x) & ~127u) | (unsigned)ib; v[4 * i + 1] = (fkey(sv4.y) & ~127u) | (unsigned)(ib - 1);
;             v[4 * i + 2] = (fkey(sv4.z) & ~127u) | (unsigned)(ib - 2); v[4 * i + 3] = (fkey(sv4.w) & ~127u) | (unsigned)(ib - 3);
	v_and_b32_e32 v0, 0xffffff80, v0
	v_sub_u32_e32 v0, v0, v170
	v_xor_b32_e32 v1, v17, v1
	v_ashrrev_i32_e32 v16, 31, v2
	v_or_b32_e32 v17, 0x80000000, v16

; DI unsigned fkey(float f) { const unsigned u = __float_as_uint(f); return (u & 0x80000000u) ? ~u : (u | 0x80000000u); }
; DI void topk_phase(unsigned char* smem_, const bf16_t* __restrict__ qp, const bf16_t* __restrict__ keys, int* __restrict__ eidx, float* __restrict__ gate) {
;     ...
;             const f32x4 sv4 = *(const f32x4*)(S + row * LDS_ + 32 * q + 4 * i);
;             const int ib = 127 - (32 * q + 4 * i);
;             v[4 * i] = (fkey(sv4.x) & ~127u) | (unsigned)ib; v[4 * i + 1] = (fkey(sv4.y) & ~127u) | (unsigned)(ib - 1);
;             v[4 * i + 2] = (fkey(sv4.z) & ~127u) | (unsigned)(ib - 2); v[4 * i + 3] = (fkey(sv4.w) & ~127u) | (unsigned)(ib - 3);
	v_and_b32_e32 v1, 0xffffff80, v1
	v_sub_u32_e32 v1, v1, v170
	v_xor_b32_e32 v2, v17, v2
	v_ashrrev_i32_e32 v16, 31, v3
	v_or_b32_e32 v17, 0x80000000, v16

; DI unsigned fkey(float f) { const unsigned u = __float_as_uint(f); return (u & 0x80000000u) ? ~u : (u | 0x80000000u); }
; DI void topk_phase(unsigned char* smem_, const bf16_t* __restrict__ qp, const bf16_t* __restrict__ keys, int* __restrict__ eidx, float* __restrict__ gate) {
;     ...
;             const f32x4 sv4 = *(const f32x4*)(S + row * LDS_ + 32 * q + 4 * i);
;             const int ib = 127 - (32 * q + 4 * i);
;             v[4 * i] = (fkey(sv4.x) & ~127u) | (unsigned)ib; v[4 * i + 1] = (fkey(sv4.y) & ~127u) | (unsigned)(ib - 1);
;             v[4 * i + 2] = (fkey(sv4.z) & ~127u) | (unsigned)(ib - 2); v[4 * i + 3] = (fkey(sv4.w) & ~127u) | (unsigned)(ib - 3);
	v_and_b32_e32 v2, 0xffffff80, v2
	v_sub_u32_e32 v2, v2, v170
	v_xor_b32_e32 v3, v17, v3
	v_ashrrev_i32_e32 v16, 31, v4
	v_or_b32_e32 v17, 0x80000000, v16

; DI unsigned fkey(float f) { const unsigned u = __float_as_uint(f); return (u & 0x80000000u) ? ~u : (u | 0x80000000u); }
; DI void topk_phase(unsigned char* smem_, const bf16_t* __restrict__ qp, const bf16_t* __restrict__ keys, int* __restrict__ eidx, float* __restrict__ gate) {
;     ...
;             const f32x4 sv4 = *(const f32x4*)(S + row * LDS_ + 32 * q + 4 * i);
;             const int ib = 127 - (32 * q + 4 * i);
;             v[4 * i] = (fkey(sv4.x) & ~127u) | (unsigned)ib; v[4 * i + 1] = (fkey(sv4.y) & ~127u) | (unsigned)(ib - 1);
;             v[4 * i + 2] = (fkey(sv4.z) & ~127u) | (unsigned)(ib - 2); v[4 * i + 3] = (fkey(sv4.w) & ~127u) | (unsigned)(ib - 3);
	v_and_b32_e32 v3, 0xffffff80, v3
	v_sub_u32_e32 v3, v3, v170
	v_xor_b32_e32 v4, v17, v4
	v_ashrrev_i32_e32 v16, 31, v5
	v_or_b32_e32 v17, 0x80000000, v16

; DI unsigned fkey(float f) { const unsigned u = __float_as_uint(f); return (u & 0x80000000u) ? ~u : (u | 0x80000000u); }
; DI void topk_phase(unsigned char* smem_, const bf16_t* __restrict__ qp, const bf16_t* __restrict__ keys, int* __restrict__ eidx, float* __restrict__ gate) {
;     ...
;             const f32x4 sv4 = *(const f32x4*)(S + row * LDS_ + 32 * q + 4 * i);
;             const int ib = 127 - (32 * q + 4 * i);
;             v[4 * i] = (fkey(sv4.x) & ~127u) | (unsigned)ib; v[4 * i + 1] = (fkey(sv4.y) & ~127u) | (unsigned)(ib - 1);
;             v[4 * i + 2] = (fkey(sv4.z) & ~127u) | (unsigned)(ib - 2); v[4 * i + 3] = (fkey(sv4.w) & ~127u) | (unsigned)(ib - 3);
	v_and_b32_e32 v4, 0xffffff80, v4
	v_sub_u32_e32 v4, v4, v177
	v_xor_b32_e32 v5, v17, v5
	v_ashrrev_i32_e32 v16, 31, v6
	v_or_b32_e32 v17, 0x80000000, v16

; DI unsigned fkey(float f) { const unsigned u = __float_as_uint(f); return (u & 0x80000000u) ? ~u : (u | 0x80000000u); }
; DI void topk_phase(unsigned char* smem_, const bf16_t* __restrict__ qp, const bf16_t* __restrict__ keys, int* __restrict__ eidx, float* __restrict__ gate) {
;     ...
;             const f32x4 sv4 = *(const f32x4*)(S + row * LDS_ + 32 * q + 4 * i);
;             const int ib = 127 - (32 * q + 4 * i);
;             v[4 * i] = (fkey(sv4.x) & ~127u) | (unsigned)ib; v[4 * i + 1] = (fkey(sv4.y) & ~127u) | (unsigned)(ib - 1);
;             v[4 * i + 2] = (fkey(sv4.z) & ~127u) | (unsigned)(ib - 2); v[4 * i + 3] = (fkey(sv4.w) & ~127u) | (unsigned)(ib - 3);
	v_and_b32_e32 v5, 0xffffff80, v5
	v_sub_u32_e32 v5, v5, v177
	v_xor_b32_e32 v6, v17, v6
	v_ashrrev_i32_e32 v16, 31, v7
	v_or_b32_e32 v17, 0x80000000, v16

; DI unsigned fkey(float f) { const unsigned u = __float_as_uint(f); return (u & 0x80000000u) ? ~u : (u | 0x80000000u); }
; DI void topk_phase(unsigned char* smem_, const bf16_t* __restrict__ qp, const bf16_t* __restrict__ keys, int* __restrict__ eidx, float* __restrict__ gate) {
;     ...
;             const f32x4 sv4 = *(const f32x4*)(S + row * LDS_ + 32 * q + 4 * i);
;             const int ib = 127 - (32 * q + 4 * i);
;             v[4 * i] = (fkey(sv4.x) & ~127u) | (unsigned)ib; v[4 * i + 1] = (fkey(sv4.y) & ~127u) | (unsigned)(ib - 1);
;             v[4 * i + 2] = (fkey(sv4.z) & ~127u) | (unsigned)(ib - 2); v[4 * i + 3] = (fkey(sv4.w) & ~127u) | (unsigned)(ib - 3);
	v_and_b32_e32 v6, 0xffffff80, v6
	v_sub_u32_e32 v6, v6, v177
	v_xor_b32_e32 v7, v17, v7
	v_ashrrev_i32_e32 v16, 31, v8
	v_or_b32_e32 v17, 0x80000000, v16

; DI unsigned fkey(float f) { const unsigned u = __float_as_uint(f); return (u & 0x80000000u) ? ~u : (u | 0x80000000u); }
; DI void topk_phase(unsigned char* smem_, const bf16_t* __restrict__ qp, const bf16_t* __restrict__ keys, int* __restrict__ eidx, float* __restrict__ gate) {
;     ...
;             const f32x4 sv4 = *(const f32x4*)(S + row * LDS_ + 32 * q + 4 * i);
;             const int ib = 127 - (32 * q + 4 * i);
;             v[4 * i] = (fkey(sv4.x) & ~127u) | (unsigned)ib; v[4 * i + 1] = (fkey(sv4.y) & ~127u) | (unsigned)(ib - 1);
;             v[4 * i + 2] = (fkey(sv4.z) & ~127u) | (unsigned)(ib - 2); v[4 * i + 3] = (fkey(sv4.w) & ~127u) | (unsigned)(ib - 3);
	v_and_b32_e32 v7, 0xffffff80, v7
	v_sub_u32_e32 v7, v7, v177
	v_xor_b32_e32 v8, v17, v8
	v_ashrrev_i32_e32 v16, 31, v9
	v_or_b32_e32 v17, 0x80000000, v16

; DI unsigned fkey(float f) { const unsigned u = __float_as_uint(f); return (u & 0x80000000u) ? ~u : (u | 0x80000000u); }
; DI void topk_phase(unsigned char* smem_, const bf16_t* __restrict__ qp, const bf16_t* __restrict__ keys, int* __restrict__ eidx, float* __restrict__ gate) {
;     ...
;             const f32x4 sv4 = *(const f32x4*)(S + row * LDS_ + 32 * q + 4 * i);
;             const int ib = 127 - (32 * q + 4 * i);
;             v[4 * i] = (fkey(sv4.x) & ~127u) | (unsigned)ib; v[4 * i + 1] = (fkey(sv4.y) & ~127u) | (unsigned)(ib - 1);
;             v[4 * i + 2] = (fkey(sv4.z) & ~127u) | (unsigned)(ib - 2); v[4 * i + 3] = (fkey(sv4.w) & ~127u) | (unsigned)(ib - 3);
	v_and_b32_e32 v8, 0xffffff80, v8
	v_sub_u32_e32 v8, v8, v178
	v_xor_b32_e32 v9, v17, v9
	v_ashrrev_i32_e32 v16, 31, v10
	v_or_b32_e32 v17, 0x80000000, v16

; DI unsigned fkey(float f) { const unsigned u = __float_as_uint(f); return (u & 0x80000000u) ? ~u : (u | 0x80000000u); }
; DI void topk_phase(unsigned char* smem_, const bf16_t* __restrict__ qp, const bf16_t* __restrict__ keys, int* __restrict__ eidx, float* __restrict__ gate) {
;     ...
;             const f32x4 sv4 = *(const f32x4*)(S + row * LDS_ + 32 * q + 4 * i);
;             const int ib = 127 - (32 * q + 4 * i);
;             v[4 * i] = (fkey(sv4.x) & ~127u) | (unsigned)ib; v[4 * i + 1] = (fkey(sv4.y) & ~127u) | (unsigned)(ib - 1);
;             v[4 * i + 2] = (fkey(sv4.z) & ~127u) | (unsigned)(ib - 2); v[4 * i + 3] = (fkey(sv4.w) & ~127u) | (unsigned)(ib - 3);
	v_and_b32_e32 v9, 0xffffff80, v9
	v_sub_u32_e32 v9, v9, v178
	v_xor_b32_e32 v10, v17, v10
	v_and_b32_e32 v10, 0xffffff80, v10
	v_sub_u32_e32 v10, v10, v178
	v_add_u32_e32 v16, 0x7d, v10
	v_not_b32_e32 v10, v11
	v_or_b32_e32 v17, 0x80000000, v11
	v_cmp_gt_i32_e32 vcc, 0, v11
	v_ashrrev_i32_e32 v11, 31, v12
	v_add_u32_e32 v0, 0x7f, v0
	v_cndmask_b32_e32 v10, v17, v10, vcc
	v_and_b32_e32 v10, 0xffffff80, v10
	v_sub_u32_e32 v10, v10, v178
	v_add_u32_e32 v17, 0x7c, v10
	v_or_b32_e32 v10, 0x80000000, v11

; DI unsigned fkey(float f) { const unsigned u = __float_as_uint(f); return (u & 0x80000000u) ? ~u : (u | 0x80000000u); }
; DI void topk_phase(unsigned char* smem_, const bf16_t* __restrict__ qp, const bf16_t* __restrict__ keys, int* __restrict__ eidx, float* __restrict__ gate) {
;     ...
;             const f32x4 sv4 = *(const f32x4*)(S + row * LDS_ + 32 * q + 4 * i);
;             const int ib = 127 - (32 * q + 4 * i);
;             v[4 * i] = (fkey(sv4.x) & ~127u) | (unsigned)ib; v[4 * i + 1] = (fkey(sv4.y) & ~127u) | (unsigned)(ib - 1);
;             v[4 * i + 2] = (fkey(sv4.z) & ~127u) | (unsigned)(ib - 2); v[4 * i + 3] = (fkey(sv4.w) & ~127u) | (unsigned)(ib - 3);
	v_add_u32_e32 v1, 0x7e, v1
	v_add_u32_e32 v2, 0x7d, v2
	v_xor_b32_e32 v10, v10, v12
	v_and_b32_e32 v10, 0xffffff80, v10
	v_sub_u32_e32 v10, v10, v179
	v_add_u32_e32 v18, 0x7f, v10
	v_ashrrev_i32_e32 v10, 31, v13
	v_or_b32_e32 v11, 0x80000000, v10

; DI unsigned fkey(float f) { const unsigned u = __float_as_uint(f); return (u & 0x80000000u) ? ~u : (u | 0x80000000u); }
; DI void topk_phase(unsigned char* smem_, const bf16_t* __restrict__ qp, const bf16_t* __restrict__ keys, int* __restrict__ eidx, float* __restrict__ gate) {
;     ...
;             const f32x4 sv4 = *(const f32x4*)(S + row * LDS_ + 32 * q + 4 * i);
;             const int ib = 127 - (32 * q + 4 * i);
;             v[4 * i] = (fkey(sv4.x) & ~127u) | (unsigned)ib; v[4 * i + 1] = (fkey(sv4.y) & ~127u) | (unsigned)(ib - 1);
;             v[4 * i + 2] = (fkey(sv4.z) & ~127u) | (unsigned)(ib - 2); v[4 * i + 3] = (fkey(sv4.w) & ~127u) | (unsigned)(ib - 3);
	v_add_u32_e32 v3, 0x7c, v3
	v_add_u32_e32 v4, 0x7f, v4
	v_xor_b32_e32 v10, v11, v13
	v_and_b32_e32 v10, 0xffffff80, v10
	v_sub_u32_e32 v10, v10, v179
	v_add_u32_e32 v19, 0x7e, v10
	v_ashrrev_i32_e32 v10, 31, v14
	v_or_b32_e32 v11, 0x80000000, v10

; DI unsigned fkey(float f) { const unsigned u = __float_as_uint(f); return (u & 0x80000000u) ? ~u : (u | 0x80000000u); }
; DI void topk_phase(unsigned char* smem_, const bf16_t* __restrict__ qp, const bf16_t* __restrict__ keys, int* __restrict__ eidx, float* __restrict__ gate) {
;     ...
;             const f32x4 sv4 = *(const f32x4*)(S + row * LDS_ + 32 * q + 4 * i);
;             const int ib = 127 - (32 * q + 4 * i);
;             v[4 * i] = (fkey(sv4.x) & ~127u) | (unsigned)ib; v[4 * i + 1] = (fkey(sv4.y) & ~127u) | (unsigned)(ib - 1);
;             v[4 * i + 2] = (fkey(sv4.z) & ~127u) | (unsigned)(ib - 2); v[4 * i + 3] = (fkey(sv4.w) & ~127u) | (unsigned)(ib - 3);
	v_add_u32_e32 v5, 0x7e, v5
	v_add_u32_e32 v6, 0x7d, v6
	v_xor_b32_e32 v10, v11, v14
	v_and_b32_e32 v10, 0xffffff80, v10
	v_sub_u32_e32 v10, v10, v179
	v_add_u32_e32 v14, 0x7d, v10
	ds_read_b128 v[10:13], v171 offset:17472
	v_cmp_gt_i32_e32 vcc, 0, v15
	v_add_u32_e32 v7, 0x7c, v7
	v_add_u32_e32 v8, 0x7f, v8
	v_cndmask_b32_e32 v15, v21, v20, vcc
	s_waitcnt lgkmcnt(0)
	v_ashrrev_i32_e32 v20, 31, v10
	v_or_b32_e32 v21, 0x80000000, v20

; DI unsigned fkey(float f) { const unsigned u = __float_as_uint(f); return (u & 0x80000000u) ? ~u : (u | 0x80000000u); }
; DI void topk_phase(unsigned char* smem_, const bf16_t* __restrict__ qp, const bf16_t* __restrict__ keys, int* __restrict__ eidx, float* __restrict__ gate) {
;     ...
;             const f32x4 sv4 = *(const f32x4*)(S + row * LDS_ + 32 * q + 4 * i);
;             const int ib = 127 - (32 * q + 4 * i);
;             v[4 * i] = (fkey(sv4.x) & ~127u) | (unsigned)ib; v[4 * i + 1] = (fkey(sv4.y) & ~127u) | (unsigned)(ib - 1);
;             v[4 * i + 2] = (fkey(sv4.z) & ~127u) | (unsigned)(ib - 2); v[4 * i + 3] = (fkey(sv4.w) & ~127u) | (unsigned)(ib - 3);
	v_not_b32_e32 v23, v13
	v_or_b32_e32 v24, 0x80000000, v13
	v_xor_b32_e32 v10, v21, v10
	v_and_b32_e32 v10, 0xffffff80, v10
	v_sub_u32_e32 v10, v10, v180
	v_add_u32_e32 v20, 0x7f, v10
	v_not_b32_e32 v10, v11
	v_or_b32_e32 v21, 0x80000000, v11
	v_cmp_gt_i32_e32 vcc, 0, v11
	v_ashrrev_i32_e32 v11, 31, v12
	v_and_b32_e32 v15, 0xffffff80, v15
	v_cndmask_b32_e32 v10, v21, v10, vcc
	v_and_b32_e32 v10, 0xffffff80, v10
	v_sub_u32_e32 v10, v10, v180
	v_add_u32_e32 v21, 0x7e, v10
	v_or_b32_e32 v10, 0x80000000, v11

; DI unsigned fkey(float f) { const unsigned u = __float_as_uint(f); return (u & 0x80000000u) ? ~u : (u | 0x80000000u); }
; DI void topk_phase(unsigned char* smem_, const bf16_t* __restrict__ qp, const bf16_t* __restrict__ keys, int* __restrict__ eidx, float* __restrict__ gate) {
;     ...
;             const f32x4 sv4 = *(const f32x4*)(S + row * LDS_ + 32 * q + 4 * i);
;             const int ib = 127 - (32 * q + 4 * i);
;             v[4 * i] = (fkey(sv4.x) & ~127u) | (unsigned)ib; v[4 * i + 1] = (fkey(sv4.y) & ~127u) | (unsigned)(ib - 1);
;             v[4 * i + 2] = (fkey(sv4.z) & ~127u) | (unsigned)(ib - 2); v[4 * i + 3] = (fkey(sv4.w) & ~127u) | (unsigned)(ib - 3);
	v_sub_u32_e32 v15, v15, v179
	v_add_u32_e32 v9, 0x7e, v9
	v_xor_b32_e32 v10, v10, v12
	v_and_b32_e32 v10, 0xffffff80, v10
	v_sub_u32_e32 v10, v10, v180
	v_add_u32_e32 v22, 0x7d, v10
	v_cmp_gt_i32_e32 vcc, 0, v13
	ds_read_b128 v[10:13], v171 offset:17488
	v_add_u32_e32 v15, 0x7c, v15
	v_cndmask_b32_e32 v23, v24, v23, vcc
	v_and_b32_e32 v23, 0xffffff80, v23
	v_sub_u32_e32 v23, v23, v180
	s_waitcnt lgkmcnt(0)
	v_ashrrev_i32_e32 v24, 31, v10
	v_or_b32_e32 v25, 0x80000000, v24

; DI unsigned fkey(float f) { const unsigned u = __float_as_uint(f); return (u & 0x80000000u) ? ~u : (u | 0x80000000u); }
; DI void topk_phase(unsigned char* smem_, const bf16_t* __restrict__ qp, const bf16_t* __restrict__ keys, int* __restrict__ eidx, float* __restrict__ gate) {
;     ...
;             const f32x4 sv4 = *(const f32x4*)(S + row * LDS_ + 32 * q + 4 * i);
;             const int ib = 127 - (32 * q + 4 * i);
;             v[4 * i] = (fkey(sv4.x) & ~127u) | (unsigned)ib; v[4 * i + 1] = (fkey(sv4.y) & ~127u) | (unsigned)(ib - 1);
;             v[4 * i + 2] = (fkey(sv4.z) & ~127u) | (unsigned)(ib - 2); v[4 * i + 3] = (fkey(sv4.w) & ~127u) | (unsigned)(ib - 3);
	v_not_b32_e32 v27, v13
	v_or_b32_e32 v28, 0x80000000, v13
	v_xor_b32_e32 v10, v25, v10
	v_and_b32_e32 v10, 0xffffff80, v10
	v_sub_u32_e32 v10, v10, v181
	v_add_u32_e32 v24, 0x7f, v10
	v_not_b32_e32 v10, v11
	v_or_b32_e32 v25, 0x80000000, v11
	v_cmp_gt_i32_e32 vcc, 0, v11
	v_ashrrev_i32_e32 v11, 31, v12
	v_add_u32_e32 v23, 0x7c, v23
	v_cndmask_b32_e32 v10, v25, v10, vcc
	v_and_b32_e32 v10, 0xffffff80, v10
	v_sub_u32_e32 v10, v10, v181
	v_add_u32_e32 v25, 0x7e, v10
	v_or_b32_e32 v10, 0x80000000, v11

; DI unsigned fkey(float f) { const unsigned u = __float_as_uint(f); return (u & 0x80000000u) ? ~u : (u | 0x80000000u); }
; DI void topk_phase(unsigned char* smem_, const bf16_t* __restrict__ qp, const bf16_t* __restrict__ keys, int* __restrict__ eidx, float* __restrict__ gate) {
;     ...
;         for (int i = 0; i < 8; ++i) {
;             const f32x4 sv4 = *(const f32x4*)(S + row * LDS_ + 32 * q + 4 * i);
;             const int ib = 127 - (32 * q + 4 * i);
;             v[4 * i] = (fkey(sv4.x) & ~127u) | (unsigned)ib; v[4 * i + 1] = (fkey(sv4.y) & ~127u) | (unsigned)(ib - 1);
;             v[4 * i + 2] = (fkey(sv4.z) & ~127u) | (unsigned)(ib - 2); v[4 * i + 3] = (fkey(sv4.w) & ~127u) | (unsigned)(ib - 3);
;         }
	s_nop 1
	v_xor_b32_e32 v10, v10, v12
	v_and_b32_e32 v10, 0xffffff80, v10
	v_sub_u32_e32 v10, v10, v181
	v_add_u32_e32 v26, 0x7d, v10
	v_cmp_gt_i32_e32 vcc, 0, v13
	ds_read_b128 v[10:13], v171 offset:17504
	s_waitcnt lgkmcnt(0)
	v_ashrrev_i32_e32 v29, 31, v10
	v_cndmask_b32_e32 v27, v28, v27, vcc
	v_or_b32_e32 v28, 0x80000000, v29

; DI unsigned fkey(float f) { const unsigned u = __float_as_uint(f); return (u & 0x80000000u) ? ~u : (u | 0x80000000u); }
; DI void topk_phase(unsigned char* smem_, const bf16_t* __restrict__ qp, const bf16_t* __restrict__ keys, int* __restrict__ eidx, float* __restrict__ gate) {
;     ...
;         for (int i = 0; i < 8; ++i) {
;             const f32x4 sv4 = *(const f32x4*)(S + row * LDS_ + 32 * q + 4 * i);
;             const int ib = 127 - (32 * q + 4 * i);
;             v[4 * i] = (fkey(sv4.x) & ~127u) | (unsigned)ib; v[4 * i + 1] = (fkey(sv4.y) & ~127u) | (unsigned)(ib - 1);
;             v[4 * i + 2] = (fkey(sv4.z) & ~127u) | (unsigned)(ib - 2); v[4 * i + 3] = (fkey(sv4.w) & ~127u) | (unsigned)(ib - 3);
;         }
	v_not_b32_e32 v31, v13
	v_or_b32_e32 v116, 0x80000000, v13
	v_xor_b32_e32 v10, v28, v10
	v_and_b32_e32 v10, 0xffffff80, v10
	v_sub_u32_e32 v10, v10, v182
	v_add_u32_e32 v28, 0x7f, v10
	v_not_b32_e32 v10, v11
	v_or_b32_e32 v29, 0x80000000, v11
	v_cmp_gt_i32_e32 vcc, 0, v11
	v_ashrrev_i32_e32 v11, 31, v12
	v_and_b32_e32 v27, 0xffffff80, v27
	v_cndmask_b32_e32 v10, v29, v10, vcc
	v_and_b32_e32 v10, 0xffffff80, v10
	v_sub_u32_e32 v10, v10, v182
	v_add_u32_e32 v29, 0x7e, v10
	v_or_b32_e32 v10, 0x80000000, v11

; DI unsigned fkey(float f) { const unsigned u = __float_as_uint(f); return (u & 0x80000000u) ? ~u : (u | 0x80000000u); }
; DI void topk_phase(unsigned char* smem_, const bf16_t* __restrict__ qp, const bf16_t* __restrict__ keys, int* __restrict__ eidx, float* __restrict__ gate) {
;     ...
;         for (int i = 0; i < 8; ++i) {
;             const f32x4 sv4 = *(const f32x4*)(S + row * LDS_ + 32 * q + 4 * i);
;             const int ib = 127 - (32 * q + 4 * i);
;             v[4 * i] = (fkey(sv4.x) & ~127u) | (unsigned)ib; v[4 * i + 1] = (fkey(sv4.y) & ~127u) | (unsigned)(ib - 1);
;             v[4 * i + 2] = (fkey(sv4.z) & ~127u) | (unsigned)(ib - 2); v[4 * i + 3] = (fkey(sv4.w) & ~127u) | (unsigned)(ib - 3);
;         }
	v_sub_u32_e32 v27, v27, v181
	v_add_u32_e32 v27, 0x7c, v27
	v_xor_b32_e32 v10, v10, v12
	v_and_b32_e32 v10, 0xffffff80, v10
	v_sub_u32_e32 v10, v10, v182
	v_add_u32_e32 v30, 0x7d, v10
	v_cmp_gt_i32_e32 vcc, 0, v13
	ds_read_b128 v[10:13], v171 offset:17520
	s_waitcnt lgkmcnt(0)
	v_ashrrev_i32_e32 v117, 31, v10
	v_cndmask_b32_e32 v31, v116, v31, vcc
	v_or_b32_e32 v116, 0x80000000, v117

; DI unsigned fkey(float f) { const unsigned u = __float_as_uint(f); return (u & 0x80000000u) ? ~u : (u | 0x80000000u); }
; DI void topk_phase(unsigned char* smem_, const bf16_t* __restrict__ qp, const bf16_t* __restrict__ keys, int* __restrict__ eidx, float* __restrict__ gate) {
;     ...
;         for (int i = 0; i < 8; ++i) {
;             const f32x4 sv4 = *(const f32x4*)(S + row * LDS_ + 32 * q + 4 * i);
;             const int ib = 127 - (32 * q + 4 * i);
;             v[4 * i] = (fkey(sv4.x) & ~127u) | (unsigned)ib; v[4 * i + 1] = (fkey(sv4.y) & ~127u) | (unsigned)(ib - 1);
;             v[4 * i + 2] = (fkey(sv4.z) & ~127u) | (unsigned)(ib - 2); v[4 * i + 3] = (fkey(sv4.w) & ~127u) | (unsigned)(ib - 3);
;         }
	v_and_b32_e32 v31, 0xffffff80, v31
	v_sub_u32_e32 v31, v31, v182
	v_xor_b32_e32 v10, v116, v10
	v_ashrrev_i32_e32 v116, 31, v11
	v_or_b32_e32 v117, 0x80000000, v116

; DI unsigned fkey(float f) { const unsigned u = __float_as_uint(f); return (u & 0x80000000u) ? ~u : (u | 0x80000000u); }
; DI void topk_phase(unsigned char* smem_, const bf16_t* __restrict__ qp, const bf16_t* __restrict__ keys, int* __restrict__ eidx, float* __restrict__ gate) {
;     ...
;         for (int i = 0; i < 8; ++i) {
;             const f32x4 sv4 = *(const f32x4*)(S + row * LDS_ + 32 * q + 4 * i);
;             const int ib = 127 - (32 * q + 4 * i);
;             v[4 * i] = (fkey(sv4.x) & ~127u) | (unsigned)ib; v[4 * i + 1] = (fkey(sv4.y) & ~127u) | (unsigned)(ib - 1);
;             v[4 * i + 2] = (fkey(sv4.z) & ~127u) | (unsigned)(ib - 2); v[4 * i + 3] = (fkey(sv4.w) & ~127u) | (unsigned)(ib - 3);
;         }
	v_and_b32_e32 v10, 0xffffff80, v10
	v_sub_u32_e32 v10, v10, v183
	v_xor_b32_e32 v11, v117, v11
	v_ashrrev_i32_e32 v116, 31, v12
	v_or_b32_e32 v117, 0x80000000, v116

; DI unsigned fkey(float f) { const unsigned u = __float_as_uint(f); return (u & 0x80000000u) ? ~u : (u | 0x80000000u); }
; DI void topk_phase(unsigned char* smem_, const bf16_t* __restrict__ qp, const bf16_t* __restrict__ keys, int* __restrict__ eidx, float* __restrict__ gate) {
;     ...
;         for (int i = 0; i < 8; ++i) {
;             const f32x4 sv4 = *(const f32x4*)(S + row * LDS_ + 32 * q + 4 * i);
;             const int ib = 127 - (32 * q + 4 * i);
;             v[4 * i] = (fkey(sv4.x) & ~127u) | (unsigned)ib; v[4 * i + 1] = (fkey(sv4.y) & ~127u) | (unsigned)(ib - 1);
;             v[4 * i + 2] = (fkey(sv4.z) & ~127u) | (unsigned)(ib - 2); v[4 * i + 3] = (fkey(sv4.w) & ~127u) | (unsigned)(ib - 3);
;         }
	v_and_b32_e32 v11, 0xffffff80, v11
	v_sub_u32_e32 v11, v11, v183
	v_xor_b32_e32 v12, v117, v12
	v_ashrrev_i32_e32 v116, 31, v13
	v_or_b32_e32 v117, 0x80000000, v116

; DI unsigned fkey(float f) { const unsigned u = __float_as_uint(f); return (u & 0x80000000u) ? ~u : (u | 0x80000000u); }
; template <int N> DI void bitonic_sort_desc(unsigned (&v)[N]) {
; #pragma unroll
;     for (int k = 2; k <= N; k <<= 1)
; #pragma unroll
;         for (int j = k >> 1; j > 0; j >>= 1)
; #pragma unroll
;             for (int i = 0; i < N; ++i) { const int l = i ^ j; if (l > i) { if ((i & k) == 0) cswap(v[i], v[l]); else cswap(v[l], v[i]); } }
; DI void topk_phase(unsigned char* smem_, const bf16_t* __restrict__ qp, const bf16_t* __restrict__ keys, int* __restrict__ eidx, float* __restrict__ gate) {
;     ...
;         for (int i = 0; i < 8; ++i) {
;             const f32x4 sv4 = *(const f32x4*)(S + row * LDS_ + 32 * q + 4 * i);
;             const int ib = 127 - (32 * q + 4 * i);
;             v[4 * i] = (fkey(sv4.x) & ~127u) | (unsigned)ib; v[4 * i + 1] = (fkey(sv4.y) & ~127u) | (unsigned)(ib - 1);
;             v[4 * i + 2] = (fkey(sv4.z) & ~127u) | (unsigned)(ib - 2); v[4 * i + 3] = (fkey(sv4.w) & ~127u) | (unsigned)(ib - 3);
;         }
;         bitonic_sort_desc<32>(v);
	v_and_b32_e32 v12, 0xffffff80, v12
	v_sub_u32_e32 v12, v12, v183
	v_xor_b32_e32 v13, v117, v13
	v_and_b32_e32 v13, 0xffffff80, v13
	v_sub_u32_e32 v13, v13, v183
	v_add_u32_e32 v31, 0x7c, v31
	v_add_u32_e32 v10, 0x7f, v10
	v_add_u32_e32 v11, 0x7e, v11
	v_add_u32_e32 v12, 0x7d, v12
	v_add_u32_e32 v13, 0x7c, v13
	v_max_u32_e32 v116, v0, v1
	v_min_u32_e32 v0, v0, v1
	v_max_u32_e32 v1, v3, v2
	v_min_u32_e32 v2, v3, v2
	v_max_u32_e32 v3, v4, v5
	v_min_u32_e32 v4, v4, v5
	v_max_u32_e32 v5, v7, v6
	v_min_u32_e32 v6, v7, v6
	v_max_u32_e32 v7, v8, v9
	v_min_u32_e32 v8, v8, v9
	v_max_u32_e32 v9, v17, v16
	v_min_u32_e32 v16, v17, v16
	v_max_u32_e32 v17, v18, v19
	v_min_u32_e32 v18, v18, v19
	v_max_u32_e32 v19, v15, v14
	v_min_u32_e32 v14, v15, v14
	v_max_u32_e32 v15, v20, v21
	v_min_u32_e32 v20, v20, v21
	v_max_u32_e32 v21, v23, v22
	v_min_u32_e32 v22, v23, v22
	v_max_u32_e32 v23, v24, v25
	v_min_u32_e32 v24, v24, v25
	v_max_u32_e32 v25, v27, v26
	v_min_u32_e32 v26, v27, v26
	v_max_u32_e32 v27, v28, v29
	v_min_u32_e32 v28, v28, v29
	v_max_u32_e32 v29, v31, v30
	v_min_u32_e32 v30, v31, v30
	v_max_u32_e32 v31, v10, v11
	v_min_u32_e32 v10, v10, v11
	v_max_u32_e32 v11, v13, v12
	v_min_u32_e32 v12, v13, v12
	v_max_u32_e32 v13, v116, v2
	v_min_u32_e32 v2, v116, v2
	v_max_u32_e32 v116, v0, v1
	v_min_u32_e32 v0, v0, v1
	v_max_u32_e32 v1, v6, v3
	v_min_u32_e32 v3, v6, v3
	v_max_u32_e32 v6, v5, v4
	v_min_u32_e32 v4, v5, v4
	v_max_u32_e32 v5, v7, v16
	v_min_u32_e32 v7, v7, v16
	v_max_u32_e32 v16, v8, v9
	v_min_u32_e32 v8, v8, v9
	v_max_u32_e32 v9, v14, v17
	v_min_u32_e32 v14, v14, v17
	v_max_u32_e32 v17, v19, v18
	v_min_u32_e32 v18, v19, v18
	v_max_u32_e32 v19, v15, v22
	v_min_u32_e32 v15, v15, v22
	v_max_u32_e32 v22, v20, v21
	v_min_u32_e32 v20, v20, v21
	v_max_u32_e32 v21, v26, v23
	v_min_u32_e32 v23, v26, v23
	v_max_u32_e32 v26, v25, v24
	v_min_u32_e32 v24, v25, v24
	v_max_u32_e32 v25, v27, v30
	v_min_u32_e32 v27, v27, v30
	v_max_u32_e32 v30, v28, v29
	v_min_u32_e32 v28, v28, v29
	v_max_u32_e32 v29, v12, v31
	v_min_u32_e32 v12, v12, v31
	v_max_u32_e32 v31, v11, v10
	v_min_u32_e32 v10, v11, v10
	v_max_u32_e32 v11, v13, v116
	v_min_u32_e32 v13, v13, v116
	v_max_u32_e32 v116, v2, v0
	v_min_u32_e32 v0, v2, v0
	v_max_u32_e32 v2, v4, v3
	v_min_u32_e32 v3, v4, v3
	v_max_u32_e32 v4, v6, v1
	v_min_u32_e32 v1, v6, v1
	v_max_u32_e32 v6, v5, v16
	v_min_u32_e32 v5, v5, v16
	v_max_u32_e32 v16, v7, v8
	v_min_u32_e32 v7, v7, v8
	v_max_u32_e32 v8, v18, v14
	v_min_u32_e32 v14, v18, v14
	v_max_u32_e32 v18, v17, v9
	v_min_u32_e32 v9, v17, v9
	v_max_u32_e32 v17, v19, v22
	v_min_u32_e32 v19, v19, v22
	v_max_u32_e32 v22, v15, v20
	v_min_u32_e32 v15, v15, v20
	v_max_u32_e32 v20, v24, v23
	v_min_u32_e32 v23, v24, v23
	v_max_u32_e32 v24, v26, v21
	v_min_u32_e32 v21, v26, v21
	v_max_u32_e32 v26, v25, v30
	v_min_u32_e32 v25, v25, v30
	v_max_u32_e32 v30, v27, v28
	v_min_u32_e32 v27, v27, v28
	v_max_u32_e32 v28, v10, v12
	v_min_u32_e32 v10, v10, v12
	v_max_u32_e32 v12, v31, v29
	v_min_u32_e32 v29, v31, v29
	v_max_u32_e32 v31, v11, v3
	v_min_u32_e32 v3, v11, v3
	v_max_u32_e32 v11, v13, v2
	v_min_u32_e32 v2, v13, v2
	v_max_u32_e32 v13, v116, v1
	v_min_u32_e32 v1, v116, v1
	v_max_u32_e32 v116, v0, v4
	v_min_u32_e32 v0, v0, v4
	v_max_u32_e32 v4, v14, v6
	v_min_u32_e32 v6, v14, v6
	v_max_u32_e32 v14, v8, v5
	v_min_u32_e32 v5, v8, v5
	v_max_u32_e32 v8, v9, v16
	v_min_u32_e32 v9, v9, v16
	v_max_u32_e32 v16, v18, v7
	v_min_u32_e32 v7, v18, v7
	v_max_u32_e32 v18, v17, v23
	v_min_u32_e32 v17, v17, v23
	v_max_u32_e32 v23, v19, v20
	v_min_u32_e32 v19, v19, v20
	v_max_u32_e32 v20, v22, v21
	v_min_u32_e32 v21, v22, v21
	v_max_u32_e32 v22, v15, v24
	v_min_u32_e32 v15, v15, v24
	v_max_u32_e32 v24, v10, v26
	v_min_u32_e32 v10, v10, v26
	v_max_u32_e32 v26, v28, v25
	v_min_u32_e32 v25, v28, v25
	v_max_u32_e32 v28, v29, v30
	v_min_u32_e32 v29, v29, v30
	v_max_u32_e32 v30, v12, v27
	v_min_u32_e32 v12, v12, v27
	v_max_u32_e32 v27, v31, v13
	v_min_u32_e32 v13, v31, v13
	v_max_u32_e32 v31, v11, v116
	v_min_u32_e32 v11, v11, v116
	v_max_u32_e32 v116, v3, v1
	v_min_u32_e32 v1, v3, v1
	v_max_u32_e32 v3, v2, v0
	v_min_u32_e32 v0, v2, v0
	v_max_u32_e32 v2, v9, v6
	v_min_u32_e32 v6, v9, v6
	v_max_u32_e32 v9, v7, v5
	v_min_u32_e32 v5, v7, v5
	v_max_u32_e32 v7, v8, v4
	v_min_u32_e32 v4, v8, v4
	v_max_u32_e32 v8, v16, v14
	v_min_u32_e32 v14, v16, v14
	v_max_u32_e32 v16, v18, v20
	v_min_u32_e32 v18, v18, v20
	v_max_u32_e32 v20, v23, v22
	v_min_u32_e32 v22, v23, v22
	v_max_u32_e32 v23, v17, v21
	v_min_u32_e32 v17, v17, v21
	v_max_u32_e32 v21, v19, v15
	v_min_u32_e32 v15, v19, v15
	v_max_u32_e32 v19, v29, v10
	v_min_u32_e32 v10, v29, v10
	v_max_u32_e32 v29, v12, v25
	v_min_u32_e32 v12, v12, v25
	v_max_u32_e32 v25, v28, v24
	v_min_u32_e32 v24, v28, v24
	v_max_u32_e32 v28, v30, v26
	v_min_u32_e32 v26, v30, v26
	v_max_u32_e32 v30, v27, v31
	v_min_u32_e32 v27, v27, v31
	v_max_u32_e32 v31, v13, v11
	v_min_u32_e32 v11, v13, v11
	v_max_u32_e32 v13, v116, v3
	v_min_u32_e32 v3, v116, v3
	v_max_u32_e32 v116, v1, v0
	v_min_u32_e32 v0, v1, v0
	v_max_u32_e32 v1, v5, v6
	v_min_u32_e32 v5, v5, v6
	v_max_u32_e32 v6, v9, v2
	v_min_u32_e32 v2, v9, v2
	v_max_u32_e32 v9, v14, v4
	v_min_u32_e32 v4, v14, v4
	v_max_u32_e32 v14, v8, v7
	v_min_u32_e32 v7, v8, v7
	v_max_u32_e32 v8, v16, v20
	v_min_u32_e32 v16, v16, v20
	v_max_u32_e32 v20, v18, v22
	v_min_u32_e32 v18, v18, v22
	v_max_u32_e32 v22, v23, v21
	v_min_u32_e32 v21, v23, v21
	v_max_u32_e32 v23, v17, v15
	v_min_u32_e32 v15, v17, v15
	v_max_u32_e32 v17, v12, v10
	v_min_u32_e32 v10, v12, v10
	v_max_u32_e32 v12, v29, v19
	v_min_u32_e32 v19, v29, v19
	v_max_u32_e32 v29, v26, v24
; template <int N> DI void bitonic_sort_desc(unsigned (&v)[N]) {
; #pragma unroll
;     for (int k = 2; k <= N; k <<= 1)
; #pragma unroll
;         for (int j = k >> 1; j > 0; j >>= 1)
; #pragma unroll
;             for (int i = 0; i < N; ++i) { const int l = i ^ j; if (l > i) { if ((i & k) == 0) cswap(v[i], v[l]); else cswap(v[l], v[i]); } }
; }
; DI void merge_top16(unsigned (&v)[16], int st) {
;     unsigned x[16];
; #pragma unroll
;     for (int i = 0; i < 16; ++i) x[i] = (unsigned)__shfl_xor((int)v[15 - i], st);
; #pragma unroll
;     for (int i = 0; i < 16; ++i) v[i] = max(v[i], x[i]);
; #pragma unroll
;     for (int j = 8; j > 0; j >>= 1)
; #pragma unroll
;         for (int i = 0; i < 16; ++i) { const int l = i ^ j; if (l > i) cswap(v[i], v[l]); }
; }
; DI void topk_phase(unsigned char* smem_, const bf16_t* __restrict__ qp, const bf16_t* __restrict__ keys, int* __restrict__ eidx, float* __restrict__ gate) {
;     ...
;         bitonic_sort_desc<32>(v);
;         unsigned t16[16];
; #pragma unroll
;         for (int i = 0; i < 16; ++i) t16[i] = v[i];
;         merge_top16(t16, 1);
	v_min_u32_e32 v24, v26, v24
	v_max_u32_e32 v26, v28, v25
	v_min_u32_e32 v25, v28, v25
	v_max_u32_e32 v28, v30, v5
	v_min_u32_e32 v5, v30, v5
	v_max_u32_e32 v30, v27, v1
	v_min_u32_e32 v1, v27, v1
	v_max_u32_e32 v27, v31, v2
	v_min_u32_e32 v2, v31, v2
	v_max_u32_e32 v31, v11, v6
	v_min_u32_e32 v6, v11, v6
	v_max_u32_e32 v11, v13, v4
	v_min_u32_e32 v4, v13, v4
	v_max_u32_e32 v13, v3, v9
	v_min_u32_e32 v3, v3, v9
	v_max_u32_e32 v9, v116, v7
	v_min_u32_e32 v7, v116, v7
	v_max_u32_e32 v116, v0, v14
	v_min_u32_e32 v0, v0, v14
	v_max_u32_e32 v14, v10, v8
	v_min_u32_e32 v8, v10, v8
	v_max_u32_e32 v10, v17, v16
	v_min_u32_e32 v16, v17, v16
	v_max_u32_e32 v17, v19, v20
	v_min_u32_e32 v19, v19, v20
	v_max_u32_e32 v20, v12, v18
	v_min_u32_e32 v12, v12, v18
	v_max_u32_e32 v18, v24, v22
	v_min_u32_e32 v22, v24, v22
	v_max_u32_e32 v24, v29, v21
	v_min_u32_e32 v21, v29, v21
	v_max_u32_e32 v29, v25, v23
	v_min_u32_e32 v23, v25, v23
	v_max_u32_e32 v25, v26, v15
	v_min_u32_e32 v15, v26, v15
	v_max_u32_e32 v26, v28, v11
	v_min_u32_e32 v11, v28, v11
	v_max_u32_e32 v28, v30, v13
	v_min_u32_e32 v13, v30, v13
	v_max_u32_e32 v30, v27, v9
	v_min_u32_e32 v9, v27, v9
	v_max_u32_e32 v27, v31, v116
	v_min_u32_e32 v31, v31, v116
	v_max_u32_e32 v116, v5, v4
	v_min_u32_e32 v4, v5, v4
	v_max_u32_e32 v5, v1, v3
	v_min_u32_e32 v1, v1, v3
	v_max_u32_e32 v3, v2, v7
	v_min_u32_e32 v2, v2, v7
	v_max_u32_e32 v7, v6, v0
	v_min_u32_e32 v0, v6, v0
	v_max_u32_e32 v6, v22, v8
	v_min_u32_e32 v8, v22, v8
	v_max_u32_e32 v22, v21, v16
	v_min_u32_e32 v16, v21, v16
	v_max_u32_e32 v21, v23, v19
	v_min_u32_e32 v19, v23, v19
	v_max_u32_e32 v23, v15, v12
	v_min_u32_e32 v12, v15, v12
	v_max_u32_e32 v15, v18, v14
	v_min_u32_e32 v14, v18, v14
	v_max_u32_e32 v18, v24, v10
	v_min_u32_e32 v10, v24, v10
	v_max_u32_e32 v24, v29, v17
	v_min_u32_e32 v17, v29, v17
	v_max_u32_e32 v29, v25, v20
	v_min_u32_e32 v20, v25, v20
	v_max_u32_e32 v25, v26, v30
	v_min_u32_e32 v26, v26, v30
	v_max_u32_e32 v30, v28, v27
	v_min_u32_e32 v27, v28, v27
	v_max_u32_e32 v28, v11, v9
	v_min_u32_e32 v9, v11, v9
	v_max_u32_e32 v11, v13, v31
	v_min_u32_e32 v13, v13, v31
	v_max_u32_e32 v31, v116, v3
	v_min_u32_e32 v3, v116, v3
	v_max_u32_e32 v116, v5, v7
	v_min_u32_e32 v5, v5, v7
	v_max_u32_e32 v7, v4, v2
	v_min_u32_e32 v2, v4, v2
	v_max_u32_e32 v4, v1, v0
	v_min_u32_e32 v0, v1, v0
	v_max_u32_e32 v1, v19, v8
	v_min_u32_e32 v8, v19, v8
	v_max_u32_e32 v19, v12, v16
	v_min_u32_e32 v12, v12, v16
	v_max_u32_e32 v16, v21, v6
	v_min_u32_e32 v6, v21, v6
	v_max_u32_e32 v21, v23, v22
	v_min_u32_e32 v22, v23, v22
	v_max_u32_e32 v23, v17, v14
	v_min_u32_e32 v14, v17, v14
	v_max_u32_e32 v17, v20, v10
	v_min_u32_e32 v10, v20, v10
	v_max_u32_e32 v20, v24, v15
	v_min_u32_e32 v15, v24, v15
	v_max_u32_e32 v24, v29, v18
	v_min_u32_e32 v18, v29, v18
	v_min_u32_e32 v29, v25, v30
	v_min_u32_e32 v117, v26, v27
	v_min_u32_e32 v118, v28, v11
	v_min_u32_e32 v119, v9, v13
	v_min_u32_e32 v120, v31, v116
	v_min_u32_e32 v121, v3, v5
	v_min_u32_e32 v122, v7, v4
	v_min_u32_e32 v123, v2, v0
	v_min_u32_e32 v124, v12, v8
	v_min_u32_e32 v125, v19, v1
	v_min_u32_e32 v126, v22, v6
	v_min_u32_e32 v127, v21, v16
	v_min_u32_e32 v142, v10, v14
	v_min_u32_e32 v143, v17, v23
	v_min_u32_e32 v144, v18, v15
	v_min_u32_e32 v145, v24, v20
	v_max3_u32 v25, v25, v30, v124
	v_max3_u32 v8, v29, v12, v8
	v_max3_u32 v12, v26, v27, v125
	v_max3_u32 v1, v117, v19, v1
	v_max3_u32 v11, v28, v11, v126
	v_max3_u32 v6, v118, v22, v6
	v_max3_u32 v9, v9, v13, v127
	v_max3_u32 v13, v119, v21, v16
	v_max3_u32 v16, v31, v116, v142
	v_max3_u32 v10, v120, v10, v14
	v_max3_u32 v3, v3, v5, v143
	v_max3_u32 v5, v121, v17, v23
	v_max3_u32 v4, v7, v4, v144
	v_max3_u32 v7, v122, v18, v15
	v_max3_u32 v0, v2, v0, v145
	v_max3_u32 v2, v123, v24, v20
	v_max_u32_e32 v14, v25, v16
	v_min_u32_e32 v15, v25, v16
	v_max_u32_e32 v16, v8, v10
	v_min_u32_e32 v8, v8, v10
	v_max_u32_e32 v10, v12, v3
	v_min_u32_e32 v3, v12, v3
	v_max_u32_e32 v12, v1, v5
	v_min_u32_e32 v1, v1, v5
	v_max_u32_e32 v5, v11, v4
	v_min_u32_e32 v4, v11, v4
	v_max_u32_e32 v11, v6, v7
	v_min_u32_e32 v6, v6, v7
	v_max_u32_e32 v7, v9, v0
	v_min_u32_e32 v0, v9, v0
	v_max_u32_e32 v9, v13, v2
	v_min_u32_e32 v2, v13, v2
	v_max_u32_e32 v13, v14, v5
	v_min_u32_e32 v5, v14, v5
	v_max_u32_e32 v14, v16, v11
	v_min_u32_e32 v11, v16, v11
	v_max_u32_e32 v16, v10, v7
	v_min_u32_e32 v7, v10, v7
	v_max_u32_e32 v10, v12, v9
	v_min_u32_e32 v9, v12, v9
	v_max_u32_e32 v12, v15, v4
	v_min_u32_e32 v4, v15, v4
	v_max_u32_e32 v15, v8, v6
	v_min_u32_e32 v6, v8, v6
	v_max_u32_e32 v8, v3, v0
	v_min_u32_e32 v0, v3, v0
	v_max_u32_e32 v3, v1, v2
	v_min_u32_e32 v1, v1, v2
	v_max_u32_e32 v2, v13, v16
	v_min_u32_e32 v13, v13, v16
	v_max_u32_e32 v16, v14, v10
	v_min_u32_e32 v10, v14, v10
	v_max_u32_e32 v14, v5, v7
	v_min_u32_e32 v5, v5, v7
	v_max_u32_e32 v7, v11, v9
	v_min_u32_e32 v9, v11, v9
	v_max_u32_e32 v11, v12, v8
	v_min_u32_e32 v8, v12, v8
	v_max_u32_e32 v12, v15, v3
	v_min_u32_e32 v3, v15, v3
	v_max_u32_e32 v15, v4, v0
	v_min_u32_e32 v0, v4, v0
	v_max_u32_e32 v4, v6, v1
	v_min_u32_e32 v1, v6, v1
	v_max_u32_e32 v6, v2, v16
	v_min_u32_e32 v2, v2, v16
	v_max_u32_e32 v16, v13, v10
	v_min_u32_e32 v10, v13, v10
	v_max_u32_e32 v13, v14, v7
	v_min_u32_e32 v7, v14, v7
	v_max_u32_e32 v14, v5, v9
	v_min_u32_e32 v5, v5, v9
	v_max_u32_e32 v9, v11, v12
	v_min_u32_e32 v11, v11, v12
	v_max_u32_e32 v12, v8, v3
	v_min_u32_e32 v3, v8, v3
	v_max_u32_e32 v8, v15, v4
	v_min_u32_e32 v4, v15, v4
	v_max_u32_e32 v15, v0, v1
	v_min_u32_e32 v0, v0, v1
	s_nop 1
	v_mov_b32_dpp v1, v0 quad_perm:[1,0,3,2] row_mask:0xf bank_mask:0xf
	v_mov_b32_dpp v17, v15 quad_perm:[1,0,3,2] row_mask:0xf bank_mask:0xf
	v_mov_b32_dpp v18, v4 quad_perm:[1,0,3,2] row_mask:0xf bank_mask:0xf
	v_mov_b32_dpp v19, v8 quad_perm:[1,0,3,2] row_mask:0xf bank_mask:0xf
	v_mov_b32_dpp v20, v3 quad_perm:[1,0,3,2] row_mask:0xf bank_mask:0xf
	v_mov_b32_dpp v21, v12 quad_perm:[1,0,3,2] row_mask:0xf bank_mask:0xf
	v_mov_b32_dpp v22, v11 quad_perm:[1,0,3,2] row_mask:0xf bank_mask:0xf
	v_mov_b32_dpp v23, v9 quad_perm:[1,0,3,2] row_mask:0xf bank_mask:0xf
	v_mov_b32_dpp v24, v5 quad_perm:[1,0,3,2] row_mask:0xf bank_mask:0xf
	v_mov_b32_dpp v25, v14 quad_perm:[1,0,3,2] row_mask:0xf bank_mask:0xf
	v_mov_b32_dpp v26, v7 quad_perm:[1,0,3,2] row_mask:0xf bank_mask:0xf
	v_mov_b32_dpp v27, v13 quad_perm:[1,0,3,2] row_mask:0xf bank_mask:0xf
	v_mov_b32_dpp v28, v10 quad_perm:[1,0,3,2] row_mask:0xf bank_mask:0xf
	v_mov_b32_dpp v29, v16 quad_perm:[1,0,3,2] row_mask:0xf bank_mask:0xf
	v_mov_b32_dpp v30, v2 quad_perm:[1,0,3,2] row_mask:0xf bank_mask:0xf
	v_mov_b32_dpp v31, v6 quad_perm:[1,0,3,2] row_mask:0xf bank_mask:0xf
	s_waitcnt lgkmcnt(0)
; DI void merge_top16(unsigned (&v)[16], int st) {
;     unsigned x[16];
; #pragma unroll
;     for (int i = 0; i < 16; ++i) x[i] = (unsigned)__shfl_xor((int)v[15 - i], st);
; #pragma unroll
;     for (int i = 0; i < 16; ++i) v[i] = max(v[i], x[i]);
; #pragma unroll
;     for (int j = 8; j > 0; j >>= 1)
; #pragma unroll
;         for (int i = 0; i < 16; ++i) { const int l = i ^ j; if (l > i) cswap(v[i], v[l]); }
; }
; DI void topk_phase(unsigned char* smem_, const bf16_t* __restrict__ qp, const bf16_t* __restrict__ keys, int* __restrict__ eidx, float* __restrict__ gate) {
;     ...
;         merge_top16(t16, 1);
;         merge_top16(t16, 2);
; #pragma unroll
;         for (int i = 0; i < 16; ++i) if ((i >> 2) == q) { const int idx = 127 - (int)(t16[i] & 127u); SI[row * 32 + 16 * p + i] = idx; SV[row * 32 + 16 * p + i] = S[row * LDS_ + idx]; }
	v_max_u32_e32 v1, v6, v1
	v_max_u32_e32 v2, v2, v17
	v_max_u32_e32 v6, v16, v18
	v_max_u32_e32 v10, v10, v19
	v_max_u32_e32 v13, v13, v20
	v_max_u32_e32 v7, v7, v21
	v_max_u32_e32 v14, v14, v22
	v_max_u32_e32 v5, v5, v23
	v_max_u32_e32 v9, v9, v24
	v_max_u32_e32 v11, v11, v25
	v_max_u32_e32 v12, v12, v26
	v_max_u32_e32 v3, v3, v27
	v_max_u32_e32 v8, v8, v28
	v_max_u32_e32 v4, v4, v29
	v_max_u32_e32 v15, v15, v30
	v_max_u32_e32 v0, v0, v31
	v_max_u32_e32 v16, v1, v9
	v_min_u32_e32 v1, v1, v9
	v_max_u32_e32 v9, v2, v11
	v_min_u32_e32 v2, v2, v11
	v_max_u32_e32 v11, v6, v12
	v_min_u32_e32 v6, v6, v12
	v_max_u32_e32 v12, v10, v3
	v_min_u32_e32 v3, v10, v3
	v_max_u32_e32 v10, v13, v8
	v_min_u32_e32 v8, v13, v8
	v_max_u32_e32 v13, v7, v4
	v_min_u32_e32 v4, v7, v4
	v_max_u32_e32 v7, v14, v15
	v_min_u32_e32 v14, v14, v15
	v_max_u32_e32 v15, v5, v0
	v_min_u32_e32 v0, v5, v0
	v_max_u32_e32 v5, v16, v10
	v_min_u32_e32 v10, v16, v10
	v_max_u32_e32 v16, v9, v13
	v_min_u32_e32 v9, v9, v13
	v_max_u32_e32 v13, v11, v7
	v_min_u32_e32 v7, v11, v7
	v_max_u32_e32 v11, v12, v15
	v_min_u32_e32 v12, v12, v15
	v_max_u32_e32 v15, v1, v8
	v_min_u32_e32 v1, v1, v8
	v_max_u32_e32 v8, v2, v4
	v_min_u32_e32 v2, v2, v4
	v_max_u32_e32 v4, v6, v14
	v_min_u32_e32 v6, v6, v14
	v_max_u32_e32 v14, v3, v0
	v_min_u32_e32 v0, v3, v0
	v_max_u32_e32 v3, v5, v13
	v_min_u32_e32 v5, v5, v13
	v_max_u32_e32 v13, v16, v11
	v_min_u32_e32 v11, v16, v11
	v_max_u32_e32 v16, v10, v7
	v_min_u32_e32 v7, v10, v7
	v_max_u32_e32 v10, v9, v12
	v_min_u32_e32 v9, v9, v12
	v_max_u32_e32 v12, v15, v4
	v_min_u32_e32 v4, v15, v4
	v_max_u32_e32 v15, v8, v14
	v_min_u32_e32 v8, v8, v14
	v_max_u32_e32 v14, v1, v6
	v_min_u32_e32 v1, v1, v6
	v_max_u32_e32 v6, v2, v0
	v_min_u32_e32 v0, v2, v0
	v_max_u32_e32 v2, v3, v13
	v_min_u32_e32 v3, v3, v13
	v_max_u32_e32 v13, v5, v11
	v_min_u32_e32 v5, v5, v11
	v_max_u32_e32 v11, v16, v10
	v_min_u32_e32 v10, v16, v10
	v_max_u32_e32 v16, v7, v9
	v_min_u32_e32 v7, v7, v9
	v_max_u32_e32 v9, v12, v15
	v_min_u32_e32 v12, v12, v15
	v_max_u32_e32 v15, v4, v8
	v_min_u32_e32 v17, v4, v8
	v_max_u32_e32 v18, v14, v6
	v_min_u32_e32 v14, v14, v6
	v_max_u32_e32 v19, v1, v0
	v_min_u32_e32 v20, v1, v0
	s_nop 1
	v_mov_b32_dpp v0, v20 quad_perm:[2,3,0,1] row_mask:0xf bank_mask:0xf
	v_mov_b32_dpp v1, v19 quad_perm:[2,3,0,1] row_mask:0xf bank_mask:0xf
	v_mov_b32_dpp v4, v14 quad_perm:[2,3,0,1] row_mask:0xf bank_mask:0xf
	v_mov_b32_dpp v6, v18 quad_perm:[2,3,0,1] row_mask:0xf bank_mask:0xf
	v_mov_b32_dpp v8, v17 quad_perm:[2,3,0,1] row_mask:0xf bank_mask:0xf
	v_mov_b32_dpp v21, v15 quad_perm:[2,3,0,1] row_mask:0xf bank_mask:0xf
	v_mov_b32_dpp v22, v12 quad_perm:[2,3,0,1] row_mask:0xf bank_mask:0xf
	v_mov_b32_dpp v23, v9 quad_perm:[2,3,0,1] row_mask:0xf bank_mask:0xf
	v_mov_b32_dpp v24, v7 quad_perm:[2,3,0,1] row_mask:0xf bank_mask:0xf
	v_mov_b32_dpp v25, v16 quad_perm:[2,3,0,1] row_mask:0xf bank_mask:0xf
	v_mov_b32_dpp v26, v10 quad_perm:[2,3,0,1] row_mask:0xf bank_mask:0xf
	v_mov_b32_dpp v27, v11 quad_perm:[2,3,0,1] row_mask:0xf bank_mask:0xf
	v_mov_b32_dpp v28, v5 quad_perm:[2,3,0,1] row_mask:0xf bank_mask:0xf
	v_mov_b32_dpp v29, v13 quad_perm:[2,3,0,1] row_mask:0xf bank_mask:0xf
	v_mov_b32_dpp v30, v3 quad_perm:[2,3,0,1] row_mask:0xf bank_mask:0xf
	v_mov_b32_dpp v31, v2 quad_perm:[2,3,0,1] row_mask:0xf bank_mask:0xf
	s_waitcnt lgkmcnt(0)
	v_max_u32_e32 v0, v2, v0
	v_max_u32_e32 v1, v3, v1
	v_max_u32_e32 v2, v13, v4
	v_max_u32_e32 v3, v5, v6
	v_max_u32_e32 v4, v11, v8
	v_max_u32_e32 v5, v10, v21
	v_max_u32_e32 v6, v16, v22
	v_max_u32_e32 v7, v7, v23
	v_max_u32_e32 v8, v9, v24
	v_max_u32_e32 v9, v12, v25
	v_max_u32_e32 v10, v15, v26
	v_max_u32_e32 v11, v17, v27
	v_max_u32_e32 v12, v18, v28
	v_max_u32_e32 v13, v14, v29
	v_max_u32_e32 v14, v19, v30
	v_max_u32_e32 v15, v20, v31
	v_max_u32_e32 v16, v0, v8
	v_max_u32_e32 v17, v1, v9
	v_max_u32_e32 v18, v2, v10
	v_max_u32_e32 v19, v3, v11
	v_max_u32_e32 v20, v4, v12
	v_max_u32_e32 v21, v5, v13
	v_max_u32_e32 v22, v6, v14
	v_max_u32_e32 v23, v7, v15
	s_and_saveexec_b64 s[0:1], s[4:5]
	s_cbranch_execz .LBB0_59
	v_max_u32_e32 v24, v16, v20
	v_max_u32_e32 v25, v18, v22
	v_max_u32_e32 v27, v17, v21
	v_max_u32_e32 v28, v19, v23
	v_min_u32_e32 v26, v24, v25
	v_min_u32_e32 v29, v27, v28
	v_max_u32_e32 v24, v24, v25
	v_max_u32_e32 v25, v27, v28
	v_min_u32_e32 v30, v26, v29
	v_max_u32_e32 v29, v26, v29
	v_min_u32_e32 v26, v24, v25
	v_max_u32_e32 v24, v24, v25
	v_xor_b32_e32 v25, -1, v26
	v_xor_b32_e32 v24, -1, v24
	v_and_b32_e32 v25, 0x7f, v25
	v_and_b32_e32 v24, 0x7f, v24
	v_lshl_add_u32 v26, v24, 2, v169
	v_lshl_add_u32 v27, v25, 2, v169
	ds_read_b32 v26, v26 offset:17408
	ds_read_b32 v27, v27 offset:17408
	v_xor_b32_e32 v28, -1, v29
	s_waitcnt lgkmcnt(0)
	ds_write_b64 v175, v[26:27] offset:53248
	v_xor_b32_e32 v26, -1, v30
	v_and_b32_e32 v27, 0x7f, v26
	v_and_b32_e32 v26, 0x7f, v28
	v_lshl_add_u32 v28, v26, 2, v169
	ds_write_b128 v184, v[24:27] offset:61440
	v_lshl_add_u32 v24, v27, 2, v169
	ds_read_b32 v28, v28 offset:17408
	ds_read_b32 v29, v24 offset:17408
	s_waitcnt lgkmcnt(0)
	ds_write_b64 v184, v[28:29] offset:53256

; DI unsigned fkey(float f) { const unsigned u = __float_as_uint(f); return (u & 0x80000000u) ? ~u : (u | 0x80000000u); }
; DI void topk_phase(unsigned char* smem_, const bf16_t* __restrict__ qp, const bf16_t* __restrict__ keys, int* __restrict__ eidx, float* __restrict__ gate) {
;     ...
;         for (int i = 0; i < 8; ++i) {
;             const f32x4 sv4 = *(const f32x4*)(S + row * LDS_ + 32 * q + 4 * i);
;             const int ib = 127 - (32 * q + 4 * i);
;             v[4 * i] = (fkey(sv4.x) & ~127u) | (unsigned)ib; v[4 * i + 1] = (fkey(sv4.y) & ~127u) | (unsigned)(ib - 1);
;             v[4 * i + 2] = (fkey(sv4.z) & ~127u) | (unsigned)(ib - 2); v[4 * i + 3] = (fkey(sv4.w) & ~127u) | (unsigned)(ib - 3);
;         }
.LBB0_67:
	ds_read_b128 v[0:3], v171 offset:17408
	ds_read_b128 v[4:7], v171 offset:17424
	ds_read_b128 v[8:11], v171 offset:17440
	ds_read_b128 v[12:15], v171 offset:17456
	s_waitcnt lgkmcnt(3)
	v_ashrrev_i32_e32 v16, 31, v0
	v_or_b32_e32 v17, 0x80000000, v16

; DI unsigned fkey(float f) { const unsigned u = __float_as_uint(f); return (u & 0x80000000u) ? ~u : (u | 0x80000000u); }
; DI void topk_phase(unsigned char* smem_, const bf16_t* __restrict__ qp, const bf16_t* __restrict__ keys, int* __restrict__ eidx, float* __restrict__ gate) {
;     ...
;         for (int i = 0; i < 8; ++i) {
;             const f32x4 sv4 = *(const f32x4*)(S + row * LDS_ + 32 * q + 4 * i);
;             const int ib = 127 - (32 * q + 4 * i);
;             v[4 * i] = (fkey(sv4.x) & ~127u) | (unsigned)ib; v[4 * i + 1] = (fkey(sv4.y) & ~127u) | (unsigned)(ib - 1);
;             v[4 * i + 2] = (fkey(sv4.z) & ~127u) | (unsigned)(ib - 2); v[4 * i + 3] = (fkey(sv4.w) & ~127u) | (unsigned)(ib - 3);
;         }
	s_nop 1
	v_xor_b32_e32 v0, v17, v0
	v_and_b32_e32 v0, 0xffffff80, v0
	v_sub_u32_e32 v0, v0, v170
	v_add_u32_e32 v16, 0x7f, v0
	v_not_b32_e32 v0, v1
	v_or_b32_e32 v17, 0x80000000, v1
	v_cmp_gt_i32_e32 vcc, 0, v1
	v_ashrrev_i32_e32 v1, 31, v2
	s_nop 0
	v_cndmask_b32_e32 v0, v17, v0, vcc
	v_and_b32_e32 v0, 0xffffff80, v0
	v_sub_u32_e32 v0, v0, v170
	v_add_u32_e32 v17, 0x7e, v0
	v_or_b32_e32 v0, 0x80000000, v1

; DI unsigned fkey(float f) { const unsigned u = __float_as_uint(f); return (u & 0x80000000u) ? ~u : (u | 0x80000000u); }
; DI void topk_phase(unsigned char* smem_, const bf16_t* __restrict__ qp, const bf16_t* __restrict__ keys, int* __restrict__ eidx, float* __restrict__ gate) {
;     ...
;         for (int i = 0; i < 8; ++i) {
;             const f32x4 sv4 = *(const f32x4*)(S + row * LDS_ + 32 * q + 4 * i);
;             const int ib = 127 - (32 * q + 4 * i);
;             v[4 * i] = (fkey(sv4.x) & ~127u) | (unsigned)ib; v[4 * i + 1] = (fkey(sv4.y) & ~127u) | (unsigned)(ib - 1);
;             v[4 * i + 2] = (fkey(sv4.z) & ~127u) | (unsigned)(ib - 2); v[4 * i + 3] = (fkey(sv4.w) & ~127u) | (unsigned)(ib - 3);
;         }
	s_nop 1
	v_xor_b32_e32 v0, v0, v2
	v_and_b32_e32 v0, 0xffffff80, v0
	v_sub_u32_e32 v0, v0, v170
	v_add_u32_e32 v18, 0x7d, v0
	v_ashrrev_i32_e32 v0, 31, v3
	v_or_b32_e32 v1, 0x80000000, v0

; DI unsigned fkey(float f) { const unsigned u = __float_as_uint(f); return (u & 0x80000000u) ? ~u : (u | 0x80000000u); }
; DI void topk_phase(unsigned char* smem_, const bf16_t* __restrict__ qp, const bf16_t* __restrict__ keys, int* __restrict__ eidx, float* __restrict__ gate) {
;     ...
;         for (int i = 0; i < 8; ++i) {
;             const f32x4 sv4 = *(const f32x4*)(S + row * LDS_ + 32 * q + 4 * i);
;             const int ib = 127 - (32 * q + 4 * i);
;             v[4 * i] = (fkey(sv4.x) & ~127u) | (unsigned)ib; v[4 * i + 1] = (fkey(sv4.y) & ~127u) | (unsigned)(ib - 1);
;             v[4 * i + 2] = (fkey(sv4.z) & ~127u) | (unsigned)(ib - 2); v[4 * i + 3] = (fkey(sv4.w) & ~127u) | (unsigned)(ib - 3);
;         }
	s_nop 1
	v_xor_b32_e32 v0, v1, v3
	v_and_b32_e32 v0, 0xffffff80, v0
	v_sub_u32_e32 v0, v0, v170
	v_add_u32_e32 v19, 0x7c, v0
	s_waitcnt lgkmcnt(2)
	v_ashrrev_i32_e32 v0, 31, v4
	v_or_b32_e32 v1, 0x80000000, v0

; DI unsigned fkey(float f) { const unsigned u = __float_as_uint(f); return (u & 0x80000000u) ? ~u : (u | 0x80000000u); }
; DI void topk_phase(unsigned char* smem_, const bf16_t* __restrict__ qp, const bf16_t* __restrict__ keys, int* __restrict__ eidx, float* __restrict__ gate) {
;     ...
;         for (int i = 0; i < 8; ++i) {
;             const f32x4 sv4 = *(const f32x4*)(S + row * LDS_ + 32 * q + 4 * i);
;             const int ib = 127 - (32 * q + 4 * i);
;             v[4 * i] = (fkey(sv4.x) & ~127u) | (unsigned)ib; v[4 * i + 1] = (fkey(sv4.y) & ~127u) | (unsigned)(ib - 1);
;             v[4 * i + 2] = (fkey(sv4.z) & ~127u) | (unsigned)(ib - 2); v[4 * i + 3] = (fkey(sv4.w) & ~127u) | (unsigned)(ib - 3);
;         }
	s_nop 1
	v_xor_b32_e32 v0, v1, v4
	v_and_b32_e32 v0, 0xffffff80, v0
	v_sub_u32_e32 v0, v0, v177
	v_add_u32_e32 v20, 0x7f, v0
	v_ashrrev_i32_e32 v0, 31, v5
	v_or_b32_e32 v1, 0x80000000, v0

; DI unsigned fkey(float f) { const unsigned u = __float_as_uint(f); return (u & 0x80000000u) ? ~u : (u | 0x80000000u); }
; DI void topk_phase(unsigned char* smem_, const bf16_t* __restrict__ qp, const bf16_t* __restrict__ keys, int* __restrict__ eidx, float* __restrict__ gate) {
;     ...
;         for (int i = 0; i < 8; ++i) {
;             const f32x4 sv4 = *(const f32x4*)(S + row * LDS_ + 32 * q + 4 * i);
;             const int ib = 127 - (32 * q + 4 * i);
;             v[4 * i] = (fkey(sv4.x) & ~127u) | (unsigned)ib; v[4 * i + 1] = (fkey(sv4.y) & ~127u) | (unsigned)(ib - 1);
;             v[4 * i + 2] = (fkey(sv4.z) & ~127u) | (unsigned)(ib - 2); v[4 * i + 3] = (fkey(sv4.w) & ~127u) | (unsigned)(ib - 3);
;         }
	s_nop 1
	v_xor_b32_e32 v0, v1, v5
	v_and_b32_e32 v0, 0xffffff80, v0
	v_sub_u32_e32 v0, v0, v177
	v_add_u32_e32 v21, 0x7e, v0
	v_ashrrev_i32_e32 v0, 31, v6
	v_or_b32_e32 v1, 0x80000000, v0

; DI unsigned fkey(float f) { const unsigned u = __float_as_uint(f); return (u & 0x80000000u) ? ~u : (u | 0x80000000u); }
; DI void topk_phase(unsigned char* smem_, const bf16_t* __restrict__ qp, const bf16_t* __restrict__ keys, int* __restrict__ eidx, float* __restrict__ gate) {
;     ...
;         for (int i = 0; i < 8; ++i) {
;             const f32x4 sv4 = *(const f32x4*)(S + row * LDS_ + 32 * q + 4 * i);
;             const int ib = 127 - (32 * q + 4 * i);
;             v[4 * i] = (fkey(sv4.x) & ~127u) | (unsigned)ib; v[4 * i + 1] = (fkey(sv4.y) & ~127u) | (unsigned)(ib - 1);
;             v[4 * i + 2] = (fkey(sv4.z) & ~127u) | (unsigned)(ib - 2); v[4 * i + 3] = (fkey(sv4.w) & ~127u) | (unsigned)(ib - 3);
;         }
	s_nop 1
	v_xor_b32_e32 v0, v1, v6
	v_and_b32_e32 v0, 0xffffff80, v0
	v_sub_u32_e32 v0, v0, v177
	v_add_u32_e32 v22, 0x7d, v0
	v_ashrrev_i32_e32 v0, 31, v7
	v_or_b32_e32 v1, 0x80000000, v0

; DI unsigned fkey(float f) { const unsigned u = __float_as_uint(f); return (u & 0x80000000u) ? ~u : (u | 0x80000000u); }
; DI void topk_phase(unsigned char* smem_, const bf16_t* __restrict__ qp, const bf16_t* __restrict__ keys, int* __restrict__ eidx, float* __restrict__ gate) {
;     ...
;         for (int i = 0; i < 8; ++i) {
;             const f32x4 sv4 = *(const f32x4*)(S + row * LDS_ + 32 * q + 4 * i);
;             const int ib = 127 - (32 * q + 4 * i);
;             v[4 * i] = (fkey(sv4.x) & ~127u) | (unsigned)ib; v[4 * i + 1] = (fkey(sv4.y) & ~127u) | (unsigned)(ib - 1);
;             v[4 * i + 2] = (fkey(sv4.z) & ~127u) | (unsigned)(ib - 2); v[4 * i + 3] = (fkey(sv4.w) & ~127u) | (unsigned)(ib - 3);
;         }
	s_nop 1
	v_xor_b32_e32 v0, v1, v7
	v_and_b32_e32 v0, 0xffffff80, v0
	v_sub_u32_e32 v0, v0, v177
	v_add_u32_e32 v23, 0x7c, v0
	s_waitcnt lgkmcnt(1)
	v_ashrrev_i32_e32 v0, 31, v8
	v_or_b32_e32 v1, 0x80000000, v0

; DI unsigned fkey(float f) { const unsigned u = __float_as_uint(f); return (u & 0x80000000u) ? ~u : (u | 0x80000000u); }
; DI void topk_phase(unsigned char* smem_, const bf16_t* __restrict__ qp, const bf16_t* __restrict__ keys, int* __restrict__ eidx, float* __restrict__ gate) {
;     ...
;         for (int i = 0; i < 8; ++i) {
;             const f32x4 sv4 = *(const f32x4*)(S + row * LDS_ + 32 * q + 4 * i);
;             const int ib = 127 - (32 * q + 4 * i);
;             v[4 * i] = (fkey(sv4.x) & ~127u) | (unsigned)ib; v[4 * i + 1] = (fkey(sv4.y) & ~127u) | (unsigned)(ib - 1);
;             v[4 * i + 2] = (fkey(sv4.z) & ~127u) | (unsigned)(ib - 2); v[4 * i + 3] = (fkey(sv4.w) & ~127u) | (unsigned)(ib - 3);
;         }
	s_nop 1
	v_xor_b32_e32 v0, v1, v8
	v_and_b32_e32 v0, 0xffffff80, v0
	v_sub_u32_e32 v0, v0, v178
	v_add_u32_e32 v8, 0x7f, v0
	v_ashrrev_i32_e32 v0, 31, v9
	v_or_b32_e32 v1, 0x80000000, v0

; DI unsigned fkey(float f) { const unsigned u = __float_as_uint(f); return (u & 0x80000000u) ? ~u : (u | 0x80000000u); }
; DI void topk_phase(unsigned char* smem_, const bf16_t* __restrict__ qp, const bf16_t* __restrict__ keys, int* __restrict__ eidx, float* __restrict__ gate) {
;     ...
;         for (int i = 0; i < 8; ++i) {
;             const f32x4 sv4 = *(const f32x4*)(S + row * LDS_ + 32 * q + 4 * i);
;             const int ib = 127 - (32 * q + 4 * i);
;             v[4 * i] = (fkey(sv4.x) & ~127u) | (unsigned)ib; v[4 * i + 1] = (fkey(sv4.y) & ~127u) | (unsigned)(ib - 1);
;             v[4 * i + 2] = (fkey(sv4.z) & ~127u) | (unsigned)(ib - 2); v[4 * i + 3] = (fkey(sv4.w) & ~127u) | (unsigned)(ib - 3);
;         }
	s_nop 1
	v_xor_b32_e32 v0, v1, v9
	v_and_b32_e32 v0, 0xffffff80, v0
	v_sub_u32_e32 v0, v0, v178
	v_add_u32_e32 v9, 0x7e, v0
	v_ashrrev_i32_e32 v0, 31, v10
	v_or_b32_e32 v1, 0x80000000, v0

; DI unsigned fkey(float f) { const unsigned u = __float_as_uint(f); return (u & 0x80000000u) ? ~u : (u | 0x80000000u); }
; DI void topk_phase(unsigned char* smem_, const bf16_t* __restrict__ qp, const bf16_t* __restrict__ keys, int* __restrict__ eidx, float* __restrict__ gate) {
;     ...
;         for (int i = 0; i < 8; ++i) {
;             const f32x4 sv4 = *(const f32x4*)(S + row * LDS_ + 32 * q + 4 * i);
;             const int ib = 127 - (32 * q + 4 * i);
;             v[4 * i] = (fkey(sv4.x) & ~127u) | (unsigned)ib; v[4 * i + 1] = (fkey(sv4.y) & ~127u) | (unsigned)(ib - 1);
;             v[4 * i + 2] = (fkey(sv4.z) & ~127u) | (unsigned)(ib - 2); v[4 * i + 3] = (fkey(sv4.w) & ~127u) | (unsigned)(ib - 3);
;         }
	s_nop 1
	v_xor_b32_e32 v0, v1, v10
	v_and_b32_e32 v0, 0xffffff80, v0
	v_sub_u32_e32 v0, v0, v178
	v_add_u32_e32 v10, 0x7d, v0
	v_ashrrev_i32_e32 v0, 31, v11
	v_or_b32_e32 v1, 0x80000000, v0

; DI unsigned fkey(float f) { const unsigned u = __float_as_uint(f); return (u & 0x80000000u) ? ~u : (u | 0x80000000u); }
; DI void topk_phase(unsigned char* smem_, const bf16_t* __restrict__ qp, const bf16_t* __restrict__ keys, int* __restrict__ eidx, float* __restrict__ gate) {
;     ...
;         for (int i = 0; i < 8; ++i) {
;             const f32x4 sv4 = *(const f32x4*)(S + row * LDS_ + 32 * q + 4 * i);
;             const int ib = 127 - (32 * q + 4 * i);
;             v[4 * i] = (fkey(sv4.x) & ~127u) | (unsigned)ib; v[4 * i + 1] = (fkey(sv4.y) & ~127u) | (unsigned)(ib - 1);
;             v[4 * i + 2] = (fkey(sv4.z) & ~127u) | (unsigned)(ib - 2); v[4 * i + 3] = (fkey(sv4.w) & ~127u) | (unsigned)(ib - 3);
;         }
	s_nop 1
	v_xor_b32_e32 v0, v1, v11
	v_and_b32_e32 v0, 0xffffff80, v0
	v_sub_u32_e32 v0, v0, v178
	v_add_u32_e32 v11, 0x7c, v0
	s_waitcnt lgkmcnt(0)
	v_ashrrev_i32_e32 v0, 31, v12
	v_or_b32_e32 v1, 0x80000000, v0

; DI unsigned fkey(float f) { const unsigned u = __float_as_uint(f); return (u & 0x80000000u) ? ~u : (u | 0x80000000u); }
; DI void topk_phase(unsigned char* smem_, const bf16_t* __restrict__ qp, const bf16_t* __restrict__ keys, int* __restrict__ eidx, float* __restrict__ gate) {
;     ...
;         for (int i = 0; i < 8; ++i) {
;             const f32x4 sv4 = *(const f32x4*)(S + row * LDS_ + 32 * q + 4 * i);
;             const int ib = 127 - (32 * q + 4 * i);
;             v[4 * i] = (fkey(sv4.x) & ~127u) | (unsigned)ib; v[4 * i + 1] = (fkey(sv4.y) & ~127u) | (unsigned)(ib - 1);
;             v[4 * i + 2] = (fkey(sv4.z) & ~127u) | (unsigned)(ib - 2); v[4 * i + 3] = (fkey(sv4.w) & ~127u) | (unsigned)(ib - 3);
;         }
	s_nop 1
	v_xor_b32_e32 v0, v1, v12
	v_and_b32_e32 v0, 0xffffff80, v0
	v_sub_u32_e32 v0, v0, v179
	v_add_u32_e32 v12, 0x7f, v0
	v_ashrrev_i32_e32 v0, 31, v13
	v_or_b32_e32 v1, 0x80000000, v0

; DI unsigned fkey(float f) { const unsigned u = __float_as_uint(f); return (u & 0x80000000u) ? ~u : (u | 0x80000000u); }
; DI void topk_phase(unsigned char* smem_, const bf16_t* __restrict__ qp, const bf16_t* __restrict__ keys, int* __restrict__ eidx, float* __restrict__ gate) {
;     ...
;         for (int i = 0; i < 8; ++i) {
;             const f32x4 sv4 = *(const f32x4*)(S + row * LDS_ + 32 * q + 4 * i);
;             const int ib = 127 - (32 * q + 4 * i);
;             v[4 * i] = (fkey(sv4.x) & ~127u) | (unsigned)ib; v[4 * i + 1] = (fkey(sv4.y) & ~127u) | (unsigned)(ib - 1);
;             v[4 * i + 2] = (fkey(sv4.z) & ~127u) | (unsigned)(ib - 2); v[4 * i + 3] = (fkey(sv4.w) & ~127u) | (unsigned)(ib - 3);
;         }
	s_nop 1
	v_xor_b32_e32 v0, v1, v13
	v_and_b32_e32 v0, 0xffffff80, v0
	v_sub_u32_e32 v0, v0, v179
	v_add_u32_e32 v13, 0x7e, v0
	v_ashrrev_i32_e32 v0, 31, v14
	v_or_b32_e32 v1, 0x80000000, v0

; DI unsigned fkey(float f) { const unsigned u = __float_as_uint(f); return (u & 0x80000000u) ? ~u : (u | 0x80000000u); }
; DI void topk_phase(unsigned char* smem_, const bf16_t* __restrict__ qp, const bf16_t* __restrict__ keys, int* __restrict__ eidx, float* __restrict__ gate) {
;     ...
;         for (int i = 0; i < 8; ++i) {
;             const f32x4 sv4 = *(const f32x4*)(S + row * LDS_ + 32 * q + 4 * i);
;             const int ib = 127 - (32 * q + 4 * i);
;             v[4 * i] = (fkey(sv4.x) & ~127u) | (unsigned)ib; v[4 * i + 1] = (fkey(sv4.y) & ~127u) | (unsigned)(ib - 1);
;             v[4 * i + 2] = (fkey(sv4.z) & ~127u) | (unsigned)(ib - 2); v[4 * i + 3] = (fkey(sv4.w) & ~127u) | (unsigned)(ib - 3);
;         }
	s_nop 1
	v_xor_b32_e32 v0, v1, v14
	v_and_b32_e32 v0, 0xffffff80, v0
	v_sub_u32_e32 v0, v0, v179
	v_add_u32_e32 v14, 0x7d, v0
	v_ashrrev_i32_e32 v0, 31, v15
	v_or_b32_e32 v1, 0x80000000, v0

; DI unsigned fkey(float f) { const unsigned u = __float_as_uint(f); return (u & 0x80000000u) ? ~u : (u | 0x80000000u); }
; DI void topk_phase(unsigned char* smem_, const bf16_t* __restrict__ qp, const bf16_t* __restrict__ keys, int* __restrict__ eidx, float* __restrict__ gate) {
;     ...
;         for (int i = 0; i < 8; ++i) {
;             const f32x4 sv4 = *(const f32x4*)(S + row * LDS_ + 32 * q + 4 * i);
;             const int ib = 127 - (32 * q + 4 * i);
;             v[4 * i] = (fkey(sv4.x) & ~127u) | (unsigned)ib; v[4 * i + 1] = (fkey(sv4.y) & ~127u) | (unsigned)(ib - 1);
;             v[4 * i + 2] = (fkey(sv4.z) & ~127u) | (unsigned)(ib - 2); v[4 * i + 3] = (fkey(sv4.w) & ~127u) | (unsigned)(ib - 3);
;         }
	s_nop 1
	v_xor_b32_e32 v4, v1, v15
	ds_read_b128 v[0:3], v171 offset:17472
	v_and_b32_e32 v4, 0xffffff80, v4
	v_sub_u32_e32 v4, v4, v179
	v_add_u32_e32 v15, 0x7c, v4
	ds_read_b128 v[4:7], v171 offset:17488
	s_waitcnt lgkmcnt(1)
	v_ashrrev_i32_e32 v24, 31, v0
	v_or_b32_e32 v25, 0x80000000, v24

; DI unsigned fkey(float f) { const unsigned u = __float_as_uint(f); return (u & 0x80000000u) ? ~u : (u | 0x80000000u); }
; DI void topk_phase(unsigned char* smem_, const bf16_t* __restrict__ qp, const bf16_t* __restrict__ keys, int* __restrict__ eidx, float* __restrict__ gate) {
;     ...
;         for (int i = 0; i < 8; ++i) {
;             const f32x4 sv4 = *(const f32x4*)(S + row * LDS_ + 32 * q + 4 * i);
;             const int ib = 127 - (32 * q + 4 * i);
;             v[4 * i] = (fkey(sv4.x) & ~127u) | (unsigned)ib; v[4 * i + 1] = (fkey(sv4.y) & ~127u) | (unsigned)(ib - 1);
;             v[4 * i + 2] = (fkey(sv4.z) & ~127u) | (unsigned)(ib - 2); v[4 * i + 3] = (fkey(sv4.w) & ~127u) | (unsigned)(ib - 3);
;         }
	s_nop 1
	v_xor_b32_e32 v0, v25, v0
	v_and_b32_e32 v0, 0xffffff80, v0
	v_sub_u32_e32 v0, v0, v180
	v_add_u32_e32 v24, 0x7f, v0
	v_not_b32_e32 v0, v1
	v_or_b32_e32 v25, 0x80000000, v1
	v_cmp_gt_i32_e32 vcc, 0, v1
	v_ashrrev_i32_e32 v1, 31, v2
	s_nop 0
	v_cndmask_b32_e32 v0, v25, v0, vcc
	v_and_b32_e32 v0, 0xffffff80, v0
	v_sub_u32_e32 v0, v0, v180
	v_add_u32_e32 v25, 0x7e, v0
	v_or_b32_e32 v0, 0x80000000, v1

; DI unsigned fkey(float f) { const unsigned u = __float_as_uint(f); return (u & 0x80000000u) ? ~u : (u | 0x80000000u); }
; DI void topk_phase(unsigned char* smem_, const bf16_t* __restrict__ qp, const bf16_t* __restrict__ keys, int* __restrict__ eidx, float* __restrict__ gate) {
;     ...
;         for (int i = 0; i < 8; ++i) {
;             const f32x4 sv4 = *(const f32x4*)(S + row * LDS_ + 32 * q + 4 * i);
;             const int ib = 127 - (32 * q + 4 * i);
;             v[4 * i] = (fkey(sv4.x) & ~127u) | (unsigned)ib; v[4 * i + 1] = (fkey(sv4.y) & ~127u) | (unsigned)(ib - 1);
;             v[4 * i + 2] = (fkey(sv4.z) & ~127u) | (unsigned)(ib - 2); v[4 * i + 3] = (fkey(sv4.w) & ~127u) | (unsigned)(ib - 3);
;         }
	s_nop 1
	v_xor_b32_e32 v0, v0, v2
	v_and_b32_e32 v0, 0xffffff80, v0
	v_sub_u32_e32 v0, v0, v180
	v_add_u32_e32 v26, 0x7d, v0
	v_ashrrev_i32_e32 v0, 31, v3
	v_or_b32_e32 v1, 0x80000000, v0

; DI unsigned fkey(float f) { const unsigned u = __float_as_uint(f); return (u & 0x80000000u) ? ~u : (u | 0x80000000u); }
; DI void topk_phase(unsigned char* smem_, const bf16_t* __restrict__ qp, const bf16_t* __restrict__ keys, int* __restrict__ eidx, float* __restrict__ gate) {
;     ...
;         for (int i = 0; i < 8; ++i) {
;             const f32x4 sv4 = *(const f32x4*)(S + row * LDS_ + 32 * q + 4 * i);
;             const int ib = 127 - (32 * q + 4 * i);
;             v[4 * i] = (fkey(sv4.x) & ~127u) | (unsigned)ib; v[4 * i + 1] = (fkey(sv4.y) & ~127u) | (unsigned)(ib - 1);
;             v[4 * i + 2] = (fkey(sv4.z) & ~127u) | (unsigned)(ib - 2); v[4 * i + 3] = (fkey(sv4.w) & ~127u) | (unsigned)(ib - 3);
;         }
	s_nop 1
	v_xor_b32_e32 v0, v1, v3
	v_and_b32_e32 v0, 0xffffff80, v0
	v_sub_u32_e32 v0, v0, v180
	v_add_u32_e32 v27, 0x7c, v0
	s_waitcnt lgkmcnt(0)
	v_ashrrev_i32_e32 v0, 31, v4
	v_or_b32_e32 v1, 0x80000000, v0

; DI unsigned fkey(float f) { const unsigned u = __float_as_uint(f); return (u & 0x80000000u) ? ~u : (u | 0x80000000u); }
; DI void topk_phase(unsigned char* smem_, const bf16_t* __restrict__ qp, const bf16_t* __restrict__ keys, int* __restrict__ eidx, float* __restrict__ gate) {
;     ...
;         for (int i = 0; i < 8; ++i) {
;             const f32x4 sv4 = *(const f32x4*)(S + row * LDS_ + 32 * q + 4 * i);
;             const int ib = 127 - (32 * q + 4 * i);
;             v[4 * i] = (fkey(sv4.x) & ~127u) | (unsigned)ib; v[4 * i + 1] = (fkey(sv4.y) & ~127u) | (unsigned)(ib - 1);
;             v[4 * i + 2] = (fkey(sv4.z) & ~127u) | (unsigned)(ib - 2); v[4 * i + 3] = (fkey(sv4.w) & ~127u) | (unsigned)(ib - 3);
;         }
	s_nop 1
	v_xor_b32_e32 v0, v1, v4
	v_and_b32_e32 v0, 0xffffff80, v0
	v_sub_u32_e32 v0, v0, v181
	v_add_u32_e32 v28, 0x7f, v0
	v_ashrrev_i32_e32 v0, 31, v5
	v_or_b32_e32 v1, 0x80000000, v0

; DI unsigned fkey(float f) { const unsigned u = __float_as_uint(f); return (u & 0x80000000u) ? ~u : (u | 0x80000000u); }
; DI void topk_phase(unsigned char* smem_, const bf16_t* __restrict__ qp, const bf16_t* __restrict__ keys, int* __restrict__ eidx, float* __restrict__ gate) {
;     ...
;         for (int i = 0; i < 8; ++i) {
;             const f32x4 sv4 = *(const f32x4*)(S + row * LDS_ + 32 * q + 4 * i);
;             const int ib = 127 - (32 * q + 4 * i);
;             v[4 * i] = (fkey(sv4.x) & ~127u) | (unsigned)ib; v[4 * i + 1] = (fkey(sv4.y) & ~127u) | (unsigned)(ib - 1);
;             v[4 * i + 2] = (fkey(sv4.z) & ~127u) | (unsigned)(ib - 2); v[4 * i + 3] = (fkey(sv4.w) & ~127u) | (unsigned)(ib - 3);
;         }
	s_nop 1
	v_xor_b32_e32 v0, v1, v5
	v_and_b32_e32 v0, 0xffffff80, v0
	v_sub_u32_e32 v0, v0, v181
	v_add_u32_e32 v29, 0x7e, v0
	v_ashrrev_i32_e32 v0, 31, v6
	v_or_b32_e32 v1, 0x80000000, v0

; DI unsigned fkey(float f) { const unsigned u = __float_as_uint(f); return (u & 0x80000000u) ? ~u : (u | 0x80000000u); }
; DI void topk_phase(unsigned char* smem_, const bf16_t* __restrict__ qp, const bf16_t* __restrict__ keys, int* __restrict__ eidx, float* __restrict__ gate) {
;     ...
;         for (int i = 0; i < 8; ++i) {
;             const f32x4 sv4 = *(const f32x4*)(S + row * LDS_ + 32 * q + 4 * i);
;             const int ib = 127 - (32 * q + 4 * i);
;             v[4 * i] = (fkey(sv4.x) & ~127u) | (unsigned)ib; v[4 * i + 1] = (fkey(sv4.y) & ~127u) | (unsigned)(ib - 1);
;             v[4 * i + 2] = (fkey(sv4.z) & ~127u) | (unsigned)(ib - 2); v[4 * i + 3] = (fkey(sv4.w) & ~127u) | (unsigned)(ib - 3);
;         }
	s_nop 1
	v_xor_b32_e32 v0, v1, v6
	v_and_b32_e32 v0, 0xffffff80, v0
	v_sub_u32_e32 v0, v0, v181
	v_add_u32_e32 v30, 0x7d, v0
	v_ashrrev_i32_e32 v0, 31, v7
	v_or_b32_e32 v1, 0x80000000, v0

; DI unsigned fkey(float f) { const unsigned u = __float_as_uint(f); return (u & 0x80000000u) ? ~u : (u | 0x80000000u); }
; DI void topk_phase(unsigned char* smem_, const bf16_t* __restrict__ qp, const bf16_t* __restrict__ keys, int* __restrict__ eidx, float* __restrict__ gate) {
;     ...
;         for (int i = 0; i < 8; ++i) {
;             const f32x4 sv4 = *(const f32x4*)(S + row * LDS_ + 32 * q + 4 * i);
;             const int ib = 127 - (32 * q + 4 * i);
;             v[4 * i] = (fkey(sv4.x) & ~127u) | (unsigned)ib; v[4 * i + 1] = (fkey(sv4.y) & ~127u) | (unsigned)(ib - 1);
;             v[4 * i + 2] = (fkey(sv4.z) & ~127u) | (unsigned)(ib - 2); v[4 * i + 3] = (fkey(sv4.w) & ~127u) | (unsigned)(ib - 3);
;         }
	s_nop 1
	v_xor_b32_e32 v4, v1, v7
	ds_read_b128 v[0:3], v171 offset:17504
	v_and_b32_e32 v4, 0xffffff80, v4
	v_sub_u32_e32 v4, v4, v181
	v_add_u32_e32 v31, 0x7c, v4
	ds_read_b128 v[4:7], v171 offset:17520
	s_waitcnt lgkmcnt(1)
	v_ashrrev_i32_e32 v117, 31, v0
	v_or_b32_e32 v118, 0x80000000, v117

; DI unsigned fkey(float f) { const unsigned u = __float_as_uint(f); return (u & 0x80000000u) ? ~u : (u | 0x80000000u); }
; DI void topk_phase(unsigned char* smem_, const bf16_t* __restrict__ qp, const bf16_t* __restrict__ keys, int* __restrict__ eidx, float* __restrict__ gate) {
;     ...
;         for (int i = 0; i < 8; ++i) {
;             const f32x4 sv4 = *(const f32x4*)(S + row * LDS_ + 32 * q + 4 * i);
;             const int ib = 127 - (32 * q + 4 * i);
;             v[4 * i] = (fkey(sv4.x) & ~127u) | (unsigned)ib; v[4 * i + 1] = (fkey(sv4.y) & ~127u) | (unsigned)(ib - 1);
;             v[4 * i + 2] = (fkey(sv4.z) & ~127u) | (unsigned)(ib - 2); v[4 * i + 3] = (fkey(sv4.w) & ~127u) | (unsigned)(ib - 3);
;         }
	s_nop 1
	v_xor_b32_e32 v0, v118, v0
	v_ashrrev_i32_e32 v117, 31, v1
	v_or_b32_e32 v118, 0x80000000, v117

; DI unsigned fkey(float f) { const unsigned u = __float_as_uint(f); return (u & 0x80000000u) ? ~u : (u | 0x80000000u); }
; DI void topk_phase(unsigned char* smem_, const bf16_t* __restrict__ qp, const bf16_t* __restrict__ keys, int* __restrict__ eidx, float* __restrict__ gate) {
;     ...
;         for (int i = 0; i < 8; ++i) {
;             const f32x4 sv4 = *(const f32x4*)(S + row * LDS_ + 32 * q + 4 * i);
;             const int ib = 127 - (32 * q + 4 * i);
;             v[4 * i] = (fkey(sv4.x) & ~127u) | (unsigned)ib; v[4 * i + 1] = (fkey(sv4.y) & ~127u) | (unsigned)(ib - 1);
;             v[4 * i + 2] = (fkey(sv4.z) & ~127u) | (unsigned)(ib - 2); v[4 * i + 3] = (fkey(sv4.w) & ~127u) | (unsigned)(ib - 3);
;         }
	v_and_b32_e32 v0, 0xffffff80, v0
	v_sub_u32_e32 v0, v0, v182
	v_xor_b32_e32 v1, v118, v1
	v_ashrrev_i32_e32 v117, 31, v2
	v_or_b32_e32 v118, 0x80000000, v117

; DI unsigned fkey(float f) { const unsigned u = __float_as_uint(f); return (u & 0x80000000u) ? ~u : (u | 0x80000000u); }
; DI void topk_phase(unsigned char* smem_, const bf16_t* __restrict__ qp, const bf16_t* __restrict__ keys, int* __restrict__ eidx, float* __restrict__ gate) {
;     ...
;         for (int i = 0; i < 8; ++i) {
;             const f32x4 sv4 = *(const f32x4*)(S + row * LDS_ + 32 * q + 4 * i);
;             const int ib = 127 - (32 * q + 4 * i);
;             v[4 * i] = (fkey(sv4.x) & ~127u) | (unsigned)ib; v[4 * i + 1] = (fkey(sv4.y) & ~127u) | (unsigned)(ib - 1);
;             v[4 * i + 2] = (fkey(sv4.z) & ~127u) | (unsigned)(ib - 2); v[4 * i + 3] = (fkey(sv4.w) & ~127u) | (unsigned)(ib - 3);
;         }
	v_and_b32_e32 v1, 0xffffff80, v1
	v_sub_u32_e32 v1, v1, v182
	v_xor_b32_e32 v2, v118, v2
	v_ashrrev_i32_e32 v117, 31, v3
	v_or_b32_e32 v118, 0x80000000, v117

; DI unsigned fkey(float f) { const unsigned u = __float_as_uint(f); return (u & 0x80000000u) ? ~u : (u | 0x80000000u); }
; DI void topk_phase(unsigned char* smem_, const bf16_t* __restrict__ qp, const bf16_t* __restrict__ keys, int* __restrict__ eidx, float* __restrict__ gate) {
;     ...
;         for (int i = 0; i < 8; ++i) {
;             const f32x4 sv4 = *(const f32x4*)(S + row * LDS_ + 32 * q + 4 * i);
;             const int ib = 127 - (32 * q + 4 * i);
;             v[4 * i] = (fkey(sv4.x) & ~127u) | (unsigned)ib; v[4 * i + 1] = (fkey(sv4.y) & ~127u) | (unsigned)(ib - 1);
;             v[4 * i + 2] = (fkey(sv4.z) & ~127u) | (unsigned)(ib - 2); v[4 * i + 3] = (fkey(sv4.w) & ~127u) | (unsigned)(ib - 3);
;         }
	v_and_b32_e32 v2, 0xffffff80, v2
	v_sub_u32_e32 v2, v2, v182
	v_xor_b32_e32 v3, v118, v3
	s_waitcnt lgkmcnt(0)
	v_ashrrev_i32_e32 v117, 31, v4
	v_or_b32_e32 v118, 0x80000000, v117

; DI unsigned fkey(float f) { const unsigned u = __float_as_uint(f); return (u & 0x80000000u) ? ~u : (u | 0x80000000u); }
; DI void topk_phase(unsigned char* smem_, const bf16_t* __restrict__ qp, const bf16_t* __restrict__ keys, int* __restrict__ eidx, float* __restrict__ gate) {
;     ...
;         for (int i = 0; i < 8; ++i) {
;             const f32x4 sv4 = *(const f32x4*)(S + row * LDS_ + 32 * q + 4 * i);
;             const int ib = 127 - (32 * q + 4 * i);
;             v[4 * i] = (fkey(sv4.x) & ~127u) | (unsigned)ib; v[4 * i + 1] = (fkey(sv4.y) & ~127u) | (unsigned)(ib - 1);
;             v[4 * i + 2] = (fkey(sv4.z) & ~127u) | (unsigned)(ib - 2); v[4 * i + 3] = (fkey(sv4.w) & ~127u) | (unsigned)(ib - 3);
;         }
	v_and_b32_e32 v3, 0xffffff80, v3
	v_sub_u32_e32 v3, v3, v182
	v_xor_b32_e32 v4, v118, v4
	v_ashrrev_i32_e32 v117, 31, v5
	v_or_b32_e32 v118, 0x80000000, v117

; DI unsigned fkey(float f) { const unsigned u = __float_as_uint(f); return (u & 0x80000000u) ? ~u : (u | 0x80000000u); }
; DI void topk_phase(unsigned char* smem_, const bf16_t* __restrict__ qp, const bf16_t* __restrict__ keys, int* __restrict__ eidx, float* __restrict__ gate) {
;     ...
;         for (int i = 0; i < 8; ++i) {
;             const f32x4 sv4 = *(const f32x4*)(S + row * LDS_ + 32 * q + 4 * i);
;             const int ib = 127 - (32 * q + 4 * i);
;             v[4 * i] = (fkey(sv4.x) & ~127u) | (unsigned)ib; v[4 * i + 1] = (fkey(sv4.y) & ~127u) | (unsigned)(ib - 1);
;             v[4 * i + 2] = (fkey(sv4.z) & ~127u) | (unsigned)(ib - 2); v[4 * i + 3] = (fkey(sv4.w) & ~127u) | (unsigned)(ib - 3);
;         }
	v_and_b32_e32 v4, 0xffffff80, v4
	v_sub_u32_e32 v4, v4, v183
	v_xor_b32_e32 v5, v118, v5
	v_ashrrev_i32_e32 v117, 31, v6
	v_or_b32_e32 v118, 0x80000000, v117

; DI unsigned fkey(float f) { const unsigned u = __float_as_uint(f); return (u & 0x80000000u) ? ~u : (u | 0x80000000u); }
; DI void topk_phase(unsigned char* smem_, const bf16_t* __restrict__ qp, const bf16_t* __restrict__ keys, int* __restrict__ eidx, float* __restrict__ gate) {
;     ...
;         for (int i = 0; i < 8; ++i) {
;             const f32x4 sv4 = *(const f32x4*)(S + row * LDS_ + 32 * q + 4 * i);
;             const int ib = 127 - (32 * q + 4 * i);
;             v[4 * i] = (fkey(sv4.x) & ~127u) | (unsigned)ib; v[4 * i + 1] = (fkey(sv4.y) & ~127u) | (unsigned)(ib - 1);
;             v[4 * i + 2] = (fkey(sv4.z) & ~127u) | (unsigned)(ib - 2); v[4 * i + 3] = (fkey(sv4.w) & ~127u) | (unsigned)(ib - 3);
;         }
	v_and_b32_e32 v5, 0xffffff80, v5
	v_sub_u32_e32 v5, v5, v183
	v_xor_b32_e32 v6, v118, v6
	v_ashrrev_i32_e32 v117, 31, v7
	v_or_b32_e32 v118, 0x80000000, v117

; DI unsigned fkey(float f) { const unsigned u = __float_as_uint(f); return (u & 0x80000000u) ? ~u : (u | 0x80000000u); }
; template <int N> DI void bitonic_sort_desc(unsigned (&v)[N]) {
; #pragma unroll
;     for (int k = 2; k <= N; k <<= 1)
; #pragma unroll
;         for (int j = k >> 1; j > 0; j >>= 1)
; #pragma unroll
;             for (int i = 0; i < N; ++i) { const int l = i ^ j; if (l > i) { if ((i & k) == 0) cswap(v[i], v[l]); else cswap(v[l], v[i]); } }
; DI void topk_phase(unsigned char* smem_, const bf16_t* __restrict__ qp, const bf16_t* __restrict__ keys, int* __restrict__ eidx, float* __restrict__ gate) {
;     ...
;         for (int i = 0; i < 8; ++i) {
;             const f32x4 sv4 = *(const f32x4*)(S + row * LDS_ + 32 * q + 4 * i);
;             const int ib = 127 - (32 * q + 4 * i);
;             v[4 * i] = (fkey(sv4.x) & ~127u) | (unsigned)ib; v[4 * i + 1] = (fkey(sv4.y) & ~127u) | (unsigned)(ib - 1);
;             v[4 * i + 2] = (fkey(sv4.z) & ~127u) | (unsigned)(ib - 2); v[4 * i + 3] = (fkey(sv4.w) & ~127u) | (unsigned)(ib - 3);
;         }
;         bitonic_sort_desc<32>(v);
	v_and_b32_e32 v6, 0xffffff80, v6
	v_sub_u32_e32 v6, v6, v183
	v_xor_b32_e32 v7, v118, v7
	v_and_b32_e32 v7, 0xffffff80, v7
	v_sub_u32_e32 v7, v7, v183
	v_add_u32_e32 v0, 0x7f, v0
	v_add_u32_e32 v1, 0x7e, v1
	v_add_u32_e32 v2, 0x7d, v2
	v_add_u32_e32 v3, 0x7c, v3
	v_add_u32_e32 v4, 0x7f, v4
	v_add_u32_e32 v5, 0x7e, v5
	v_add_u32_e32 v6, 0x7d, v6
	v_add_u32_e32 v7, 0x7c, v7
	v_max_u32_e32 v117, v16, v17
	v_min_u32_e32 v16, v16, v17
	v_max_u32_e32 v17, v19, v18
	v_min_u32_e32 v18, v19, v18
	v_max_u32_e32 v19, v20, v21
	v_min_u32_e32 v20, v20, v21
	v_max_u32_e32 v21, v23, v22
	v_min_u32_e32 v22, v23, v22
	v_max_u32_e32 v23, v8, v9
	v_min_u32_e32 v8, v8, v9
	v_max_u32_e32 v9, v11, v10
	v_min_u32_e32 v10, v11, v10
	v_max_u32_e32 v11, v12, v13
	v_min_u32_e32 v12, v12, v13
	v_max_u32_e32 v13, v15, v14
	v_min_u32_e32 v14, v15, v14
	v_max_u32_e32 v15, v24, v25
	v_min_u32_e32 v24, v24, v25
	v_max_u32_e32 v25, v27, v26
	v_min_u32_e32 v26, v27, v26
	v_max_u32_e32 v27, v28, v29
	v_min_u32_e32 v28, v28, v29
	v_max_u32_e32 v29, v31, v30
	v_min_u32_e32 v30, v31, v30
	v_max_u32_e32 v31, v0, v1
	v_min_u32_e32 v0, v0, v1
	v_max_u32_e32 v1, v3, v2
	v_min_u32_e32 v2, v3, v2
	v_max_u32_e32 v3, v4, v5
	v_min_u32_e32 v4, v4, v5
	v_max_u32_e32 v5, v7, v6
	v_min_u32_e32 v6, v7, v6
	v_max_u32_e32 v7, v117, v18
	v_min_u32_e32 v18, v117, v18
	v_max_u32_e32 v117, v16, v17
	v_min_u32_e32 v16, v16, v17
	v_max_u32_e32 v17, v22, v19
	v_min_u32_e32 v19, v22, v19
	v_max_u32_e32 v22, v21, v20
	v_min_u32_e32 v20, v21, v20
	v_max_u32_e32 v21, v23, v10
	v_min_u32_e32 v10, v23, v10
	v_max_u32_e32 v23, v8, v9
	v_min_u32_e32 v8, v8, v9
	v_max_u32_e32 v9, v14, v11
	v_min_u32_e32 v11, v14, v11
	v_max_u32_e32 v14, v13, v12
	v_min_u32_e32 v12, v13, v12
	v_max_u32_e32 v13, v15, v26
	v_min_u32_e32 v15, v15, v26
	v_max_u32_e32 v26, v24, v25
	v_min_u32_e32 v24, v24, v25
	v_max_u32_e32 v25, v30, v27
	v_min_u32_e32 v27, v30, v27
	v_max_u32_e32 v30, v29, v28
	v_min_u32_e32 v28, v29, v28
	v_max_u32_e32 v29, v31, v2
	v_min_u32_e32 v2, v31, v2
	v_max_u32_e32 v31, v0, v1
	v_min_u32_e32 v0, v0, v1
	v_max_u32_e32 v1, v6, v3
	v_min_u32_e32 v3, v6, v3
	v_max_u32_e32 v6, v5, v4
	v_min_u32_e32 v4, v5, v4
	v_max_u32_e32 v5, v7, v117
	v_min_u32_e32 v7, v7, v117
	v_max_u32_e32 v117, v18, v16
	v_min_u32_e32 v16, v18, v16
	v_max_u32_e32 v18, v20, v19
	v_min_u32_e32 v19, v20, v19
	v_max_u32_e32 v20, v22, v17
	v_min_u32_e32 v17, v22, v17
	v_max_u32_e32 v22, v21, v23
	v_min_u32_e32 v21, v21, v23
	v_max_u32_e32 v23, v10, v8
	v_min_u32_e32 v8, v10, v8
	v_max_u32_e32 v10, v12, v11
	v_min_u32_e32 v11, v12, v11
	v_max_u32_e32 v12, v14, v9
	v_min_u32_e32 v9, v14, v9
	v_max_u32_e32 v14, v13, v26
	v_min_u32_e32 v13, v13, v26
	v_max_u32_e32 v26, v15, v24
	v_min_u32_e32 v15, v15, v24
	v_max_u32_e32 v24, v28, v27
	v_min_u32_e32 v27, v28, v27
	v_max_u32_e32 v28, v30, v25
	v_min_u32_e32 v25, v30, v25
	v_max_u32_e32 v30, v29, v31
	v_min_u32_e32 v29, v29, v31
	v_max_u32_e32 v31, v2, v0
	v_min_u32_e32 v0, v2, v0
	v_max_u32_e32 v2, v4, v3
	v_min_u32_e32 v3, v4, v3
	v_max_u32_e32 v4, v6, v1
	v_min_u32_e32 v1, v6, v1
	v_max_u32_e32 v6, v5, v19
	v_min_u32_e32 v5, v5, v19
	v_max_u32_e32 v19, v7, v18
	v_min_u32_e32 v7, v7, v18
	v_max_u32_e32 v18, v117, v17
	v_min_u32_e32 v17, v117, v17
	v_max_u32_e32 v117, v16, v20
	v_min_u32_e32 v16, v16, v20
	v_max_u32_e32 v20, v11, v22
	v_min_u32_e32 v11, v11, v22
	v_max_u32_e32 v22, v10, v21
	v_min_u32_e32 v10, v10, v21
	v_max_u32_e32 v21, v9, v23
	v_min_u32_e32 v9, v9, v23
	v_max_u32_e32 v23, v12, v8
	v_min_u32_e32 v8, v12, v8
	v_max_u32_e32 v12, v14, v27
	v_min_u32_e32 v14, v14, v27
	v_max_u32_e32 v27, v13, v24
	v_min_u32_e32 v13, v13, v24
	v_max_u32_e32 v24, v26, v25
	v_min_u32_e32 v25, v26, v25
	v_max_u32_e32 v26, v15, v28
	v_min_u32_e32 v15, v15, v28
	v_max_u32_e32 v28, v3, v30
	v_min_u32_e32 v3, v3, v30
	v_max_u32_e32 v30, v2, v29
	v_min_u32_e32 v2, v2, v29
	v_max_u32_e32 v29, v1, v31
	v_min_u32_e32 v1, v1, v31
	v_max_u32_e32 v31, v4, v0
	v_min_u32_e32 v0, v4, v0
	v_max_u32_e32 v4, v6, v18
	v_min_u32_e32 v6, v6, v18
	v_max_u32_e32 v18, v19, v117
	v_min_u32_e32 v19, v19, v117
	v_max_u32_e32 v117, v5, v17
	v_min_u32_e32 v5, v5, v17
	v_max_u32_e32 v17, v7, v16
	v_min_u32_e32 v7, v7, v16
	v_max_u32_e32 v16, v9, v11
	v_min_u32_e32 v9, v9, v11
	v_max_u32_e32 v11, v8, v10
	v_min_u32_e32 v8, v8, v10
	v_max_u32_e32 v10, v21, v20
	v_min_u32_e32 v20, v21, v20
	v_max_u32_e32 v21, v23, v22
	v_min_u32_e32 v22, v23, v22
	v_max_u32_e32 v23, v12, v24
	v_min_u32_e32 v12, v12, v24
	v_max_u32_e32 v24, v27, v26
	v_min_u32_e32 v26, v27, v26
	v_max_u32_e32 v27, v14, v25
	v_min_u32_e32 v14, v14, v25
	v_max_u32_e32 v25, v13, v15
	v_min_u32_e32 v13, v13, v15
	v_max_u32_e32 v15, v1, v3
	v_min_u32_e32 v1, v1, v3
	v_max_u32_e32 v3, v0, v2
	v_min_u32_e32 v0, v0, v2
	v_max_u32_e32 v2, v29, v28
	v_min_u32_e32 v28, v29, v28
	v_max_u32_e32 v29, v31, v30
	v_min_u32_e32 v30, v31, v30
	v_max_u32_e32 v31, v4, v18
	v_min_u32_e32 v4, v4, v18
	v_max_u32_e32 v18, v6, v19
	v_min_u32_e32 v6, v6, v19
	v_max_u32_e32 v19, v117, v17
	v_min_u32_e32 v17, v117, v17
	v_max_u32_e32 v117, v5, v7
	v_min_u32_e32 v5, v5, v7
	v_max_u32_e32 v7, v8, v9
	v_min_u32_e32 v8, v8, v9
	v_max_u32_e32 v9, v11, v16
	v_min_u32_e32 v11, v11, v16
	v_max_u32_e32 v16, v22, v20
	v_min_u32_e32 v20, v22, v20
	v_max_u32_e32 v22, v21, v10
	v_min_u32_e32 v10, v21, v10
	v_max_u32_e32 v21, v23, v24
	v_min_u32_e32 v23, v23, v24
	v_max_u32_e32 v24, v12, v26
	v_min_u32_e32 v12, v12, v26
	v_max_u32_e32 v26, v27, v25
	v_min_u32_e32 v25, v27, v25
	v_max_u32_e32 v27, v14, v13
	v_min_u32_e32 v13, v14, v13
	v_max_u32_e32 v14, v0, v1
	v_min_u32_e32 v0, v0, v1
	v_max_u32_e32 v1, v3, v15
; template <int N> DI void bitonic_sort_desc(unsigned (&v)[N]) {
; #pragma unroll
;     for (int k = 2; k <= N; k <<= 1)
; #pragma unroll
;         for (int j = k >> 1; j > 0; j >>= 1)
; #pragma unroll
;             for (int i = 0; i < N; ++i) { const int l = i ^ j; if (l > i) { if ((i & k) == 0) cswap(v[i], v[l]); else cswap(v[l], v[i]); } }
; }
; DI void merge_top16(unsigned (&v)[16], int st) {
;     unsigned x[16];
; #pragma unroll
;     for (int i = 0; i < 16; ++i) x[i] = (unsigned)__shfl_xor((int)v[15 - i], st);
; #pragma unroll
;     for (int i = 0; i < 16; ++i) v[i] = max(v[i], x[i]);
; #pragma unroll
;     for (int j = 8; j > 0; j >>= 1)
; #pragma unroll
;         for (int i = 0; i < 16; ++i) { const int l = i ^ j; if (l > i) cswap(v[i], v[l]); }
; }
; DI void topk_phase(unsigned char* smem_, const bf16_t* __restrict__ qp, const bf16_t* __restrict__ keys, int* __restrict__ eidx, float* __restrict__ gate) {
;     ...
;         bitonic_sort_desc<32>(v);
;         unsigned t16[16];
; #pragma unroll
;         for (int i = 0; i < 16; ++i) t16[i] = v[i];
;         merge_top16(t16, 1);
	v_min_u32_e32 v3, v3, v15
	v_max_u32_e32 v15, v30, v28
	v_min_u32_e32 v28, v30, v28
	v_max_u32_e32 v30, v29, v2
	v_min_u32_e32 v2, v29, v2
	v_max_u32_e32 v29, v31, v8
	v_min_u32_e32 v8, v31, v8
	v_max_u32_e32 v31, v4, v7
	v_min_u32_e32 v4, v4, v7
	v_max_u32_e32 v7, v18, v11
	v_min_u32_e32 v11, v18, v11
	v_max_u32_e32 v18, v6, v9
	v_min_u32_e32 v6, v6, v9
	v_max_u32_e32 v9, v19, v20
	v_min_u32_e32 v19, v19, v20
	v_max_u32_e32 v20, v17, v16
	v_min_u32_e32 v16, v17, v16
	v_max_u32_e32 v17, v117, v10
	v_min_u32_e32 v10, v117, v10
	v_max_u32_e32 v117, v5, v22
	v_min_u32_e32 v5, v5, v22
	v_max_u32_e32 v22, v0, v21
	v_min_u32_e32 v0, v0, v21
	v_max_u32_e32 v21, v14, v23
	v_min_u32_e32 v14, v14, v23
	v_max_u32_e32 v23, v3, v24
	v_min_u32_e32 v3, v3, v24
	v_max_u32_e32 v24, v1, v12
	v_min_u32_e32 v1, v1, v12
	v_max_u32_e32 v12, v28, v26
	v_min_u32_e32 v26, v28, v26
	v_max_u32_e32 v28, v15, v25
	v_min_u32_e32 v15, v15, v25
	v_max_u32_e32 v25, v2, v27
	v_min_u32_e32 v2, v2, v27
	v_max_u32_e32 v27, v30, v13
	v_min_u32_e32 v13, v30, v13
	v_max_u32_e32 v30, v29, v9
	v_min_u32_e32 v9, v29, v9
	v_max_u32_e32 v29, v31, v20
	v_min_u32_e32 v20, v31, v20
	v_max_u32_e32 v31, v7, v17
	v_min_u32_e32 v7, v7, v17
	v_max_u32_e32 v17, v18, v117
	v_min_u32_e32 v18, v18, v117
	v_max_u32_e32 v117, v8, v19
	v_min_u32_e32 v8, v8, v19
	v_max_u32_e32 v19, v4, v16
	v_min_u32_e32 v4, v4, v16
	v_max_u32_e32 v16, v11, v10
	v_min_u32_e32 v10, v11, v10
	v_max_u32_e32 v11, v6, v5
	v_min_u32_e32 v5, v6, v5
	v_max_u32_e32 v6, v26, v0
	v_min_u32_e32 v0, v26, v0
	v_max_u32_e32 v26, v15, v14
	v_min_u32_e32 v14, v15, v14
	v_max_u32_e32 v15, v2, v3
	v_min_u32_e32 v2, v2, v3
	v_max_u32_e32 v3, v13, v1
	v_min_u32_e32 v1, v13, v1
	v_max_u32_e32 v13, v12, v22
	v_min_u32_e32 v12, v12, v22
	v_max_u32_e32 v22, v28, v21
	v_min_u32_e32 v21, v28, v21
	v_max_u32_e32 v28, v25, v23
	v_min_u32_e32 v23, v25, v23
	v_max_u32_e32 v25, v27, v24
	v_min_u32_e32 v24, v27, v24
	v_max_u32_e32 v27, v30, v31
	v_min_u32_e32 v30, v30, v31
	v_max_u32_e32 v31, v29, v17
	v_min_u32_e32 v17, v29, v17
	v_max_u32_e32 v29, v9, v7
	v_min_u32_e32 v7, v9, v7
	v_max_u32_e32 v9, v20, v18
	v_min_u32_e32 v18, v20, v18
	v_max_u32_e32 v20, v117, v16
	v_min_u32_e32 v16, v117, v16
	v_max_u32_e32 v117, v19, v11
	v_min_u32_e32 v11, v19, v11
	v_max_u32_e32 v19, v8, v10
	v_min_u32_e32 v8, v8, v10
	v_max_u32_e32 v10, v4, v5
	v_min_u32_e32 v4, v4, v5
	v_max_u32_e32 v5, v2, v0
	v_min_u32_e32 v0, v2, v0
	v_max_u32_e32 v2, v1, v14
	v_min_u32_e32 v1, v1, v14
	v_max_u32_e32 v14, v15, v6
	v_min_u32_e32 v6, v15, v6
	v_max_u32_e32 v15, v3, v26
	v_min_u32_e32 v3, v3, v26
	v_max_u32_e32 v26, v23, v12
	v_min_u32_e32 v12, v23, v12
	v_max_u32_e32 v23, v24, v21
	v_min_u32_e32 v21, v24, v21
	v_max_u32_e32 v24, v28, v13
	v_min_u32_e32 v13, v28, v13
	v_max_u32_e32 v28, v25, v22
	v_min_u32_e32 v22, v25, v22
	v_min_u32_e32 v25, v27, v31
	v_min_u32_e32 v118, v30, v17
	v_min_u32_e32 v119, v29, v9
	v_min_u32_e32 v120, v7, v18
	v_min_u32_e32 v121, v20, v117
	v_min_u32_e32 v122, v16, v11
	v_min_u32_e32 v123, v19, v10
	v_min_u32_e32 v124, v8, v4
	v_min_u32_e32 v125, v1, v0
	v_min_u32_e32 v126, v2, v5
	v_min_u32_e32 v127, v3, v6
	v_min_u32_e32 v142, v15, v14
	v_min_u32_e32 v143, v21, v12
	v_min_u32_e32 v144, v23, v26
	v_min_u32_e32 v145, v22, v13
	v_min_u32_e32 v146, v28, v24
	v_max3_u32 v27, v27, v31, v125
	v_max3_u32 v0, v25, v1, v0
	v_max3_u32 v1, v30, v17, v126
	v_max3_u32 v2, v118, v2, v5
	v_max3_u32 v5, v29, v9, v127
	v_max3_u32 v3, v119, v3, v6
	v_max3_u32 v6, v7, v18, v142
	v_max3_u32 v7, v120, v15, v14
	v_max3_u32 v9, v20, v117, v143
	v_max3_u32 v12, v121, v21, v12
	v_max3_u32 v11, v16, v11, v144
	v_max3_u32 v14, v122, v23, v26
	v_max3_u32 v10, v19, v10, v145
	v_max3_u32 v13, v123, v22, v13
	v_max3_u32 v4, v8, v4, v146
	v_max3_u32 v8, v124, v28, v24
	v_max_u32_e32 v15, v27, v9
	v_min_u32_e32 v9, v27, v9
	v_max_u32_e32 v16, v0, v12
	v_min_u32_e32 v0, v0, v12
	v_max_u32_e32 v12, v1, v11
	v_min_u32_e32 v1, v1, v11
	v_max_u32_e32 v11, v2, v14
	v_min_u32_e32 v2, v2, v14
	v_max_u32_e32 v14, v5, v10
	v_min_u32_e32 v5, v5, v10
	v_max_u32_e32 v10, v3, v13
	v_min_u32_e32 v3, v3, v13
	v_max_u32_e32 v13, v6, v4
	v_min_u32_e32 v4, v6, v4
	v_max_u32_e32 v6, v7, v8
	v_min_u32_e32 v7, v7, v8
	v_max_u32_e32 v8, v15, v14
	v_min_u32_e32 v14, v15, v14
	v_max_u32_e32 v15, v16, v10
	v_min_u32_e32 v10, v16, v10
	v_max_u32_e32 v16, v12, v13
	v_min_u32_e32 v12, v12, v13
	v_max_u32_e32 v13, v11, v6
	v_min_u32_e32 v6, v11, v6
	v_max_u32_e32 v11, v9, v5
	v_min_u32_e32 v5, v9, v5
	v_max_u32_e32 v9, v0, v3
	v_min_u32_e32 v0, v0, v3
	v_max_u32_e32 v3, v1, v4
	v_min_u32_e32 v1, v1, v4
	v_max_u32_e32 v4, v2, v7
	v_min_u32_e32 v2, v2, v7
	v_max_u32_e32 v7, v8, v16
	v_min_u32_e32 v8, v8, v16
	v_max_u32_e32 v16, v15, v13
	v_min_u32_e32 v13, v15, v13
	v_max_u32_e32 v15, v14, v12
	v_min_u32_e32 v12, v14, v12
	v_max_u32_e32 v14, v10, v6
	v_min_u32_e32 v6, v10, v6
	v_max_u32_e32 v10, v11, v3
	v_min_u32_e32 v3, v11, v3
	v_max_u32_e32 v11, v9, v4
	v_min_u32_e32 v4, v9, v4
	v_max_u32_e32 v9, v5, v1
	v_min_u32_e32 v1, v5, v1
	v_max_u32_e32 v5, v0, v2
	v_min_u32_e32 v0, v0, v2
	v_max_u32_e32 v2, v7, v16
	v_min_u32_e32 v7, v7, v16
	v_max_u32_e32 v16, v8, v13
	v_min_u32_e32 v8, v8, v13
	v_max_u32_e32 v13, v15, v14
	v_min_u32_e32 v14, v15, v14
	v_max_u32_e32 v15, v12, v6
	v_min_u32_e32 v6, v12, v6
	v_max_u32_e32 v12, v10, v11
	v_min_u32_e32 v10, v10, v11
	v_max_u32_e32 v11, v3, v4
	v_min_u32_e32 v3, v3, v4
	v_max_u32_e32 v4, v9, v5
	v_min_u32_e32 v5, v9, v5
	v_max_u32_e32 v9, v1, v0
	v_min_u32_e32 v0, v1, v0
	s_nop 1
	v_mov_b32_dpp v1, v0 quad_perm:[1,0,3,2] row_mask:0xf bank_mask:0xf
	v_mov_b32_dpp v17, v9 quad_perm:[1,0,3,2] row_mask:0xf bank_mask:0xf
	v_mov_b32_dpp v18, v5 quad_perm:[1,0,3,2] row_mask:0xf bank_mask:0xf
	v_mov_b32_dpp v19, v4 quad_perm:[1,0,3,2] row_mask:0xf bank_mask:0xf
	v_mov_b32_dpp v20, v3 quad_perm:[1,0,3,2] row_mask:0xf bank_mask:0xf
	v_mov_b32_dpp v21, v11 quad_perm:[1,0,3,2] row_mask:0xf bank_mask:0xf
	v_mov_b32_dpp v22, v10 quad_perm:[1,0,3,2] row_mask:0xf bank_mask:0xf
	v_mov_b32_dpp v23, v12 quad_perm:[1,0,3,2] row_mask:0xf bank_mask:0xf
	v_mov_b32_dpp v24, v6 quad_perm:[1,0,3,2] row_mask:0xf bank_mask:0xf
	v_mov_b32_dpp v25, v15 quad_perm:[1,0,3,2] row_mask:0xf bank_mask:0xf
	v_mov_b32_dpp v26, v14 quad_perm:[1,0,3,2] row_mask:0xf bank_mask:0xf
	v_mov_b32_dpp v27, v13 quad_perm:[1,0,3,2] row_mask:0xf bank_mask:0xf
	v_mov_b32_dpp v28, v8 quad_perm:[1,0,3,2] row_mask:0xf bank_mask:0xf
	v_mov_b32_dpp v29, v16 quad_perm:[1,0,3,2] row_mask:0xf bank_mask:0xf
	v_mov_b32_dpp v30, v7 quad_perm:[1,0,3,2] row_mask:0xf bank_mask:0xf
	v_mov_b32_dpp v31, v2 quad_perm:[1,0,3,2] row_mask:0xf bank_mask:0xf
	s_waitcnt lgkmcnt(0)
; DI void merge_top16(unsigned (&v)[16], int st) {
;     unsigned x[16];
; #pragma unroll
;     for (int i = 0; i < 16; ++i) x[i] = (unsigned)__shfl_xor((int)v[15 - i], st);
; #pragma unroll
;     for (int i = 0; i < 16; ++i) v[i] = max(v[i], x[i]);
; #pragma unroll
;     for (int j = 8; j > 0; j >>= 1)
; #pragma unroll
;         for (int i = 0; i < 16; ++i) { const int l = i ^ j; if (l > i) cswap(v[i], v[l]); }
; }
; DI void topk_phase(unsigned char* smem_, const bf16_t* __restrict__ qp, const bf16_t* __restrict__ keys, int* __restrict__ eidx, float* __restrict__ gate) {
;     ...
;         merge_top16(t16, 1);
;         merge_top16(t16, 2);
; #pragma unroll
;         for (int i = 0; i < 16; ++i) if ((i >> 2) == q) { const int idx = 127 - (int)(t16[i] & 127u); SI[row * 32 + 16 * p + i] = idx; SV[row * 32 + 16 * p + i] = S[row * LDS_ + idx]; }
	v_max_u32_e32 v1, v2, v1
	v_max_u32_e32 v2, v7, v17
	v_max_u32_e32 v7, v16, v18
	v_max_u32_e32 v8, v8, v19
	v_max_u32_e32 v13, v13, v20
	v_max_u32_e32 v14, v14, v21
	v_max_u32_e32 v15, v15, v22
	v_max_u32_e32 v6, v6, v23
	v_max_u32_e32 v12, v12, v24
	v_max_u32_e32 v10, v10, v25
	v_max_u32_e32 v11, v11, v26
	v_max_u32_e32 v3, v3, v27
	v_max_u32_e32 v4, v4, v28
	v_max_u32_e32 v5, v5, v29
	v_max_u32_e32 v9, v9, v30
	v_max_u32_e32 v0, v0, v31
	v_max_u32_e32 v16, v1, v12
	v_min_u32_e32 v1, v1, v12
	v_max_u32_e32 v12, v2, v10
	v_min_u32_e32 v2, v2, v10
	v_max_u32_e32 v10, v7, v11
	v_min_u32_e32 v7, v7, v11
	v_max_u32_e32 v11, v8, v3
	v_min_u32_e32 v3, v8, v3
	v_max_u32_e32 v8, v13, v4
	v_min_u32_e32 v4, v13, v4
	v_max_u32_e32 v13, v14, v5
	v_min_u32_e32 v5, v14, v5
	v_max_u32_e32 v14, v15, v9
	v_min_u32_e32 v9, v15, v9
	v_max_u32_e32 v15, v6, v0
	v_min_u32_e32 v0, v6, v0
	v_max_u32_e32 v6, v16, v8
	v_min_u32_e32 v8, v16, v8
	v_max_u32_e32 v16, v12, v13
	v_min_u32_e32 v12, v12, v13
	v_max_u32_e32 v13, v10, v14
	v_min_u32_e32 v10, v10, v14
	v_max_u32_e32 v14, v11, v15
	v_min_u32_e32 v11, v11, v15
	v_max_u32_e32 v15, v1, v4
	v_min_u32_e32 v1, v1, v4
	v_max_u32_e32 v4, v2, v5
	v_min_u32_e32 v2, v2, v5
	v_max_u32_e32 v5, v7, v9
	v_min_u32_e32 v7, v7, v9
	v_max_u32_e32 v9, v3, v0
	v_min_u32_e32 v0, v3, v0
	v_max_u32_e32 v3, v6, v13
	v_min_u32_e32 v6, v6, v13
	v_max_u32_e32 v13, v16, v14
	v_min_u32_e32 v14, v16, v14
	v_max_u32_e32 v16, v8, v10
	v_min_u32_e32 v8, v8, v10
	v_max_u32_e32 v10, v12, v11
	v_min_u32_e32 v11, v12, v11
	v_max_u32_e32 v12, v15, v5
	v_min_u32_e32 v5, v15, v5
	v_max_u32_e32 v15, v4, v9
	v_min_u32_e32 v4, v4, v9
	v_max_u32_e32 v9, v1, v7
	v_min_u32_e32 v1, v1, v7
	v_max_u32_e32 v7, v2, v0
	v_min_u32_e32 v0, v2, v0
	v_max_u32_e32 v2, v3, v13
	v_min_u32_e32 v3, v3, v13
	v_max_u32_e32 v13, v6, v14
	v_min_u32_e32 v6, v6, v14
	v_max_u32_e32 v14, v16, v10
	v_min_u32_e32 v10, v16, v10
	v_max_u32_e32 v16, v8, v11
	v_min_u32_e32 v8, v8, v11
	v_max_u32_e32 v11, v12, v15
	v_min_u32_e32 v12, v12, v15
	v_max_u32_e32 v15, v5, v4
	v_min_u32_e32 v17, v5, v4
	v_max_u32_e32 v18, v9, v7
	v_min_u32_e32 v19, v9, v7
	v_max_u32_e32 v20, v1, v0
	v_min_u32_e32 v21, v1, v0
	s_nop 1
	v_mov_b32_dpp v0, v21 quad_perm:[2,3,0,1] row_mask:0xf bank_mask:0xf
	v_mov_b32_dpp v1, v20 quad_perm:[2,3,0,1] row_mask:0xf bank_mask:0xf
	v_mov_b32_dpp v4, v19 quad_perm:[2,3,0,1] row_mask:0xf bank_mask:0xf
	v_mov_b32_dpp v5, v18 quad_perm:[2,3,0,1] row_mask:0xf bank_mask:0xf
	v_mov_b32_dpp v7, v17 quad_perm:[2,3,0,1] row_mask:0xf bank_mask:0xf
	v_mov_b32_dpp v9, v15 quad_perm:[2,3,0,1] row_mask:0xf bank_mask:0xf
	v_mov_b32_dpp v22, v12 quad_perm:[2,3,0,1] row_mask:0xf bank_mask:0xf
	v_mov_b32_dpp v23, v11 quad_perm:[2,3,0,1] row_mask:0xf bank_mask:0xf
	v_mov_b32_dpp v24, v8 quad_perm:[2,3,0,1] row_mask:0xf bank_mask:0xf
	v_mov_b32_dpp v25, v16 quad_perm:[2,3,0,1] row_mask:0xf bank_mask:0xf
	v_mov_b32_dpp v26, v10 quad_perm:[2,3,0,1] row_mask:0xf bank_mask:0xf
	v_mov_b32_dpp v27, v14 quad_perm:[2,3,0,1] row_mask:0xf bank_mask:0xf
	v_mov_b32_dpp v28, v6 quad_perm:[2,3,0,1] row_mask:0xf bank_mask:0xf
	v_mov_b32_dpp v29, v13 quad_perm:[2,3,0,1] row_mask:0xf bank_mask:0xf
	v_mov_b32_dpp v30, v3 quad_perm:[2,3,0,1] row_mask:0xf bank_mask:0xf
	v_mov_b32_dpp v31, v2 quad_perm:[2,3,0,1] row_mask:0xf bank_mask:0xf
	s_waitcnt lgkmcnt(0)
	v_max_u32_e32 v0, v2, v0
	v_max_u32_e32 v1, v3, v1
	v_max_u32_e32 v2, v13, v4
	v_max_u32_e32 v3, v6, v5
	v_max_u32_e32 v4, v14, v7
	v_max_u32_e32 v5, v10, v9
	v_max_u32_e32 v6, v16, v22
	v_max_u32_e32 v7, v8, v23
	v_max_u32_e32 v8, v11, v24
	v_max_u32_e32 v9, v12, v25
	v_max_u32_e32 v10, v15, v26
	v_max_u32_e32 v11, v17, v27
	v_max_u32_e32 v12, v18, v28
	v_max_u32_e32 v13, v19, v29
	v_max_u32_e32 v14, v20, v30
	v_max_u32_e32 v15, v21, v31
	v_max_u32_e32 v16, v0, v8
	v_max_u32_e32 v17, v1, v9
	v_max_u32_e32 v18, v2, v10
	v_max_u32_e32 v19, v3, v11
	v_max_u32_e32 v20, v4, v12
	v_max_u32_e32 v21, v5, v13
	v_max_u32_e32 v22, v6, v14
	v_max_u32_e32 v23, v7, v15
	s_and_saveexec_b64 s[16:17], s[4:5]
	s_cbranch_execz .LBB0_69
	v_max_u32_e32 v24, v16, v20
	v_max_u32_e32 v25, v18, v22
	v_max_u32_e32 v27, v17, v21
	v_max_u32_e32 v28, v19, v23
	v_min_u32_e32 v26, v24, v25
	v_min_u32_e32 v29, v27, v28
	v_max_u32_e32 v24, v24, v25
	v_max_u32_e32 v25, v27, v28
	v_min_u32_e32 v30, v26, v29
	v_max_u32_e32 v29, v26, v29
	v_min_u32_e32 v26, v24, v25
	v_max_u32_e32 v24, v24, v25
	v_xor_b32_e32 v25, -1, v26
	v_xor_b32_e32 v24, -1, v24
	v_and_b32_e32 v25, 0x7f, v25
	v_and_b32_e32 v24, 0x7f, v24
	v_lshl_add_u32 v26, v24, 2, v169
	v_lshl_add_u32 v27, v25, 2, v169
	ds_read_b32 v26, v26 offset:17408
	ds_read_b32 v27, v27 offset:17408
	v_xor_b32_e32 v28, -1, v29
	s_waitcnt lgkmcnt(0)
	ds_write_b64 v184, v[26:27] offset:53312
	v_xor_b32_e32 v26, -1, v30
	v_and_b32_e32 v27, 0x7f, v26
	v_and_b32_e32 v26, 0x7f, v28
	v_lshl_add_u32 v28, v26, 2, v169
	ds_write2_b64 v116, v[24:25], v[26:27] offset0:8 offset1:9
	v_lshl_add_u32 v24, v27, 2, v169
	ds_read_b32 v28, v28 offset:17408
	ds_read_b32 v29, v24 offset:17408
	s_waitcnt lgkmcnt(0)
	ds_write_b64 v184, v[28:29] offset:53320

; DI unsigned fkey(float f) { const unsigned u = __float_as_uint(f); return (u & 0x80000000u) ? ~u : (u | 0x80000000u); }
; DI void topk_phase(unsigned char* smem_, const bf16_t* __restrict__ qp, const bf16_t* __restrict__ keys, int* __restrict__ eidx, float* __restrict__ gate) {
;     ...
;     constexpr unsigned KT[13] = {0x03020100u, 0x07060504u, 0x0b0a0908u, 0x0f0e0d0cu, 0x13121110u, 0x17161514u, 0x23222120u, 0x32313024u, 0x42414033u, 0x61605150u, 0x90807170u, 0xd0c0b0a0u, 0x0000f0e0u};
;     unsigned c16[16];
; #pragma unroll
;     for (int i = 0; i < 13; ++i) {
;         const unsigned ab = (KT[i] >> (8 * q)) & 255u;
;         const float c = SV[row * 32 + (ab >> 4)] + SV[row * 32 + 16 + (ab & 15u)];
;         c16[i] = (fkey(c) & ~255u) | (255u - ab);
;     }
.LBB0_75:
	s_or_b64 exec, exec, s[16:17]
	s_waitcnt lgkmcnt(0)
	s_barrier
	ds_read_b96 v[0:2], v175 offset:53248
	ds_read_b32 v5, v186 offset:53312
	ds_read_b32 v3, v188 offset:53312
	ds_read_b32 v4, v175 offset:53312
	s_mov_b32 s16, 0xff61b1e6
	s_waitcnt lgkmcnt(3)
	v_mov_b32_e32 v7, v2
	s_waitcnt lgkmcnt(2)
	v_add_f32_e32 v2, v0, v5
	v_ashrrev_i32_e32 v5, 31, v2
	v_or_b32_e32 v8, 0x80000000, v5

; DI unsigned fkey(float f) { const unsigned u = __float_as_uint(f); return (u & 0x80000000u) ? ~u : (u | 0x80000000u); }
; DI void topk_phase(unsigned char* smem_, const bf16_t* __restrict__ qp, const bf16_t* __restrict__ keys, int* __restrict__ eidx, float* __restrict__ gate) {
;     ...
;     constexpr unsigned KT[13] = {0x03020100u, 0x07060504u, 0x0b0a0908u, 0x0f0e0d0cu, 0x13121110u, 0x17161514u, 0x23222120u, 0x32313024u, 0x42414033u, 0x61605150u, 0x90807170u, 0xd0c0b0a0u, 0x0000f0e0u};
;     unsigned c16[16];
; #pragma unroll
;     for (int i = 0; i < 13; ++i) {
;         const unsigned ab = (KT[i] >> (8 * q)) & 255u;
;         const float c = SV[row * 32 + (ab >> 4)] + SV[row * 32 + 16 + (ab & 15u)];
;         c16[i] = (fkey(c) & ~255u) | (255u - ab);
;     }
	v_mov_b32_e32 v6, v1
	v_or_b32_e32 v158, s24, v164
	v_xor_b32_e32 v2, v8, v2
	v_and_b32_e32 v2, 0xffffff00, v2
	v_bitop3_b32 v5, v2, s71, v185 bitop3:0x36
	ds_read_b32 v2, v190 offset:53312
	ds_read_b32 v9, v211 offset:53312
	ds_read_b32 v8, v213 offset:53312
	ds_read_b32 v10, v215 offset:53312
	ds_read_b32 v11, v217 offset:53312
	ds_read_b32 v13, v219 offset:53248
	ds_read_b32 v15, v220 offset:53312
	ds_read_b32 v12, v222 offset:53248
	s_waitcnt lgkmcnt(7)
	v_pk_add_f32 v[2:3], v[0:1], v[2:3] op_sel_hi:[0,1]
	v_ashrrev_i32_e32 v14, 31, v3
	v_or_b32_e32 v16, 0x80000000, v14

; DI unsigned fkey(float f) { const unsigned u = __float_as_uint(f); return (u & 0x80000000u) ? ~u : (u | 0x80000000u); }
; DI void topk_phase(unsigned char* smem_, const bf16_t* __restrict__ qp, const bf16_t* __restrict__ keys, int* __restrict__ eidx, float* __restrict__ gate) {
;     ...
;     constexpr unsigned KT[13] = {0x03020100u, 0x07060504u, 0x0b0a0908u, 0x0f0e0d0cu, 0x13121110u, 0x17161514u, 0x23222120u, 0x32313024u, 0x42414033u, 0x61605150u, 0x90807170u, 0xd0c0b0a0u, 0x0000f0e0u};
;     unsigned c16[16];
; #pragma unroll
;     for (int i = 0; i < 13; ++i) {
;         const unsigned ab = (KT[i] >> (8 * q)) & 255u;
;         const float c = SV[row * 32 + (ab >> 4)] + SV[row * 32 + 16 + (ab & 15u)];
;         c16[i] = (fkey(c) & ~255u) | (255u - ab);
;     }
	v_ashrrev_i32_e32 v159, 31, v158
	v_lshlrev_b64 v[158:159], 7, v[158:159]
	v_xor_b32_e32 v3, v16, v3
	v_and_b32_e32 v3, 0xffffff00, v3
	v_bitop3_b32 v16, v3, s71, v187 bitop3:0x36
	v_ashrrev_i32_e32 v3, 31, v2
	v_or_b32_e32 v14, 0x80000000, v3

; DI unsigned fkey(float f) { const unsigned u = __float_as_uint(f); return (u & 0x80000000u) ? ~u : (u | 0x80000000u); }
; DI void topk_phase(unsigned char* smem_, const bf16_t* __restrict__ qp, const bf16_t* __restrict__ keys, int* __restrict__ eidx, float* __restrict__ gate) {
;     ...
;     constexpr unsigned KT[13] = {0x03020100u, 0x07060504u, 0x0b0a0908u, 0x0f0e0d0cu, 0x13121110u, 0x17161514u, 0x23222120u, 0x32313024u, 0x42414033u, 0x61605150u, 0x90807170u, 0xd0c0b0a0u, 0x0000f0e0u};
;     unsigned c16[16];
; #pragma unroll
;     for (int i = 0; i < 13; ++i) {
;         const unsigned ab = (KT[i] >> (8 * q)) & 255u;
;         const float c = SV[row * 32 + (ab >> 4)] + SV[row * 32 + 16 + (ab & 15u)];
;         c16[i] = (fkey(c) & ~255u) | (255u - ab);
;     }
	v_lshl_or_b32 v158, s23, 4, v158
	v_lshlrev_b64 v[158:159], 2, v[158:159]
	v_xor_b32_e32 v2, v14, v2
	v_and_b32_e32 v2, 0xffffff00, v2
	v_bitop3_b32 v17, v2, s71, v189 bitop3:0x36
	v_mov_b32_e32 v2, v1
	v_mov_b32_e32 v3, v0
	s_waitcnt lgkmcnt(5)
	v_pk_add_f32 v[0:1], v[2:3], v[8:9]
	s_nop 0
	v_ashrrev_i32_e32 v2, 31, v1
	v_or_b32_e32 v3, 0x80000000, v2

; DI unsigned fkey(float f) { const unsigned u = __float_as_uint(f); return (u & 0x80000000u) ? ~u : (u | 0x80000000u); }
; DI void topk_phase(unsigned char* smem_, const bf16_t* __restrict__ qp, const bf16_t* __restrict__ keys, int* __restrict__ eidx, float* __restrict__ gate) {
;     ...
;     constexpr unsigned KT[13] = {0x03020100u, 0x07060504u, 0x0b0a0908u, 0x0f0e0d0cu, 0x13121110u, 0x17161514u, 0x23222120u, 0x32313024u, 0x42414033u, 0x61605150u, 0x90807170u, 0xd0c0b0a0u, 0x0000f0e0u};
;     unsigned c16[16];
; #pragma unroll
;     for (int i = 0; i < 13; ++i) {
;         const unsigned ab = (KT[i] >> (8 * q)) & 255u;
;         const float c = SV[row * 32 + (ab >> 4)] + SV[row * 32 + 16 + (ab & 15u)];
;         c16[i] = (fkey(c) & ~255u) | (255u - ab);
;     }
	s_nop 1
	v_xor_b32_e32 v1, v3, v1
	v_and_b32_e32 v1, 0xffffff00, v1
	v_bitop3_b32 v18, v1, s71, v191 bitop3:0x36
	v_ashrrev_i32_e32 v1, 31, v0
	v_or_b32_e32 v2, 0x80000000, v1

; DI unsigned fkey(float f) { const unsigned u = __float_as_uint(f); return (u & 0x80000000u) ? ~u : (u | 0x80000000u); }
; DI void topk_phase(unsigned char* smem_, const bf16_t* __restrict__ qp, const bf16_t* __restrict__ keys, int* __restrict__ eidx, float* __restrict__ gate) {
;     ...
;     constexpr unsigned KT[13] = {0x03020100u, 0x07060504u, 0x0b0a0908u, 0x0f0e0d0cu, 0x13121110u, 0x17161514u, 0x23222120u, 0x32313024u, 0x42414033u, 0x61605150u, 0x90807170u, 0xd0c0b0a0u, 0x0000f0e0u};
;     unsigned c16[16];
; #pragma unroll
;     for (int i = 0; i < 13; ++i) {
;         const unsigned ab = (KT[i] >> (8 * q)) & 255u;
;         const float c = SV[row * 32 + (ab >> 4)] + SV[row * 32 + 16 + (ab & 15u)];
;         c16[i] = (fkey(c) & ~255u) | (255u - ab);
;     }
	s_nop 1
	v_xor_b32_e32 v0, v2, v0
	v_and_b32_e32 v0, 0xffffff00, v0
	v_bitop3_b32 v19, v0, s71, v212 bitop3:0x36
	s_waitcnt lgkmcnt(3)
	v_pk_add_f32 v[0:1], v[6:7], v[10:11]
	s_nop 0
	v_ashrrev_i32_e32 v2, 31, v0
	v_or_b32_e32 v3, 0x80000000, v2

; DI unsigned fkey(float f) { const unsigned u = __float_as_uint(f); return (u & 0x80000000u) ? ~u : (u | 0x80000000u); }
; DI void topk_phase(unsigned char* smem_, const bf16_t* __restrict__ qp, const bf16_t* __restrict__ keys, int* __restrict__ eidx, float* __restrict__ gate) {
;     ...
;     constexpr unsigned KT[13] = {0x03020100u, 0x07060504u, 0x0b0a0908u, 0x0f0e0d0cu, 0x13121110u, 0x17161514u, 0x23222120u, 0x32313024u, 0x42414033u, 0x61605150u, 0x90807170u, 0xd0c0b0a0u, 0x0000f0e0u};
;     unsigned c16[16];
; #pragma unroll
;     for (int i = 0; i < 13; ++i) {
;         const unsigned ab = (KT[i] >> (8 * q)) & 255u;
;         const float c = SV[row * 32 + (ab >> 4)] + SV[row * 32 + 16 + (ab & 15u)];
;         c16[i] = (fkey(c) & ~255u) | (255u - ab);
;     }
	s_nop 1
	v_xor_b32_e32 v0, v3, v0
	v_and_b32_e32 v0, 0xffffff00, v0
	v_bitop3_b32 v10, v0, s71, v214 bitop3:0x36
	v_ashrrev_i32_e32 v0, 31, v1
	v_or_b32_e32 v2, 0x80000000, v0

; DI unsigned fkey(float f) { const unsigned u = __float_as_uint(f); return (u & 0x80000000u) ? ~u : (u | 0x80000000u); }
; DI void topk_phase(unsigned char* smem_, const bf16_t* __restrict__ qp, const bf16_t* __restrict__ keys, int* __restrict__ eidx, float* __restrict__ gate) {
;     ...
;     constexpr unsigned KT[13] = {0x03020100u, 0x07060504u, 0x0b0a0908u, 0x0f0e0d0cu, 0x13121110u, 0x17161514u, 0x23222120u, 0x32313024u, 0x42414033u, 0x61605150u, 0x90807170u, 0xd0c0b0a0u, 0x0000f0e0u};
;     unsigned c16[16];
; #pragma unroll
;     for (int i = 0; i < 13; ++i) {
;         const unsigned ab = (KT[i] >> (8 * q)) & 255u;
;         const float c = SV[row * 32 + (ab >> 4)] + SV[row * 32 + 16 + (ab & 15u)];
;         c16[i] = (fkey(c) & ~255u) | (255u - ab);
;     }
	s_nop 1
	v_xor_b32_e32 v0, v2, v1
	v_and_b32_e32 v0, 0xffffff00, v0
	v_bitop3_b32 v11, v0, s71, v216 bitop3:0x36
	ds_read_b32 v14, v223 offset:53312
	ds_read_b32 v1, v225 offset:53248
	ds_read_b32 v3, v226 offset:53312
	ds_read_b32 v0, v228 offset:53248
	ds_read_b32 v2, v229 offset:53312
	ds_read_b32 v7, v232 offset:53248
	ds_read_b32 v6, v233 offset:53248
	s_waitcnt lgkmcnt(6)
	v_pk_add_f32 v[8:9], v[12:13], v[14:15]
	s_waitcnt lgkmcnt(2)
	v_pk_add_f32 v[0:1], v[0:1], v[2:3]
	v_ashrrev_i32_e32 v12, 31, v9
	v_or_b32_e32 v13, 0x80000000, v12

; DI unsigned fkey(float f) { const unsigned u = __float_as_uint(f); return (u & 0x80000000u) ? ~u : (u | 0x80000000u); }
; DI void topk_phase(unsigned char* smem_, const bf16_t* __restrict__ qp, const bf16_t* __restrict__ keys, int* __restrict__ eidx, float* __restrict__ gate) {
;     ...
;     constexpr unsigned KT[13] = {0x03020100u, 0x07060504u, 0x0b0a0908u, 0x0f0e0d0cu, 0x13121110u, 0x17161514u, 0x23222120u, 0x32313024u, 0x42414033u, 0x61605150u, 0x90807170u, 0xd0c0b0a0u, 0x0000f0e0u};
;     unsigned c16[16];
; #pragma unroll
;     for (int i = 0; i < 13; ++i) {
;         const unsigned ab = (KT[i] >> (8 * q)) & 255u;
;         const float c = SV[row * 32 + (ab >> 4)] + SV[row * 32 + 16 + (ab & 15u)];
;         c16[i] = (fkey(c) & ~255u) | (255u - ab);
;     }
	v_ashrrev_i32_e32 v2, 31, v1
	v_or_b32_e32 v3, 0x80000000, v2
	v_xor_b32_e32 v9, v13, v9
	v_ashrrev_i32_e32 v12, 31, v8
	v_or_b32_e32 v13, 0x80000000, v12

; DI unsigned fkey(float f) { const unsigned u = __float_as_uint(f); return (u & 0x80000000u) ? ~u : (u | 0x80000000u); }
; DI void topk_phase(unsigned char* smem_, const bf16_t* __restrict__ qp, const bf16_t* __restrict__ keys, int* __restrict__ eidx, float* __restrict__ gate) {
;     ...
;     constexpr unsigned KT[13] = {0x03020100u, 0x07060504u, 0x0b0a0908u, 0x0f0e0d0cu, 0x13121110u, 0x17161514u, 0x23222120u, 0x32313024u, 0x42414033u, 0x61605150u, 0x90807170u, 0xd0c0b0a0u, 0x0000f0e0u};
;     unsigned c16[16];
; #pragma unroll
;     for (int i = 0; i < 13; ++i) {
;         const unsigned ab = (KT[i] >> (8 * q)) & 255u;
;         const float c = SV[row * 32 + (ab >> 4)] + SV[row * 32 + 16 + (ab & 15u)];
;         c16[i] = (fkey(c) & ~255u) | (255u - ab);
;     }
	v_and_b32_e32 v9, 0xffffff00, v9
	v_bitop3_b32 v9, v9, s71, v218 bitop3:0x36
	v_xor_b32_e32 v8, v13, v8

; DI unsigned fkey(float f) { const unsigned u = __float_as_uint(f); return (u & 0x80000000u) ? ~u : (u | 0x80000000u); }
; DI void topk_phase(unsigned char* smem_, const bf16_t* __restrict__ qp, const bf16_t* __restrict__ keys, int* __restrict__ eidx, float* __restrict__ gate) {
;     ...
;     constexpr unsigned KT[13] = {0x03020100u, 0x07060504u, 0x0b0a0908u, 0x0f0e0d0cu, 0x13121110u, 0x17161514u, 0x23222120u, 0x32313024u, 0x42414033u, 0x61605150u, 0x90807170u, 0xd0c0b0a0u, 0x0000f0e0u};
;     unsigned c16[16];
; #pragma unroll
;     for (int i = 0; i < 13; ++i) {
;         const unsigned ab = (KT[i] >> (8 * q)) & 255u;
;         const float c = SV[row * 32 + (ab >> 4)] + SV[row * 32 + 16 + (ab & 15u)];
;         c16[i] = (fkey(c) & ~255u) | (255u - ab);
;     }
	v_and_b32_e32 v8, 0xffffff00, v8
	v_bitop3_b32 v8, v8, s71, v221 bitop3:0x36
	v_xor_b32_e32 v1, v3, v1
	v_and_b32_e32 v1, 0xffffff00, v1
	v_bitop3_b32 v2, v1, s71, v224 bitop3:0x36
	v_ashrrev_i32_e32 v1, 31, v0
	v_or_b32_e32 v3, 0x80000000, v1

; DI unsigned fkey(float f) { const unsigned u = __float_as_uint(f); return (u & 0x80000000u) ? ~u : (u | 0x80000000u); }
; DI void topk_phase(unsigned char* smem_, const bf16_t* __restrict__ qp, const bf16_t* __restrict__ keys, int* __restrict__ eidx, float* __restrict__ gate) {
;     ...
;     constexpr unsigned KT[13] = {0x03020100u, 0x07060504u, 0x0b0a0908u, 0x0f0e0d0cu, 0x13121110u, 0x17161514u, 0x23222120u, 0x32313024u, 0x42414033u, 0x61605150u, 0x90807170u, 0xd0c0b0a0u, 0x0000f0e0u};
;     unsigned c16[16];
; #pragma unroll
;     for (int i = 0; i < 13; ++i) {
;         const unsigned ab = (KT[i] >> (8 * q)) & 255u;
;         const float c = SV[row * 32 + (ab >> 4)] + SV[row * 32 + 16 + (ab & 15u)];
;         c16[i] = (fkey(c) & ~255u) | (255u - ab);
;     }
	v_max_u32_e32 v12, v19, v10
	v_min_u32_e32 v10, v19, v10
	v_xor_b32_e32 v0, v3, v0
	v_and_b32_e32 v0, 0xffffff00, v0
	v_bitop3_b32 v3, v0, s71, v227 bitop3:0x36
	s_waitcnt lgkmcnt(0)
	v_pk_add_f32 v[0:1], v[6:7], v[4:5] op_sel_hi:[1,0]
	v_min_u32_e32 v7, v18, v17
	v_ashrrev_i32_e32 v4, 31, v1
	v_or_b32_e32 v6, 0x80000000, v4

; DI unsigned fkey(float f) { const unsigned u = __float_as_uint(f); return (u & 0x80000000u) ? ~u : (u | 0x80000000u); }
; DI void topk_phase(unsigned char* smem_, const bf16_t* __restrict__ qp, const bf16_t* __restrict__ keys, int* __restrict__ eidx, float* __restrict__ gate) {
;     ...
;     constexpr unsigned KT[13] = {0x03020100u, 0x07060504u, 0x0b0a0908u, 0x0f0e0d0cu, 0x13121110u, 0x17161514u, 0x23222120u, 0x32313024u, 0x42414033u, 0x61605150u, 0x90807170u, 0xd0c0b0a0u, 0x0000f0e0u};
;     unsigned c16[16];
; #pragma unroll
;     for (int i = 0; i < 13; ++i) {
;         const unsigned ab = (KT[i] >> (8 * q)) & 255u;
;         const float c = SV[row * 32 + (ab >> 4)] + SV[row * 32 + 16 + (ab & 15u)];
;         c16[i] = (fkey(c) & ~255u) | (255u - ab);
;     }
	v_max_u32_e32 v13, v9, v11
	v_min_u32_e32 v9, v9, v11
	v_xor_b32_e32 v1, v6, v1
	v_and_b32_e32 v1, 0xffffff00, v1
	v_ashrrev_i32_e32 v4, 31, v0
	v_or_b32_e32 v6, 0x80000000, v4

; DI unsigned fkey(float f) { const unsigned u = __float_as_uint(f); return (u & 0x80000000u) ? ~u : (u | 0x80000000u); }
; template <int N> DI void bitonic_sort_desc(unsigned (&v)[N]) {
; #pragma unroll
;     for (int k = 2; k <= N; k <<= 1)
; #pragma unroll
;         for (int j = k >> 1; j > 0; j >>= 1)
; #pragma unroll
;             for (int i = 0; i < N; ++i) { const int l = i ^ j; if (l > i) { if ((i & k) == 0) cswap(v[i], v[l]); else cswap(v[l], v[i]); } }
; }
; DI void merge_top16(unsigned (&v)[16], int st) {
;     unsigned x[16];
; #pragma unroll
;     for (int i = 0; i < 16; ++i) x[i] = (unsigned)__shfl_xor((int)v[15 - i], st);
; #pragma unroll
;     for (int i = 0; i < 16; ++i) v[i] = max(v[i], x[i]);
; #pragma unroll
;     for (int j = 8; j > 0; j >>= 1)
; #pragma unroll
;         for (int i = 0; i < 16; ++i) { const int l = i ^ j; if (l > i) cswap(v[i], v[l]); }
; }
; DI void topk_phase(unsigned char* smem_, const bf16_t* __restrict__ qp, const bf16_t* __restrict__ keys, int* __restrict__ eidx, float* __restrict__ gate) {
;     ...
;         c16[i] = (fkey(c) & ~255u) | (255u - ab);
;     }
;     if (q >= 2) c16[12] = 0u;
;     c16[13] = 0u; c16[14] = 0u; c16[15] = 0u;
;     bitonic_sort_desc<16>(c16);
;     merge_top16(c16, 1);
;     merge_top16(c16, 2);
	v_bitop3_b32 v1, v1, s71, v230 bitop3:0x36
	v_max_u32_e32 v11, v8, v2
	v_xor_b32_e32 v0, v6, v0
	v_and_b32_e32 v0, 0xffffff00, v0
	v_max_u32_e32 v4, v5, v16
	v_min_u32_e32 v5, v5, v16
	v_max_u32_e32 v6, v18, v17
	v_min_u32_e32 v2, v8, v2
	v_max_u32_e32 v8, v1, v3
	v_min_u32_e32 v1, v1, v3
	v_bitop3_b32 v0, v0, s71, v231 bitop3:0x36
	v_max_u32_e32 v3, v4, v7
	v_min_u32_e32 v4, v4, v7
	v_max_u32_e32 v7, v5, v6
	v_min_u32_e32 v5, v5, v6
	v_max_u32_e32 v6, v9, v12
	v_min_u32_e32 v9, v9, v12
	v_max_u32_e32 v12, v13, v10
	v_min_u32_e32 v10, v13, v10
	v_max_u32_e32 v13, v11, v1
	v_min_u32_e32 v1, v11, v1
	v_max_u32_e32 v11, v2, v8
	v_min_u32_e32 v2, v2, v8
	v_cndmask_b32_e64 v0, v0, 0, s[2:3]
	v_max_u32_e32 v8, v3, v7
	v_min_u32_e32 v3, v3, v7
	v_max_u32_e32 v7, v4, v5
	v_min_u32_e32 v4, v4, v5
	v_max_u32_e32 v5, v10, v9
	v_min_u32_e32 v9, v10, v9
	v_max_u32_e32 v10, v12, v6
	v_min_u32_e32 v6, v12, v6
	v_max_u32_e32 v12, v13, v11
	v_min_u32_e32 v11, v13, v11
	v_max_u32_e32 v13, v1, v2
	v_min_u32_e32 v1, v1, v2
	v_max_u32_e32 v2, v8, v9
	v_min_u32_e32 v8, v8, v9
	v_max_u32_e32 v9, v3, v5
	v_min_u32_e32 v3, v3, v5
	v_max_u32_e32 v5, v7, v6
	v_min_u32_e32 v6, v7, v6
	v_max_u32_e32 v7, v4, v10
	v_min_u32_e32 v4, v4, v10
	v_max_u32_e32 v10, v0, v1
	v_min_u32_e32 v0, v0, v1
	v_max_u32_e32 v1, v2, v5
	v_min_u32_e32 v2, v2, v5
	v_max_u32_e32 v5, v9, v7
	v_min_u32_e32 v7, v9, v7
	v_max_u32_e32 v9, v8, v6
	v_min_u32_e32 v6, v8, v6
	v_max_u32_e32 v8, v3, v4
	v_min_u32_e32 v3, v3, v4
	v_max_u32_e32 v4, v13, v12
	v_min_u32_e32 v12, v13, v12
	v_max_u32_e32 v13, v10, v11
	v_min_u32_e32 v10, v10, v11
	v_max_u32_e32 v11, v1, v5
	v_min_u32_e32 v1, v1, v5
	v_max_u32_e32 v5, v2, v7
	v_min_u32_e32 v2, v2, v7
	v_max_u32_e32 v7, v9, v8
	v_min_u32_e32 v8, v9, v8
	v_max_u32_e32 v9, v6, v3
	v_min_u32_e32 v3, v6, v3
	v_max_u32_e32 v6, v10, v12
	v_min_u32_e32 v10, v10, v12
	v_max_u32_e32 v12, v13, v4
	v_min_u32_e32 v4, v13, v4
	v_max_u32_e32 v13, v2, v0
	v_min_u32_e32 v0, v2, v0
	v_max_u32_e32 v2, v7, v10
	v_min_u32_e32 v7, v7, v10
	v_max_u32_e32 v10, v8, v6
	v_min_u32_e32 v6, v8, v6
	v_max_u32_e32 v8, v9, v4
	v_min_u32_e32 v4, v9, v4
	v_max_u32_e32 v9, v3, v12
	v_min_u32_e32 v3, v3, v12
	v_max_u32_e32 v12, v11, v2
	v_min_u32_e32 v2, v11, v2
	v_max_u32_e32 v11, v1, v10
	v_min_u32_e32 v1, v1, v10
	v_max_u32_e32 v10, v5, v8
	v_min_u32_e32 v5, v5, v8
	v_max_u32_e32 v8, v13, v9
	v_min_u32_e32 v9, v13, v9
	v_max_u32_e32 v13, v0, v3
	v_min_u32_e32 v0, v0, v3
	v_max_u32_e32 v3, v12, v10
	v_min_u32_e32 v10, v12, v10
	v_max_u32_e32 v12, v11, v8
	v_min_u32_e32 v8, v11, v8
	v_max_u32_e32 v11, v2, v5
	v_min_u32_e32 v2, v2, v5
	v_max_u32_e32 v5, v1, v9
	v_min_u32_e32 v1, v1, v9
	v_max_u32_e32 v9, v7, v4
	v_min_u32_e32 v4, v7, v4
	v_max_u32_e32 v7, v6, v13
	v_min_u32_e32 v6, v6, v13
	v_max_u32_e32 v13, v3, v12
	v_min_u32_e32 v3, v3, v12
	v_max_u32_e32 v12, v10, v8
	v_min_u32_e32 v8, v10, v8
	v_max_u32_e32 v10, v11, v5
	v_min_u32_e32 v5, v11, v5
	v_max_u32_e32 v11, v2, v1
	v_min_u32_e32 v1, v2, v1
	v_max_u32_e32 v2, v9, v7
	v_min_u32_e32 v7, v9, v7
	v_max_u32_e32 v9, v4, v6
	v_min_u32_e32 v4, v4, v6
	s_nop 1
	v_mov_b32_dpp v6, v0 quad_perm:[1,0,3,2] row_mask:0xf bank_mask:0xf
	v_mov_b32_dpp v14, v4 quad_perm:[1,0,3,2] row_mask:0xf bank_mask:0xf
	v_mov_b32_dpp v15, v9 quad_perm:[1,0,3,2] row_mask:0xf bank_mask:0xf
	v_mov_b32_dpp v16, v7 quad_perm:[1,0,3,2] row_mask:0xf bank_mask:0xf
	v_mov_b32_dpp v17, v2 quad_perm:[1,0,3,2] row_mask:0xf bank_mask:0xf
	v_mov_b32_dpp v18, v1 quad_perm:[1,0,3,2] row_mask:0xf bank_mask:0xf
	v_mov_b32_dpp v19, v11 quad_perm:[1,0,3,2] row_mask:0xf bank_mask:0xf
	v_mov_b32_dpp v20, v5 quad_perm:[1,0,3,2] row_mask:0xf bank_mask:0xf
	v_mov_b32_dpp v21, v10 quad_perm:[1,0,3,2] row_mask:0xf bank_mask:0xf
	v_mov_b32_dpp v22, v8 quad_perm:[1,0,3,2] row_mask:0xf bank_mask:0xf
	v_mov_b32_dpp v23, v12 quad_perm:[1,0,3,2] row_mask:0xf bank_mask:0xf
	v_mov_b32_dpp v24, v3 quad_perm:[1,0,3,2] row_mask:0xf bank_mask:0xf
	v_mov_b32_dpp v25, v13 quad_perm:[1,0,3,2] row_mask:0xf bank_mask:0xf
	s_waitcnt lgkmcnt(0)
	v_max_u32_e32 v6, v8, v6
	v_max_u32_e32 v8, v10, v14
	v_max_u32_e32 v5, v5, v15
	v_max_u32_e32 v10, v11, v16
	v_max_u32_e32 v1, v1, v17
	v_max_u32_e32 v2, v2, v18
	v_max_u32_e32 v7, v7, v19
	v_max_u32_e32 v9, v9, v20
	v_max_u32_e32 v4, v4, v21
	v_max_u32_e32 v0, v0, v22
	v_max_u32_e32 v11, v13, v2
	v_min_u32_e32 v2, v13, v2
	v_max_u32_e32 v13, v3, v7
	v_min_u32_e32 v3, v3, v7
	v_max_u32_e32 v7, v12, v9
	v_min_u32_e32 v9, v12, v9
	v_max_u32_e32 v12, v6, v4
	v_min_u32_e32 v4, v6, v4
	v_max_u32_e32 v6, v8, v0
	v_min_u32_e32 v0, v8, v0
	v_max_u32_e32 v8, v5, v23
	v_min_u32_e32 v5, v5, v23
	v_max_u32_e32 v14, v10, v24
	v_min_u32_e32 v10, v10, v24
	v_max_u32_e32 v15, v1, v25
	v_min_u32_e32 v1, v1, v25
	v_max_u32_e32 v16, v11, v6
	v_min_u32_e32 v6, v11, v6
	v_max_u32_e32 v11, v13, v8
	v_min_u32_e32 v8, v13, v8
	v_max_u32_e32 v13, v7, v14
	v_min_u32_e32 v7, v7, v14
	v_max_u32_e32 v14, v12, v15
	v_min_u32_e32 v12, v12, v15
	v_max_u32_e32 v15, v2, v0
	v_min_u32_e32 v0, v2, v0
	v_max_u32_e32 v2, v3, v5
	v_min_u32_e32 v3, v3, v5
	v_max_u32_e32 v5, v9, v10
	v_min_u32_e32 v9, v9, v10
	v_max_u32_e32 v10, v4, v1
	v_min_u32_e32 v1, v4, v1
	v_max_u32_e32 v4, v16, v13
	v_min_u32_e32 v13, v16, v13
	v_max_u32_e32 v16, v11, v14
	v_min_u32_e32 v11, v11, v14
	v_max_u32_e32 v14, v6, v7
	v_min_u32_e32 v6, v6, v7
	v_max_u32_e32 v7, v8, v12
	v_min_u32_e32 v8, v8, v12
	v_max_u32_e32 v12, v15, v5
	v_min_u32_e32 v5, v15, v5
	v_max_u32_e32 v15, v2, v10
	v_min_u32_e32 v2, v2, v10
	v_max_u32_e32 v10, v0, v9
	v_min_u32_e32 v0, v0, v9
	v_max_u32_e32 v9, v3, v1
	v_min_u32_e32 v1, v3, v1
; DI void merge_top16(unsigned (&v)[16], int st) {
;     unsigned x[16];
; #pragma unroll
;     for (int i = 0; i < 16; ++i) x[i] = (unsigned)__shfl_xor((int)v[15 - i], st);
; #pragma unroll
;     for (int i = 0; i < 16; ++i) v[i] = max(v[i], x[i]);
; #pragma unroll
;     for (int j = 8; j > 0; j >>= 1)
; #pragma unroll
;         for (int i = 0; i < 16; ++i) { const int l = i ^ j; if (l > i) cswap(v[i], v[l]); }
; }
; DI void topk_phase(unsigned char* smem_, const bf16_t* __restrict__ qp, const bf16_t* __restrict__ keys, int* __restrict__ eidx, float* __restrict__ gate) {
;     ...
;     merge_top16(c16, 1);
;     merge_top16(c16, 2);
;     float bv[16]; int be[16]; float mx = -3.0e38f;
; #pragma unroll
;     for (int i = 0; i < 16; ++i) {
;         const int ab = 255 - (int)(c16[i] & 255u), a = ab >> 4, b = ab & 15;
;         bv[i] = SV[row * 32 + a] + SV[row * 32 + 16 + b];
;         be[i] = SI[row * 32 + a] * 128 + SI[row * 32 + 16 + b];
;         mx = fmaxf(mx, bv[i]);
	v_max_u32_e32 v3, v4, v16
	v_min_u32_e32 v4, v4, v16
	v_max_u32_e32 v16, v13, v11
	v_min_u32_e32 v11, v13, v11
	v_max_u32_e32 v13, v14, v7
	v_min_u32_e32 v7, v14, v7
	v_max_u32_e32 v14, v6, v8
	v_min_u32_e32 v6, v6, v8
	v_max_u32_e32 v8, v12, v15
	v_min_u32_e32 v12, v12, v15
	v_max_u32_e32 v15, v5, v2
	v_min_u32_e32 v2, v5, v2
	v_max_u32_e32 v5, v10, v9
	v_min_u32_e32 v9, v10, v9
	v_max_u32_e32 v10, v0, v1
	v_min_u32_e32 v0, v0, v1
	s_nop 1
	v_mov_b32_dpp v1, v0 quad_perm:[2,3,0,1] row_mask:0xf bank_mask:0xf
	v_mov_b32_dpp v17, v10 quad_perm:[2,3,0,1] row_mask:0xf bank_mask:0xf
	v_mov_b32_dpp v18, v9 quad_perm:[2,3,0,1] row_mask:0xf bank_mask:0xf
	v_mov_b32_dpp v19, v5 quad_perm:[2,3,0,1] row_mask:0xf bank_mask:0xf
	v_mov_b32_dpp v20, v2 quad_perm:[2,3,0,1] row_mask:0xf bank_mask:0xf
	v_mov_b32_dpp v21, v15 quad_perm:[2,3,0,1] row_mask:0xf bank_mask:0xf
	v_mov_b32_dpp v22, v12 quad_perm:[2,3,0,1] row_mask:0xf bank_mask:0xf
	v_mov_b32_dpp v23, v8 quad_perm:[2,3,0,1] row_mask:0xf bank_mask:0xf
	v_mov_b32_dpp v24, v6 quad_perm:[2,3,0,1] row_mask:0xf bank_mask:0xf
	v_mov_b32_dpp v25, v14 quad_perm:[2,3,0,1] row_mask:0xf bank_mask:0xf
	v_mov_b32_dpp v26, v7 quad_perm:[2,3,0,1] row_mask:0xf bank_mask:0xf
	v_mov_b32_dpp v27, v13 quad_perm:[2,3,0,1] row_mask:0xf bank_mask:0xf
	v_mov_b32_dpp v28, v11 quad_perm:[2,3,0,1] row_mask:0xf bank_mask:0xf
	v_mov_b32_dpp v29, v16 quad_perm:[2,3,0,1] row_mask:0xf bank_mask:0xf
	v_mov_b32_dpp v30, v4 quad_perm:[2,3,0,1] row_mask:0xf bank_mask:0xf
	v_mov_b32_dpp v31, v3 quad_perm:[2,3,0,1] row_mask:0xf bank_mask:0xf
	s_waitcnt lgkmcnt(0)
	v_max_u32_e32 v1, v3, v1
	v_max_u32_e32 v3, v4, v17
	v_max_u32_e32 v4, v16, v18
	v_max_u32_e32 v11, v11, v19
	v_max_u32_e32 v13, v13, v20
	v_max_u32_e32 v7, v7, v21
	v_max_u32_e32 v14, v14, v22
	v_max_u32_e32 v6, v6, v23
	v_max_u32_e32 v8, v8, v24
	v_max_u32_e32 v12, v12, v25
	v_max_u32_e32 v15, v15, v26
	v_max_u32_e32 v2, v2, v27
	v_max_u32_e32 v5, v5, v28
	v_max_u32_e32 v9, v9, v29
	v_max_u32_e32 v10, v10, v30
	v_max_u32_e32 v0, v0, v31
	v_max_u32_e32 v16, v1, v8
	v_min_u32_e32 v1, v1, v8
	v_max_u32_e32 v8, v3, v12
	v_min_u32_e32 v3, v3, v12
	v_max_u32_e32 v12, v4, v15
	v_min_u32_e32 v4, v4, v15
	v_max_u32_e32 v15, v11, v2
	v_min_u32_e32 v2, v11, v2
	v_max_u32_e32 v11, v13, v5
	v_min_u32_e32 v5, v13, v5
	v_max_u32_e32 v13, v7, v9
	v_min_u32_e32 v7, v7, v9
	v_max_u32_e32 v9, v14, v10
	v_min_u32_e32 v10, v14, v10
	v_max_u32_e32 v14, v6, v0
	v_min_u32_e32 v0, v6, v0
	v_max_u32_e32 v6, v16, v11
	v_min_u32_e32 v11, v16, v11
	v_max_u32_e32 v16, v8, v13
	v_min_u32_e32 v8, v8, v13
	v_max_u32_e32 v13, v12, v9
	v_min_u32_e32 v9, v12, v9
	v_max_u32_e32 v12, v15, v14
	v_min_u32_e32 v14, v15, v14
	v_max_u32_e32 v15, v1, v5
	v_min_u32_e32 v1, v1, v5
	v_max_u32_e32 v5, v3, v7
	v_min_u32_e32 v3, v3, v7
	v_max_u32_e32 v7, v4, v10
	v_min_u32_e32 v4, v4, v10
	v_max_u32_e32 v10, v2, v0
	v_min_u32_e32 v0, v2, v0
	v_max_u32_e32 v2, v6, v13
	v_min_u32_e32 v6, v6, v13
	v_max_u32_e32 v13, v16, v12
	v_min_u32_e32 v12, v16, v12
	v_max_u32_e32 v16, v11, v9
	v_min_u32_e32 v9, v11, v9
	v_max_u32_e32 v11, v8, v14
	v_min_u32_e32 v8, v8, v14
	v_max_u32_e32 v14, v15, v7
	v_min_u32_e32 v7, v15, v7
	v_max_u32_e32 v15, v5, v10
	v_min_u32_e32 v5, v5, v10
	v_max_u32_e32 v10, v1, v4
	v_min_u32_e32 v1, v1, v4
	v_max_u32_e32 v4, v3, v0
	v_min_u32_e32 v0, v3, v0
	v_max_u32_e32 v3, v2, v13
	v_not_b32_e32 v17, v3
	v_min_u32_e32 v2, v2, v13
	v_max_u32_e32 v142, v1, v0
	v_min_u32_e32 v144, v1, v0
	v_lshrrev_b32_e32 v0, 4, v17
	v_not_b32_e32 v13, v2
	v_and_or_b32 v0, v0, 15, v174
	v_max_u32_e32 v18, v6, v12
	v_lshl_add_u32 v237, v0, 2, s19
	v_lshrrev_b32_e32 v0, 4, v13
	v_not_b32_e32 v19, v18
	v_and_or_b32 v0, v0, 15, v174
	v_min_u32_e32 v6, v6, v12
	v_bitop3_b32 v1, v3, 15, v3 bitop3:0xc
	v_lshl_add_u32 v239, v0, 2, s19
	v_lshrrev_b32_e32 v0, 4, v19
	v_not_b32_e32 v12, v6
	v_lshl_add_u32 v238, v1, 2, v184
	v_bitop3_b32 v1, v2, 15, v2 bitop3:0xc
	v_and_or_b32 v0, v0, 15, v174
	v_lshl_add_u32 v240, v1, 2, v175
	v_bitop3_b32 v1, v18, 15, v18 bitop3:0xc
	v_lshl_add_u32 v241, v0, 2, s19
	v_lshrrev_b32_e32 v0, 4, v12
	v_lshl_add_u32 v242, v1, 2, v184
	v_bitop3_b32 v1, v6, 15, v6 bitop3:0xc
	v_and_or_b32 v0, v0, 15, v174
	v_max_u32_e32 v30, v7, v5
	v_min_u32_e32 v116, v7, v5
	v_max_u32_e32 v120, v10, v4
	v_min_u32_e32 v124, v10, v4
	v_lshl_add_u32 v243, v0, 2, s19
	v_lshl_add_u32 v244, v1, 2, v175
	ds_read_b32 v0, v237 offset:53248
	ds_read_b32 v1, v238 offset:53312
	ds_read_b32 v2, v239 offset:53248
	ds_read_b32 v3, v240 offset:53312
	ds_read_b32 v4, v241 offset:53248
	ds_read_b32 v5, v242 offset:53312
	ds_read_b32 v6, v243 offset:53248
	ds_read_b32 v7, v244 offset:53312
	v_max_u32_e32 v20, v16, v11
	v_min_u32_e32 v11, v16, v11
	v_not_b32_e32 v16, v11
	s_waitcnt lgkmcnt(2)
	v_add_f32_e32 v148, v4, v5
	v_lshrrev_b32_e32 v5, 4, v16
	v_and_or_b32 v5, v5, 15, v174
	v_bitop3_b32 v10, v11, 15, v11 bitop3:0xc
	v_lshl_add_u32 v5, v5, 2, s19
	v_max_u32_e32 v22, v9, v8
	s_waitcnt lgkmcnt(0)
; DI void topk_phase(unsigned char* smem_, const bf16_t* __restrict__ qp, const bf16_t* __restrict__ keys, int* __restrict__ eidx, float* __restrict__ gate) {
;     ...
;     float bv[16]; int be[16]; float mx = -3.0e38f;
; #pragma unroll
;     for (int i = 0; i < 16; ++i) {
;         const int ab = 255 - (int)(c16[i] & 255u), a = ab >> 4, b = ab & 15;
;         bv[i] = SV[row * 32 + a] + SV[row * 32 + 16 + b];
;         be[i] = SI[row * 32 + a] * 128 + SI[row * 32 + 16 + b];
;         mx = fmaxf(mx, bv[i]);
;     }
;     float sum = 0.f, ex[16];
; #pragma unroll
;     for (int i = 0; i < 16; ++i) { ex[i] = __expf(bv[i] - mx); sum += ex[i]; }
;     const float inv = 1.f / sum;
	v_add_f32_e32 v149, v6, v7
	ds_read2st64_b32 v[6:7], v5 offset0:208 offset1:240
	v_lshl_add_u32 v5, v10, 2, v175
	v_not_b32_e32 v23, v22
	v_add_u32_e32 v5, 64, v5
	ds_read2st64_b32 v[10:11], v5 offset0:208 offset1:240
	v_lshrrev_b32_e32 v5, 4, v23
	v_and_or_b32 v5, v5, 15, v174
	v_bitop3_b32 v12, v22, 15, v22 bitop3:0xc
	v_lshl_add_u32 v5, v5, 2, s19
	v_min_u32_e32 v8, v9, v8
	v_max_u32_e32 v24, v14, v15
	v_min_u32_e32 v26, v14, v15
	v_add_f32_e32 v146, v0, v1
	v_add_f32_e32 v147, v2, v3
	ds_read2st64_b32 v[14:15], v5 offset0:208 offset1:240
	v_lshl_add_u32 v5, v12, 2, v184
	v_not_b32_e32 v21, v20
	v_not_b32_e32 v9, v8
	v_max3_f32 v0, v146, s16, v147
	v_add_u32_e32 v5, 64, v5
	v_max3_f32 v4, v0, v148, v149
	v_lshrrev_b32_e32 v0, 4, v21
	v_bitop3_b32 v2, v20, 15, v20 bitop3:0xc
	ds_read2st64_b32 v[20:21], v5 offset0:208 offset1:240
	v_lshrrev_b32_e32 v5, 4, v9
	v_and_or_b32 v0, v0, 15, v174
	v_lshl_add_u32 v2, v2, 2, v184
	v_and_or_b32 v5, v5, 15, v174
	v_lshl_add_u32 v0, v0, 2, s19
	v_add_u32_e32 v2, 64, v2
	v_bitop3_b32 v8, v8, 15, v8 bitop3:0xc
	v_lshl_add_u32 v5, v5, 2, s19
	ds_read2st64_b32 v[0:1], v0 offset0:208 offset1:240
	ds_read2st64_b32 v[2:3], v2 offset0:208 offset1:240
	ds_read2st64_b32 v[28:29], v5 offset0:208 offset1:240
	v_lshl_add_u32 v5, v8, 2, v175
	v_add_u32_e32 v5, 64, v5
	v_not_b32_e32 v27, v26
	ds_read2st64_b32 v[118:119], v5 offset0:208 offset1:240
	v_lshrrev_b32_e32 v13, 4, v27
	v_and_or_b32 v13, v13, 15, v174
	s_waitcnt lgkmcnt(2)
	v_add_f32_e32 v0, v0, v2
	v_add_f32_e32 v2, v6, v10
	v_add_f32_e32 v6, v14, v20
	v_bitop3_b32 v14, v26, 15, v26 bitop3:0xc
	v_lshl_add_u32 v13, v13, 2, s19
	ds_read2st64_b32 v[16:17], v13 offset0:208 offset1:240
	v_lshl_add_u32 v13, v14, 2, v175
	v_not_b32_e32 v25, v24
	v_not_b32_e32 v31, v30
	v_max3_f32 v4, v4, v0, v2
	s_waitcnt lgkmcnt(1)
	v_add_f32_e32 v10, v28, v118
	v_add_u32_e32 v13, 64, v13
	v_max3_f32 v12, v4, v6, v10
	v_lshrrev_b32_e32 v4, 4, v25
	v_bitop3_b32 v8, v24, 15, v24 bitop3:0xc
	ds_read2st64_b32 v[22:23], v13 offset0:208 offset1:240
	v_lshrrev_b32_e32 v13, 4, v31
	v_and_or_b32 v4, v4, 15, v174
	v_lshl_add_u32 v8, v8, 2, v184
	v_and_or_b32 v13, v13, 15, v174
	v_lshl_add_u32 v4, v4, 2, s19
	v_add_u32_e32 v8, 64, v8
	v_bitop3_b32 v14, v30, 15, v30 bitop3:0xc
	v_lshl_add_u32 v13, v13, 2, s19
	ds_read2st64_b32 v[4:5], v4 offset0:208 offset1:240
	ds_read2st64_b32 v[8:9], v8 offset0:208 offset1:240
	ds_read2st64_b32 v[24:25], v13 offset0:208 offset1:240
	v_lshl_add_u32 v13, v14, 2, v184
	v_not_b32_e32 v117, v116
	v_add_u32_e32 v13, 64, v13
	ds_read2st64_b32 v[30:31], v13 offset0:208 offset1:240
	v_lshrrev_b32_e32 v13, 4, v117
	v_and_or_b32 v13, v13, 15, v174
	v_not_b32_e32 v125, v124
	v_bitop3_b32 v14, v116, 15, v116 bitop3:0xc
	v_lshl_add_u32 v13, v13, 2, s19
	ds_read2st64_b32 v[122:123], v13 offset0:208 offset1:240
	v_lshl_add_u32 v13, v14, 2, v175
	s_waitcnt lgkmcnt(3)
	v_add_f32_e32 v4, v4, v8
	v_add_f32_e32 v8, v16, v22
	v_lshrrev_b32_e32 v22, 4, v125
	v_add_u32_e32 v13, 64, v13
	v_and_or_b32 v22, v22, 15, v174
	ds_read2st64_b32 v[126:127], v13 offset0:208 offset1:240
	s_waitcnt lgkmcnt(2)
	v_add_f32_e32 v14, v24, v30
	v_bitop3_b32 v24, v124, 15, v124 bitop3:0xc
	v_lshl_add_u32 v22, v22, 2, s19
	ds_read2st64_b32 v[26:27], v22 offset0:208 offset1:240
	v_lshl_add_u32 v22, v24, 2, v175
	v_not_b32_e32 v143, v142
	v_add_u32_e32 v22, 64, v22
	ds_read2st64_b32 v[116:117], v22 offset0:208 offset1:240
	v_lshrrev_b32_e32 v22, 4, v143
	v_and_or_b32 v22, v22, 15, v174
	v_not_b32_e32 v121, v120
	v_max3_f32 v12, v12, v4, v8
	s_waitcnt lgkmcnt(2)
	v_add_f32_e32 v16, v122, v126
	v_bitop3_b32 v24, v142, 15, v142 bitop3:0xc
	v_lshl_add_u32 v22, v22, 2, s19
	v_max3_f32 v20, v12, v14, v16
	v_lshrrev_b32_e32 v12, 4, v121
	v_bitop3_b32 v18, v120, 15, v120 bitop3:0xc
	ds_read2st64_b32 v[120:121], v22 offset0:208 offset1:240
	v_lshl_add_u32 v22, v24, 2, v184
	v_not_b32_e32 v145, v144
	v_add_u32_e32 v22, 64, v22
	ds_read2st64_b32 v[124:125], v22 offset0:208 offset1:240
	v_lshrrev_b32_e32 v22, 4, v145
	v_and_or_b32 v22, v22, 15, v174
	v_and_or_b32 v12, v12, 15, v174
	v_lshl_add_u32 v18, v18, 2, v184
	v_bitop3_b32 v24, v144, 15, v144 bitop3:0xc
	v_lshl_add_u32 v22, v22, 2, s19
	v_lshl_add_u32 v12, v12, 2, s19
	v_add_u32_e32 v18, 64, v18
	ds_read2st64_b32 v[142:143], v22 offset0:208 offset1:240
	v_lshl_add_u32 v22, v24, 2, v175
	ds_read2st64_b32 v[12:13], v12 offset0:208 offset1:240
	ds_read2st64_b32 v[18:19], v18 offset0:208 offset1:240
	v_add_u32_e32 v22, 64, v22
	ds_read2st64_b32 v[144:145], v22 offset0:208 offset1:240
	s_waitcnt lgkmcnt(4)
	v_add_f32_e32 v22, v120, v124
	s_waitcnt lgkmcnt(1)
	v_add_f32_e32 v12, v12, v18
	v_add_f32_e32 v18, v26, v116
	v_max3_f32 v20, v20, v12, v18
	s_waitcnt lgkmcnt(0)
	v_add_f32_e32 v24, v142, v144
	v_max3_f32 v20, v20, v22, v24
	v_sub_f32_e32 v26, v146, v20
	v_mul_f32_e32 v26, 0x3fb8aa3b, v26
	v_exp_f32_e32 v160, v26
	v_sub_f32_e32 v26, v147, v20
	v_sub_f32_e32 v0, v0, v20
	v_mul_f32_e32 v26, 0x3fb8aa3b, v26
	v_mul_f32_e32 v0, 0x3fb8aa3b, v0
	v_exp_f32_e32 v161, v26
	v_sub_f32_e32 v26, v148, v20
	v_exp_f32_e32 v154, v0
	v_sub_f32_e32 v0, v2, v20
	v_sub_f32_e32 v2, v4, v20
	v_mul_f32_e32 v26, 0x3fb8aa3b, v26
	v_mul_f32_e32 v2, 0x3fb8aa3b, v2
	v_exp_f32_e32 v162, v26
	v_sub_f32_e32 v26, v149, v20
	v_exp_f32_e32 v150, v2
	v_sub_f32_e32 v2, v8, v20
	v_mul_f32_e32 v26, 0x3fb8aa3b, v26
	v_mul_f32_e32 v0, 0x3fb8aa3b, v0
	v_mul_f32_e32 v2, 0x3fb8aa3b, v2
	v_exp_f32_e32 v163, v26
	v_exp_f32_e32 v155, v0
	v_sub_f32_e32 v0, v6, v20
	v_exp_f32_e32 v151, v2
	v_sub_f32_e32 v2, v14, v20
	v_add_f32_e32 v26, 0, v160
	v_mul_f32_e32 v0, 0x3fb8aa3b, v0
	v_mul_f32_e32 v2, 0x3fb8aa3b, v2
	v_add_f32_e32 v26, v161, v26
	v_exp_f32_e32 v156, v0
	v_sub_f32_e32 v0, v10, v20
	v_exp_f32_e32 v152, v2
	v_sub_f32_e32 v2, v16, v20
	v_add_f32_e32 v26, v162, v26
	v_mul_f32_e32 v0, 0x3fb8aa3b, v0
	v_mul_f32_e32 v2, 0x3fb8aa3b, v2
	v_add_f32_e32 v26, v163, v26
	v_exp_f32_e32 v157, v0
	v_exp_f32_e32 v153, v2
	v_sub_f32_e32 v2, v12, v20
	v_add_f32_e32 v0, v154, v26
	v_mul_f32_e32 v2, 0x3fb8aa3b, v2
	v_add_f32_e32 v0, v155, v0
	v_exp_f32_e32 v146, v2
	v_sub_f32_e32 v2, v18, v20
	v_add_f32_e32 v0, v156, v0
	v_mul_f32_e32 v2, 0x3fb8aa3b, v2
	v_add_f32_e32 v0, v157, v0
	v_exp_f32_e32 v147, v2
	v_sub_f32_e32 v2, v22, v20
	v_add_f32_e32 v0, v150, v0
	v_mul_f32_e32 v2, 0x3fb8aa3b, v2
	v_add_f32_e32 v0, v151, v0
	v_exp_f32_e32 v148, v2
	v_sub_f32_e32 v2, v24, v20
	v_add_f32_e32 v0, v152, v0
	v_mul_f32_e32 v2, 0x3fb8aa3b, v2
	v_add_f32_e32 v0, v153, v0
	v_exp_f32_e32 v149, v2
	v_add_f32_e32 v0, v146, v0
	v_add_f32_e32 v0, v147, v0
	v_add_f32_e32 v0, v148, v0
	v_add_f32_e32 v0, v149, v0
	v_div_scale_f32 v2, s[16:17], v0, v0, 1.0
	v_rcp_f32_e32 v4, v2
	s_nop 0
	v_fma_f32 v6, -v2, v4, 1.0
	v_fmac_f32_e32 v4, v6, v4
	v_div_scale_f32 v6, vcc, 1.0, v0, 1.0
	v_mul_f32_e32 v8, v6, v4
	v_fma_f32 v10, -v2, v8, v6
	v_fmac_f32_e32 v8, v10, v4
	v_fma_f32 v2, -v2, v8, v6
	v_div_fmas_f32 v2, v2, v4, v8
	v_div_fixup_f32 v0, v2, v0, 1.0
	s_and_saveexec_b64 s[16:17], s[4:5]
	s_cbranch_execnz .LBB0_79
; DI void topk_phase(unsigned char* smem_, const bf16_t* __restrict__ qp, const bf16_t* __restrict__ keys, int* __restrict__ eidx, float* __restrict__ gate) {
;     ...
; #pragma unroll
;     for (int i = 0; i < 16; ++i) if ((i >> 2) == q) { eidx[ob + i] = be[i]; gate[ob + i] = ex[i] * inv; }
	s_or_b64 exec, exec, s[16:17]
	s_and_saveexec_b64 s[16:17], s[6:7]
	s_cbranch_execnz .LBB0_80
